# GEMM: accumulator zeroing removed via peeled first K-iteration with C=0; in-loop LDS-DMA loads use SGPR-base addressing; NA bias reads unconditional; GQA loop rewrite
# speedup vs baseline: 1.0116x; 1.0055x over previous
.LBB0_212:
	s_ashr_i32 s11, s10, 31
	s_lshl_b64 s[12:13], s[10:11], 19
	v_readlane_b32 s14, v252, 27
	v_readlane_b32 s15, v252, 28
	s_add_u32 s28, s14, s12
	s_addc_u32 s29, s15, s13
	s_and_b64 s[12:13], s[42:43], exec
	s_cselect_b32 s3, s29, s17
	s_cselect_b32 s11, s28, s16
	s_ashr_i32 s9, s8, 31
	s_lshl_b64 s[12:13], s[8:9], 19
	s_add_u32 s36, s20, s12
	s_addc_u32 s37, s22, s13
	s_and_b64 s[12:13], s[42:43], exec
	s_cselect_b32 s9, s37, s41
	s_cselect_b32 s12, s36, s40
	s_add_u32 s16, s16, 0x40080
	s_addc_u32 s17, s17, 0
	s_add_u32 s13, s40, 0x100
	s_addc_u32 s14, s41, 0
	s_mov_b32 s15, -2
	s_add_u32 s18, s16, 0xfffc0080
	s_addc_u32 s19, s17, -1
	s_add_i32 s21, 0, 0x10000
	s_cmp_eq_u32 s15, 12
	s_cselect_b32 s45, s3, s19
	s_cselect_b32 s44, s11, s18
	v_add_u32_e32 v152, s21, v155
	s_cselect_b32 s41, s9, s14
	s_cselect_b32 s40, s12, s13
	s_add_i32 s24, 0, 0x14000
	ds_read_b128 v[182:185], v152
	ds_read_b128 v[186:189], v152 offset:1024
	ds_read_b128 v[190:193], v152 offset:2048
	ds_read_b128 v[194:197], v152 offset:3072
	v_add_u32_e32 v152, s24, v155
	ds_read_b128 v[198:201], v152
	ds_read_b128 v[202:205], v152 offset:1024
	ds_read_b128 v[206:209], v152 offset:2048
	ds_read_b128 v[210:213], v152 offset:3072
	s_add_i32 m0, s26, 0xc000
	ds_read_b128 v[214:217], v157
	ds_read_b128 v[218:221], v157 offset:1024
	ds_read_b128 v[222:225], v157 offset:2048
	ds_read_b128 v[226:229], v157 offset:3072
	ds_read_b128 v[230:233], v157 offset:4096
	ds_read_b128 v[234:237], v157 offset:5120
	ds_read_b128 v[238:241], v157 offset:6144
	ds_read_b128 v[242:245], v157 offset:7168
	global_load_lds_dwordx4 v148, s[16:17]
	s_add_i32 m0, s26, 0xe000
	s_nop 0
	global_load_lds_dwordx4 v150, s[16:17]
	s_waitcnt vmcnt(8)
	s_waitcnt lgkmcnt(0)
	s_barrier
	s_setprio 1
	s_waitcnt lgkmcnt(0)
	v_mfma_f32_16x16x32_bf16 v[124:127], v[182:185], v[214:217], 0
	v_mfma_f32_16x16x32_bf16 v[120:123], v[190:193], v[214:217], 0
	v_mfma_f32_16x16x32_bf16 v[108:111], v[182:185], v[222:225], 0
	v_mfma_f32_16x16x32_bf16 v[104:107], v[190:193], v[222:225], 0
	v_mfma_f32_16x16x32_bf16 v[92:95], v[182:185], v[230:233], 0
	v_mfma_f32_16x16x32_bf16 v[88:91], v[190:193], v[230:233], 0
	v_mfma_f32_16x16x32_bf16 v[76:79], v[182:185], v[238:241], 0
	v_mfma_f32_16x16x32_bf16 v[72:75], v[190:193], v[238:241], 0
	v_mfma_f32_16x16x32_bf16 v[124:127], v[186:189], v[218:221], v[124:127]
	v_mfma_f32_16x16x32_bf16 v[120:123], v[194:197], v[218:221], v[120:123]
	v_mfma_f32_16x16x32_bf16 v[108:111], v[186:189], v[226:229], v[108:111]
	v_mfma_f32_16x16x32_bf16 v[104:107], v[194:197], v[226:229], v[104:107]
	v_mfma_f32_16x16x32_bf16 v[92:95], v[186:189], v[234:237], v[92:95]
	v_mfma_f32_16x16x32_bf16 v[88:91], v[194:197], v[234:237], v[88:91]
	v_mfma_f32_16x16x32_bf16 v[76:79], v[186:189], v[242:245], v[76:79]
	v_mfma_f32_16x16x32_bf16 v[72:75], v[194:197], v[242:245], v[72:75]
	s_setprio 0
	s_setprio 1
	v_mfma_f32_16x16x32_bf16 v[116:119], v[198:201], v[214:217], 0
	v_mfma_f32_16x16x32_bf16 v[112:115], v[206:209], v[214:217], 0
	v_mfma_f32_16x16x32_bf16 v[100:103], v[198:201], v[222:225], 0
	v_mfma_f32_16x16x32_bf16 v[96:99], v[206:209], v[222:225], 0
	v_mfma_f32_16x16x32_bf16 v[84:87], v[198:201], v[230:233], 0
	v_mfma_f32_16x16x32_bf16 v[80:83], v[206:209], v[230:233], 0
	v_mfma_f32_16x16x32_bf16 v[68:71], v[198:201], v[238:241], 0
	v_mfma_f32_16x16x32_bf16 v[64:67], v[206:209], v[238:241], 0
	v_mfma_f32_16x16x32_bf16 v[116:119], v[202:205], v[218:221], v[116:119]
	v_mfma_f32_16x16x32_bf16 v[112:115], v[210:213], v[218:221], v[112:115]
	v_mfma_f32_16x16x32_bf16 v[100:103], v[202:205], v[226:229], v[100:103]
	v_mfma_f32_16x16x32_bf16 v[96:99], v[210:213], v[226:229], v[96:99]
	v_mfma_f32_16x16x32_bf16 v[84:87], v[202:205], v[234:237], v[84:87]
	v_mfma_f32_16x16x32_bf16 v[80:83], v[210:213], v[234:237], v[80:83]
	v_mfma_f32_16x16x32_bf16 v[68:71], v[202:205], v[242:245], v[68:71]
	v_mfma_f32_16x16x32_bf16 v[64:67], v[210:213], v[242:245], v[64:67]
	s_setprio 0
	s_barrier
	s_add_u32 s60, s40, 0x80
	s_addc_u32 s61, s41, 0
	s_add_u32 s62, s44, 0x80
	s_addc_u32 s63, s45, 0
	s_add_i32 s18, s21, s23
	s_mov_b32 m0, s18
	ds_read_b128 v[214:217], v157 offset:16384
	ds_read_b128 v[218:221], v157 offset:17408
	ds_read_b128 v[222:225], v157 offset:18432
	ds_read_b128 v[226:229], v157 offset:19456
	ds_read_b128 v[230:233], v157 offset:20480
	ds_read_b128 v[234:237], v157 offset:21504
	ds_read_b128 v[238:241], v157 offset:22528
	ds_read_b128 v[242:245], v157 offset:23552
	global_load_lds_dwordx4 v130, s[40:41]
	s_add_i32 m0, s18, 0x2000
	s_add_u32 s18, s40, 0x40000
	s_addc_u32 s19, s41, 0
	s_add_i32 s21, s24, s23
	global_load_lds_dwordx4 v142, s[40:41]
	s_mov_b32 m0, s21
	s_nop 0
	global_load_lds_dwordx4 v130, s[18:19]
	s_add_i32 m0, s21, 0x2000
	s_nop 0
	global_load_lds_dwordx4 v142, s[18:19]
	s_mov_b32 m0, s26
	s_nop 0
	global_load_lds_dwordx4 v146, s[44:45]
	s_mov_b32 m0, s34
	s_nop 0
	global_load_lds_dwordx4 v144, s[44:45]
	s_waitcnt vmcnt(8)
	s_waitcnt lgkmcnt(0)
	s_barrier
	s_setprio 1
	s_waitcnt lgkmcnt(0)
	v_mfma_f32_16x16x32_bf16 v[60:63], v[182:185], v[214:217], 0
	v_mfma_f32_16x16x32_bf16 v[56:59], v[190:193], v[214:217], 0
	v_mfma_f32_16x16x32_bf16 v[44:47], v[182:185], v[222:225], 0
	v_mfma_f32_16x16x32_bf16 v[40:43], v[190:193], v[222:225], 0
	v_mfma_f32_16x16x32_bf16 v[28:31], v[182:185], v[230:233], 0
	v_mfma_f32_16x16x32_bf16 v[24:27], v[190:193], v[230:233], 0
	v_mfma_f32_16x16x32_bf16 v[12:15], v[182:185], v[238:241], 0
	v_mfma_f32_16x16x32_bf16 v[8:11], v[190:193], v[238:241], 0
	v_mfma_f32_16x16x32_bf16 v[60:63], v[186:189], v[218:221], v[60:63]
	v_mfma_f32_16x16x32_bf16 v[56:59], v[194:197], v[218:221], v[56:59]
	v_mfma_f32_16x16x32_bf16 v[44:47], v[186:189], v[226:229], v[44:47]
	v_mfma_f32_16x16x32_bf16 v[40:43], v[194:197], v[226:229], v[40:43]
	v_mfma_f32_16x16x32_bf16 v[28:31], v[186:189], v[234:237], v[28:31]
	v_mfma_f32_16x16x32_bf16 v[24:27], v[194:197], v[234:237], v[24:27]
	v_mfma_f32_16x16x32_bf16 v[12:15], v[186:189], v[242:245], v[12:15]
	v_mfma_f32_16x16x32_bf16 v[8:11], v[194:197], v[242:245], v[8:11]
	s_setprio 0
	s_setprio 1
	v_mfma_f32_16x16x32_bf16 v[52:55], v[198:201], v[214:217], 0
	v_mfma_f32_16x16x32_bf16 v[48:51], v[206:209], v[214:217], 0
	v_mfma_f32_16x16x32_bf16 v[36:39], v[198:201], v[222:225], 0
	v_mfma_f32_16x16x32_bf16 v[32:35], v[206:209], v[222:225], 0
	v_mfma_f32_16x16x32_bf16 v[20:23], v[198:201], v[230:233], 0
	v_mfma_f32_16x16x32_bf16 v[16:19], v[206:209], v[230:233], 0
	v_mfma_f32_16x16x32_bf16 v[4:7], v[198:201], v[238:241], 0
	v_mfma_f32_16x16x32_bf16 v[0:3], v[206:209], v[238:241], 0
	v_mfma_f32_16x16x32_bf16 v[52:55], v[202:205], v[218:221], v[52:55]
	v_mfma_f32_16x16x32_bf16 v[48:51], v[210:213], v[218:221], v[48:51]
	v_mfma_f32_16x16x32_bf16 v[36:39], v[202:205], v[226:229], v[36:39]
	v_mfma_f32_16x16x32_bf16 v[32:35], v[210:213], v[226:229], v[32:35]
	v_mfma_f32_16x16x32_bf16 v[20:23], v[202:205], v[234:237], v[20:23]
	v_mfma_f32_16x16x32_bf16 v[16:19], v[210:213], v[234:237], v[16:19]
	v_mfma_f32_16x16x32_bf16 v[4:7], v[202:205], v[242:245], v[4:7]
	v_mfma_f32_16x16x32_bf16 v[0:3], v[210:213], v[242:245], v[0:3]
	s_setprio 0
	s_barrier
	s_add_i32 s21, 0, 0x18000
	v_add_u32_e32 v178, s21, v155
	s_add_i32 s24, 0, 0x1c000
	ds_read_b128 v[182:185], v178
	ds_read_b128 v[186:189], v178 offset:1024
	ds_read_b128 v[190:193], v178 offset:2048
	ds_read_b128 v[194:197], v178 offset:3072
	v_add_u32_e32 v178, s24, v155
	ds_read_b128 v[198:201], v178
	ds_read_b128 v[202:205], v178 offset:1024
	ds_read_b128 v[206:209], v178 offset:2048
	ds_read_b128 v[210:213], v178 offset:3072
	s_add_u32 s18, s44, 0x40000
	s_addc_u32 s19, s45, 0
	s_mov_b32 m0, s35
	ds_read_b128 v[214:217], v157 offset:32768
	ds_read_b128 v[218:221], v157 offset:33792
	ds_read_b128 v[222:225], v157 offset:34816
	ds_read_b128 v[226:229], v157 offset:35840
	ds_read_b128 v[230:233], v157 offset:36864
	ds_read_b128 v[234:237], v157 offset:37888
	ds_read_b128 v[238:241], v157 offset:38912
	ds_read_b128 v[242:245], v157 offset:39936
	global_load_lds_dwordx4 v146, s[18:19]
	s_mov_b32 m0, s46
	s_nop 0
	global_load_lds_dwordx4 v144, s[18:19]
	s_waitcnt vmcnt(8)
	s_waitcnt lgkmcnt(0)
	s_barrier
	s_setprio 1
	s_waitcnt lgkmcnt(0)
	v_mfma_f32_16x16x32_bf16 v[124:127], v[182:185], v[214:217], v[124:127]
	v_mfma_f32_16x16x32_bf16 v[120:123], v[190:193], v[214:217], v[120:123]
	v_mfma_f32_16x16x32_bf16 v[108:111], v[182:185], v[222:225], v[108:111]
	v_mfma_f32_16x16x32_bf16 v[104:107], v[190:193], v[222:225], v[104:107]
	v_mfma_f32_16x16x32_bf16 v[92:95], v[182:185], v[230:233], v[92:95]
	v_mfma_f32_16x16x32_bf16 v[88:91], v[190:193], v[230:233], v[88:91]
	v_mfma_f32_16x16x32_bf16 v[76:79], v[182:185], v[238:241], v[76:79]
	v_mfma_f32_16x16x32_bf16 v[72:75], v[190:193], v[238:241], v[72:75]
	v_mfma_f32_16x16x32_bf16 v[124:127], v[186:189], v[218:221], v[124:127]
	v_mfma_f32_16x16x32_bf16 v[120:123], v[194:197], v[218:221], v[120:123]
	v_mfma_f32_16x16x32_bf16 v[108:111], v[186:189], v[226:229], v[108:111]
	v_mfma_f32_16x16x32_bf16 v[104:107], v[194:197], v[226:229], v[104:107]
	v_mfma_f32_16x16x32_bf16 v[92:95], v[186:189], v[234:237], v[92:95]
	v_mfma_f32_16x16x32_bf16 v[88:91], v[194:197], v[234:237], v[88:91]
	v_mfma_f32_16x16x32_bf16 v[76:79], v[186:189], v[242:245], v[76:79]
	v_mfma_f32_16x16x32_bf16 v[72:75], v[194:197], v[242:245], v[72:75]
	s_setprio 0
	s_setprio 1
	v_mfma_f32_16x16x32_bf16 v[116:119], v[198:201], v[214:217], v[116:119]
	v_mfma_f32_16x16x32_bf16 v[112:115], v[206:209], v[214:217], v[112:115]
	v_mfma_f32_16x16x32_bf16 v[100:103], v[198:201], v[222:225], v[100:103]
	v_mfma_f32_16x16x32_bf16 v[96:99], v[206:209], v[222:225], v[96:99]
	v_mfma_f32_16x16x32_bf16 v[84:87], v[198:201], v[230:233], v[84:87]
	v_mfma_f32_16x16x32_bf16 v[80:83], v[206:209], v[230:233], v[80:83]
	v_mfma_f32_16x16x32_bf16 v[68:71], v[198:201], v[238:241], v[68:71]
	v_mfma_f32_16x16x32_bf16 v[64:67], v[206:209], v[238:241], v[64:67]
	v_mfma_f32_16x16x32_bf16 v[116:119], v[202:205], v[218:221], v[116:119]
	v_mfma_f32_16x16x32_bf16 v[112:115], v[210:213], v[218:221], v[112:115]
	v_mfma_f32_16x16x32_bf16 v[100:103], v[202:205], v[226:229], v[100:103]
	v_mfma_f32_16x16x32_bf16 v[96:99], v[210:213], v[226:229], v[96:99]
	v_mfma_f32_16x16x32_bf16 v[84:87], v[202:205], v[234:237], v[84:87]
	v_mfma_f32_16x16x32_bf16 v[80:83], v[210:213], v[234:237], v[80:83]
	v_mfma_f32_16x16x32_bf16 v[68:71], v[202:205], v[242:245], v[68:71]
	v_mfma_f32_16x16x32_bf16 v[64:67], v[210:213], v[242:245], v[64:67]
	s_setprio 0
	s_barrier
	s_add_i32 s18, s21, s23
	s_mov_b32 m0, s18
	ds_read_b128 v[214:217], v157 offset:49152
	ds_read_b128 v[218:221], v157 offset:50176
	ds_read_b128 v[222:225], v157 offset:51200
	ds_read_b128 v[226:229], v157 offset:52224
	ds_read_b128 v[230:233], v157 offset:53248
	ds_read_b128 v[234:237], v157 offset:54272
	ds_read_b128 v[238:241], v157 offset:55296
	ds_read_b128 v[242:245], v157 offset:56320
	global_load_lds_dwordx4 v130, s[60:61]
	s_add_i32 m0, s18, 0x2000
	s_add_u32 s18, s40, 0x40080
	s_addc_u32 s19, s41, 0
	s_add_i32 s21, s24, s23
	global_load_lds_dwordx4 v142, s[60:61]
	s_mov_b32 m0, s21
	s_nop 0
	global_load_lds_dwordx4 v130, s[18:19]
	s_add_i32 m0, s21, 0x2000
	s_nop 0
	global_load_lds_dwordx4 v142, s[18:19]
	s_mov_b32 m0, s47
	s_nop 0
	global_load_lds_dwordx4 v146, s[62:63]
	s_mov_b32 m0, s48
	s_nop 0
	global_load_lds_dwordx4 v144, s[62:63]
	s_waitcnt vmcnt(8)
	s_waitcnt lgkmcnt(0)
	s_barrier
	s_setprio 1
	s_waitcnt lgkmcnt(0)
	v_mfma_f32_16x16x32_bf16 v[60:63], v[182:185], v[214:217], v[60:63]
	v_mfma_f32_16x16x32_bf16 v[56:59], v[190:193], v[214:217], v[56:59]
	v_mfma_f32_16x16x32_bf16 v[44:47], v[182:185], v[222:225], v[44:47]
	v_mfma_f32_16x16x32_bf16 v[40:43], v[190:193], v[222:225], v[40:43]
	v_mfma_f32_16x16x32_bf16 v[28:31], v[182:185], v[230:233], v[28:31]
	v_mfma_f32_16x16x32_bf16 v[24:27], v[190:193], v[230:233], v[24:27]
	v_mfma_f32_16x16x32_bf16 v[12:15], v[182:185], v[238:241], v[12:15]
	v_mfma_f32_16x16x32_bf16 v[8:11], v[190:193], v[238:241], v[8:11]
	v_mfma_f32_16x16x32_bf16 v[60:63], v[186:189], v[218:221], v[60:63]
	v_mfma_f32_16x16x32_bf16 v[56:59], v[194:197], v[218:221], v[56:59]
	v_mfma_f32_16x16x32_bf16 v[44:47], v[186:189], v[226:229], v[44:47]
	v_mfma_f32_16x16x32_bf16 v[40:43], v[194:197], v[226:229], v[40:43]
	v_mfma_f32_16x16x32_bf16 v[28:31], v[186:189], v[234:237], v[28:31]
	v_mfma_f32_16x16x32_bf16 v[24:27], v[194:197], v[234:237], v[24:27]
	v_mfma_f32_16x16x32_bf16 v[12:15], v[186:189], v[242:245], v[12:15]
	v_mfma_f32_16x16x32_bf16 v[8:11], v[194:197], v[242:245], v[8:11]
	s_setprio 0
	s_setprio 1
	v_mfma_f32_16x16x32_bf16 v[52:55], v[198:201], v[214:217], v[52:55]
	v_mfma_f32_16x16x32_bf16 v[48:51], v[206:209], v[214:217], v[48:51]
	v_mfma_f32_16x16x32_bf16 v[36:39], v[198:201], v[222:225], v[36:39]
	v_mfma_f32_16x16x32_bf16 v[32:35], v[206:209], v[222:225], v[32:35]
	v_mfma_f32_16x16x32_bf16 v[20:23], v[198:201], v[230:233], v[20:23]
	v_mfma_f32_16x16x32_bf16 v[16:19], v[206:209], v[230:233], v[16:19]
	v_mfma_f32_16x16x32_bf16 v[4:7], v[198:201], v[238:241], v[4:7]
	v_mfma_f32_16x16x32_bf16 v[0:3], v[206:209], v[238:241], v[0:3]
	v_mfma_f32_16x16x32_bf16 v[52:55], v[202:205], v[218:221], v[52:55]
	v_mfma_f32_16x16x32_bf16 v[48:51], v[210:213], v[218:221], v[48:51]
	v_mfma_f32_16x16x32_bf16 v[36:39], v[202:205], v[226:229], v[36:39]
	v_mfma_f32_16x16x32_bf16 v[32:35], v[210:213], v[226:229], v[32:35]
	v_mfma_f32_16x16x32_bf16 v[20:23], v[202:205], v[234:237], v[20:23]
	v_mfma_f32_16x16x32_bf16 v[16:19], v[210:213], v[234:237], v[16:19]
	v_mfma_f32_16x16x32_bf16 v[4:7], v[202:205], v[242:245], v[4:7]
	v_mfma_f32_16x16x32_bf16 v[0:3], v[210:213], v[242:245], v[0:3]
	s_setprio 0
	s_barrier
	s_add_i32 s15, s15, 2
	s_add_u32 s16, s16, 0x100
	s_addc_u32 s17, s17, 0
	s_add_u32 s13, s13, 0x100
	s_addc_u32 s14, s14, 0
	s_cmp_gt_u32 s15, 13
	s_cbranch_scc1 .Lpeel_done_213
.LBB0_213:
	s_add_u32 s18, s16, 0xfffc0080
	s_addc_u32 s19, s17, -1
	s_add_i32 s21, 0, 0x10000
	s_cmp_eq_u32 s15, 12
	s_cselect_b32 s45, s3, s19
	s_cselect_b32 s44, s11, s18
	v_add_u32_e32 v152, s21, v155
	s_cselect_b32 s41, s9, s14
	s_cselect_b32 s40, s12, s13
	s_add_i32 s24, 0, 0x14000
	ds_read_b128 v[182:185], v152
	ds_read_b128 v[186:189], v152 offset:1024
	ds_read_b128 v[190:193], v152 offset:2048
	ds_read_b128 v[194:197], v152 offset:3072
	v_add_u32_e32 v152, s24, v155
	ds_read_b128 v[198:201], v152
	ds_read_b128 v[202:205], v152 offset:1024
	ds_read_b128 v[206:209], v152 offset:2048
	ds_read_b128 v[210:213], v152 offset:3072
	s_add_i32 m0, s26, 0xc000
	ds_read_b128 v[214:217], v157
	ds_read_b128 v[218:221], v157 offset:1024
	ds_read_b128 v[222:225], v157 offset:2048
	ds_read_b128 v[226:229], v157 offset:3072
	ds_read_b128 v[230:233], v157 offset:4096
	ds_read_b128 v[234:237], v157 offset:5120
	ds_read_b128 v[238:241], v157 offset:6144
	ds_read_b128 v[242:245], v157 offset:7168
	global_load_lds_dwordx4 v148, s[16:17]
	s_add_i32 m0, s26, 0xe000
	s_nop 0
	global_load_lds_dwordx4 v150, s[16:17]
	s_waitcnt vmcnt(8)
	s_waitcnt lgkmcnt(0)
	s_barrier
	s_setprio 1
	s_waitcnt lgkmcnt(0)
	v_mfma_f32_16x16x32_bf16 v[124:127], v[182:185], v[214:217], v[124:127]
	v_mfma_f32_16x16x32_bf16 v[120:123], v[190:193], v[214:217], v[120:123]
	v_mfma_f32_16x16x32_bf16 v[108:111], v[182:185], v[222:225], v[108:111]
	v_mfma_f32_16x16x32_bf16 v[104:107], v[190:193], v[222:225], v[104:107]
	v_mfma_f32_16x16x32_bf16 v[92:95], v[182:185], v[230:233], v[92:95]
	v_mfma_f32_16x16x32_bf16 v[88:91], v[190:193], v[230:233], v[88:91]
	v_mfma_f32_16x16x32_bf16 v[76:79], v[182:185], v[238:241], v[76:79]
	v_mfma_f32_16x16x32_bf16 v[72:75], v[190:193], v[238:241], v[72:75]
	v_mfma_f32_16x16x32_bf16 v[124:127], v[186:189], v[218:221], v[124:127]
	v_mfma_f32_16x16x32_bf16 v[120:123], v[194:197], v[218:221], v[120:123]
	v_mfma_f32_16x16x32_bf16 v[108:111], v[186:189], v[226:229], v[108:111]
	v_mfma_f32_16x16x32_bf16 v[104:107], v[194:197], v[226:229], v[104:107]
	v_mfma_f32_16x16x32_bf16 v[92:95], v[186:189], v[234:237], v[92:95]
	v_mfma_f32_16x16x32_bf16 v[88:91], v[194:197], v[234:237], v[88:91]
	v_mfma_f32_16x16x32_bf16 v[76:79], v[186:189], v[242:245], v[76:79]
	v_mfma_f32_16x16x32_bf16 v[72:75], v[194:197], v[242:245], v[72:75]
	s_setprio 0
	s_setprio 1
	v_mfma_f32_16x16x32_bf16 v[116:119], v[198:201], v[214:217], v[116:119]
	v_mfma_f32_16x16x32_bf16 v[112:115], v[206:209], v[214:217], v[112:115]
	v_mfma_f32_16x16x32_bf16 v[100:103], v[198:201], v[222:225], v[100:103]
	v_mfma_f32_16x16x32_bf16 v[96:99], v[206:209], v[222:225], v[96:99]
	v_mfma_f32_16x16x32_bf16 v[84:87], v[198:201], v[230:233], v[84:87]
	v_mfma_f32_16x16x32_bf16 v[80:83], v[206:209], v[230:233], v[80:83]
	v_mfma_f32_16x16x32_bf16 v[68:71], v[198:201], v[238:241], v[68:71]
	v_mfma_f32_16x16x32_bf16 v[64:67], v[206:209], v[238:241], v[64:67]
	v_mfma_f32_16x16x32_bf16 v[116:119], v[202:205], v[218:221], v[116:119]
	v_mfma_f32_16x16x32_bf16 v[112:115], v[210:213], v[218:221], v[112:115]
	v_mfma_f32_16x16x32_bf16 v[100:103], v[202:205], v[226:229], v[100:103]
	v_mfma_f32_16x16x32_bf16 v[96:99], v[210:213], v[226:229], v[96:99]
	v_mfma_f32_16x16x32_bf16 v[84:87], v[202:205], v[234:237], v[84:87]
	v_mfma_f32_16x16x32_bf16 v[80:83], v[210:213], v[234:237], v[80:83]
	v_mfma_f32_16x16x32_bf16 v[68:71], v[202:205], v[242:245], v[68:71]
	v_mfma_f32_16x16x32_bf16 v[64:67], v[210:213], v[242:245], v[64:67]
	s_setprio 0
	s_barrier
	s_add_u32 s60, s40, 0x80
	s_addc_u32 s61, s41, 0
	s_add_u32 s62, s44, 0x80
	s_addc_u32 s63, s45, 0
	s_add_i32 s18, s21, s23
	s_mov_b32 m0, s18
	ds_read_b128 v[214:217], v157 offset:16384
	ds_read_b128 v[218:221], v157 offset:17408
	ds_read_b128 v[222:225], v157 offset:18432
	ds_read_b128 v[226:229], v157 offset:19456
	ds_read_b128 v[230:233], v157 offset:20480
	ds_read_b128 v[234:237], v157 offset:21504
	ds_read_b128 v[238:241], v157 offset:22528
	ds_read_b128 v[242:245], v157 offset:23552
	global_load_lds_dwordx4 v130, s[40:41]
	s_add_i32 m0, s18, 0x2000
	s_add_u32 s18, s40, 0x40000
	s_addc_u32 s19, s41, 0
	s_add_i32 s21, s24, s23
	global_load_lds_dwordx4 v142, s[40:41]
	s_mov_b32 m0, s21
	s_nop 0
	global_load_lds_dwordx4 v130, s[18:19]
	s_add_i32 m0, s21, 0x2000
	s_nop 0
	global_load_lds_dwordx4 v142, s[18:19]
	s_mov_b32 m0, s26
	s_nop 0
	global_load_lds_dwordx4 v146, s[44:45]
	s_mov_b32 m0, s34
	s_nop 0
	global_load_lds_dwordx4 v144, s[44:45]
	s_waitcnt vmcnt(8)
	s_waitcnt lgkmcnt(0)
	s_barrier
	s_setprio 1
	s_waitcnt lgkmcnt(0)
	v_mfma_f32_16x16x32_bf16 v[60:63], v[182:185], v[214:217], v[60:63]
	v_mfma_f32_16x16x32_bf16 v[56:59], v[190:193], v[214:217], v[56:59]
	v_mfma_f32_16x16x32_bf16 v[44:47], v[182:185], v[222:225], v[44:47]
	v_mfma_f32_16x16x32_bf16 v[40:43], v[190:193], v[222:225], v[40:43]
	v_mfma_f32_16x16x32_bf16 v[28:31], v[182:185], v[230:233], v[28:31]
	v_mfma_f32_16x16x32_bf16 v[24:27], v[190:193], v[230:233], v[24:27]
	v_mfma_f32_16x16x32_bf16 v[12:15], v[182:185], v[238:241], v[12:15]
	v_mfma_f32_16x16x32_bf16 v[8:11], v[190:193], v[238:241], v[8:11]
	v_mfma_f32_16x16x32_bf16 v[60:63], v[186:189], v[218:221], v[60:63]
	v_mfma_f32_16x16x32_bf16 v[56:59], v[194:197], v[218:221], v[56:59]
	v_mfma_f32_16x16x32_bf16 v[44:47], v[186:189], v[226:229], v[44:47]
	v_mfma_f32_16x16x32_bf16 v[40:43], v[194:197], v[226:229], v[40:43]
	v_mfma_f32_16x16x32_bf16 v[28:31], v[186:189], v[234:237], v[28:31]
	v_mfma_f32_16x16x32_bf16 v[24:27], v[194:197], v[234:237], v[24:27]
	v_mfma_f32_16x16x32_bf16 v[12:15], v[186:189], v[242:245], v[12:15]
	v_mfma_f32_16x16x32_bf16 v[8:11], v[194:197], v[242:245], v[8:11]
	s_setprio 0
	s_setprio 1
	v_mfma_f32_16x16x32_bf16 v[52:55], v[198:201], v[214:217], v[52:55]
	v_mfma_f32_16x16x32_bf16 v[48:51], v[206:209], v[214:217], v[48:51]
	v_mfma_f32_16x16x32_bf16 v[36:39], v[198:201], v[222:225], v[36:39]
	v_mfma_f32_16x16x32_bf16 v[32:35], v[206:209], v[222:225], v[32:35]
	v_mfma_f32_16x16x32_bf16 v[20:23], v[198:201], v[230:233], v[20:23]
	v_mfma_f32_16x16x32_bf16 v[16:19], v[206:209], v[230:233], v[16:19]
	v_mfma_f32_16x16x32_bf16 v[4:7], v[198:201], v[238:241], v[4:7]
	v_mfma_f32_16x16x32_bf16 v[0:3], v[206:209], v[238:241], v[0:3]
	v_mfma_f32_16x16x32_bf16 v[52:55], v[202:205], v[218:221], v[52:55]
	v_mfma_f32_16x16x32_bf16 v[48:51], v[210:213], v[218:221], v[48:51]
	v_mfma_f32_16x16x32_bf16 v[36:39], v[202:205], v[226:229], v[36:39]
	v_mfma_f32_16x16x32_bf16 v[32:35], v[210:213], v[226:229], v[32:35]
	v_mfma_f32_16x16x32_bf16 v[20:23], v[202:205], v[234:237], v[20:23]
	v_mfma_f32_16x16x32_bf16 v[16:19], v[210:213], v[234:237], v[16:19]
	v_mfma_f32_16x16x32_bf16 v[4:7], v[202:205], v[242:245], v[4:7]
	v_mfma_f32_16x16x32_bf16 v[0:3], v[210:213], v[242:245], v[0:3]
	s_setprio 0
	s_barrier
	s_add_i32 s21, 0, 0x18000
	v_add_u32_e32 v178, s21, v155
	s_add_i32 s24, 0, 0x1c000
	ds_read_b128 v[182:185], v178
	ds_read_b128 v[186:189], v178 offset:1024
	ds_read_b128 v[190:193], v178 offset:2048
	ds_read_b128 v[194:197], v178 offset:3072
	v_add_u32_e32 v178, s24, v155
	ds_read_b128 v[198:201], v178
	ds_read_b128 v[202:205], v178 offset:1024
	ds_read_b128 v[206:209], v178 offset:2048
	ds_read_b128 v[210:213], v178 offset:3072
	s_add_u32 s18, s44, 0x40000
	s_addc_u32 s19, s45, 0
	s_mov_b32 m0, s35
	ds_read_b128 v[214:217], v157 offset:32768
	ds_read_b128 v[218:221], v157 offset:33792
	ds_read_b128 v[222:225], v157 offset:34816
	ds_read_b128 v[226:229], v157 offset:35840
	ds_read_b128 v[230:233], v157 offset:36864
	ds_read_b128 v[234:237], v157 offset:37888
	ds_read_b128 v[238:241], v157 offset:38912
	ds_read_b128 v[242:245], v157 offset:39936
	global_load_lds_dwordx4 v146, s[18:19]
	s_mov_b32 m0, s46
	s_nop 0
	global_load_lds_dwordx4 v144, s[18:19]
	s_waitcnt vmcnt(8)
	s_waitcnt lgkmcnt(0)
	s_barrier
	s_setprio 1
	s_waitcnt lgkmcnt(0)
	v_mfma_f32_16x16x32_bf16 v[124:127], v[182:185], v[214:217], v[124:127]
	v_mfma_f32_16x16x32_bf16 v[120:123], v[190:193], v[214:217], v[120:123]
	v_mfma_f32_16x16x32_bf16 v[108:111], v[182:185], v[222:225], v[108:111]
	v_mfma_f32_16x16x32_bf16 v[104:107], v[190:193], v[222:225], v[104:107]
	v_mfma_f32_16x16x32_bf16 v[92:95], v[182:185], v[230:233], v[92:95]
	v_mfma_f32_16x16x32_bf16 v[88:91], v[190:193], v[230:233], v[88:91]
	v_mfma_f32_16x16x32_bf16 v[76:79], v[182:185], v[238:241], v[76:79]
	v_mfma_f32_16x16x32_bf16 v[72:75], v[190:193], v[238:241], v[72:75]
	v_mfma_f32_16x16x32_bf16 v[124:127], v[186:189], v[218:221], v[124:127]
	v_mfma_f32_16x16x32_bf16 v[120:123], v[194:197], v[218:221], v[120:123]
	v_mfma_f32_16x16x32_bf16 v[108:111], v[186:189], v[226:229], v[108:111]
	v_mfma_f32_16x16x32_bf16 v[104:107], v[194:197], v[226:229], v[104:107]
	v_mfma_f32_16x16x32_bf16 v[92:95], v[186:189], v[234:237], v[92:95]
	v_mfma_f32_16x16x32_bf16 v[88:91], v[194:197], v[234:237], v[88:91]
	v_mfma_f32_16x16x32_bf16 v[76:79], v[186:189], v[242:245], v[76:79]
	v_mfma_f32_16x16x32_bf16 v[72:75], v[194:197], v[242:245], v[72:75]
	s_setprio 0
	s_setprio 1
	v_mfma_f32_16x16x32_bf16 v[116:119], v[198:201], v[214:217], v[116:119]
	v_mfma_f32_16x16x32_bf16 v[112:115], v[206:209], v[214:217], v[112:115]
	v_mfma_f32_16x16x32_bf16 v[100:103], v[198:201], v[222:225], v[100:103]
	v_mfma_f32_16x16x32_bf16 v[96:99], v[206:209], v[222:225], v[96:99]
	v_mfma_f32_16x16x32_bf16 v[84:87], v[198:201], v[230:233], v[84:87]
	v_mfma_f32_16x16x32_bf16 v[80:83], v[206:209], v[230:233], v[80:83]
	v_mfma_f32_16x16x32_bf16 v[68:71], v[198:201], v[238:241], v[68:71]
	v_mfma_f32_16x16x32_bf16 v[64:67], v[206:209], v[238:241], v[64:67]
	v_mfma_f32_16x16x32_bf16 v[116:119], v[202:205], v[218:221], v[116:119]
	v_mfma_f32_16x16x32_bf16 v[112:115], v[210:213], v[218:221], v[112:115]
	v_mfma_f32_16x16x32_bf16 v[100:103], v[202:205], v[226:229], v[100:103]
	v_mfma_f32_16x16x32_bf16 v[96:99], v[210:213], v[226:229], v[96:99]
	v_mfma_f32_16x16x32_bf16 v[84:87], v[202:205], v[234:237], v[84:87]
	v_mfma_f32_16x16x32_bf16 v[80:83], v[210:213], v[234:237], v[80:83]
	v_mfma_f32_16x16x32_bf16 v[68:71], v[202:205], v[242:245], v[68:71]
	v_mfma_f32_16x16x32_bf16 v[64:67], v[210:213], v[242:245], v[64:67]
	s_setprio 0
	s_barrier
	s_add_i32 s18, s21, s23
	s_mov_b32 m0, s18
	ds_read_b128 v[214:217], v157 offset:49152
	ds_read_b128 v[218:221], v157 offset:50176
	ds_read_b128 v[222:225], v157 offset:51200
	ds_read_b128 v[226:229], v157 offset:52224
	ds_read_b128 v[230:233], v157 offset:53248
	ds_read_b128 v[234:237], v157 offset:54272
	ds_read_b128 v[238:241], v157 offset:55296
	ds_read_b128 v[242:245], v157 offset:56320
	global_load_lds_dwordx4 v130, s[60:61]
	s_add_i32 m0, s18, 0x2000
	s_add_u32 s18, s40, 0x40080
	s_addc_u32 s19, s41, 0
	s_add_i32 s21, s24, s23
	global_load_lds_dwordx4 v142, s[60:61]
	s_mov_b32 m0, s21
	s_nop 0
	global_load_lds_dwordx4 v130, s[18:19]
	s_add_i32 m0, s21, 0x2000
	s_nop 0
	global_load_lds_dwordx4 v142, s[18:19]
	s_mov_b32 m0, s47
	s_nop 0
	global_load_lds_dwordx4 v146, s[62:63]
	s_mov_b32 m0, s48
	s_nop 0
	global_load_lds_dwordx4 v144, s[62:63]
	s_waitcnt vmcnt(8)
	s_waitcnt lgkmcnt(0)
	s_barrier
	s_setprio 1
	s_waitcnt lgkmcnt(0)
	v_mfma_f32_16x16x32_bf16 v[60:63], v[182:185], v[214:217], v[60:63]
	v_mfma_f32_16x16x32_bf16 v[56:59], v[190:193], v[214:217], v[56:59]
	v_mfma_f32_16x16x32_bf16 v[44:47], v[182:185], v[222:225], v[44:47]
	v_mfma_f32_16x16x32_bf16 v[40:43], v[190:193], v[222:225], v[40:43]
	v_mfma_f32_16x16x32_bf16 v[28:31], v[182:185], v[230:233], v[28:31]
	v_mfma_f32_16x16x32_bf16 v[24:27], v[190:193], v[230:233], v[24:27]
	v_mfma_f32_16x16x32_bf16 v[12:15], v[182:185], v[238:241], v[12:15]
	v_mfma_f32_16x16x32_bf16 v[8:11], v[190:193], v[238:241], v[8:11]
	v_mfma_f32_16x16x32_bf16 v[60:63], v[186:189], v[218:221], v[60:63]
	v_mfma_f32_16x16x32_bf16 v[56:59], v[194:197], v[218:221], v[56:59]
	v_mfma_f32_16x16x32_bf16 v[44:47], v[186:189], v[226:229], v[44:47]
	v_mfma_f32_16x16x32_bf16 v[40:43], v[194:197], v[226:229], v[40:43]
	v_mfma_f32_16x16x32_bf16 v[28:31], v[186:189], v[234:237], v[28:31]
	v_mfma_f32_16x16x32_bf16 v[24:27], v[194:197], v[234:237], v[24:27]
	v_mfma_f32_16x16x32_bf16 v[12:15], v[186:189], v[242:245], v[12:15]
	v_mfma_f32_16x16x32_bf16 v[8:11], v[194:197], v[242:245], v[8:11]
	s_setprio 0
	s_setprio 1
	v_mfma_f32_16x16x32_bf16 v[52:55], v[198:201], v[214:217], v[52:55]
	v_mfma_f32_16x16x32_bf16 v[48:51], v[206:209], v[214:217], v[48:51]
	v_mfma_f32_16x16x32_bf16 v[36:39], v[198:201], v[222:225], v[36:39]
	v_mfma_f32_16x16x32_bf16 v[32:35], v[206:209], v[222:225], v[32:35]
	v_mfma_f32_16x16x32_bf16 v[20:23], v[198:201], v[230:233], v[20:23]
	v_mfma_f32_16x16x32_bf16 v[16:19], v[206:209], v[230:233], v[16:19]
	v_mfma_f32_16x16x32_bf16 v[4:7], v[198:201], v[238:241], v[4:7]
	v_mfma_f32_16x16x32_bf16 v[0:3], v[206:209], v[238:241], v[0:3]
	v_mfma_f32_16x16x32_bf16 v[52:55], v[202:205], v[218:221], v[52:55]
	v_mfma_f32_16x16x32_bf16 v[48:51], v[210:213], v[218:221], v[48:51]
	v_mfma_f32_16x16x32_bf16 v[36:39], v[202:205], v[226:229], v[36:39]
	v_mfma_f32_16x16x32_bf16 v[32:35], v[210:213], v[226:229], v[32:35]
	v_mfma_f32_16x16x32_bf16 v[20:23], v[202:205], v[234:237], v[20:23]
	v_mfma_f32_16x16x32_bf16 v[16:19], v[210:213], v[234:237], v[16:19]
	v_mfma_f32_16x16x32_bf16 v[4:7], v[202:205], v[242:245], v[4:7]
	v_mfma_f32_16x16x32_bf16 v[0:3], v[210:213], v[242:245], v[0:3]
	s_setprio 0
	s_barrier
	s_add_i32 s15, s15, 2
	s_add_u32 s16, s16, 0x100
	s_addc_u32 s17, s17, 0
	s_add_u32 s13, s13, 0x100
	s_addc_u32 s14, s14, 0
	s_cmp_gt_u32 s15, 13
	s_cbranch_scc0 .LBB0_213
.Lpeel_done_213:
	s_and_b64 vcc, exec, s[6:7]
	s_cbranch_vccz .LBB0_216
	s_barrier

.LBB0_285:
	s_add_i32 s11, s49, -2
	s_add_u32 s50, s40, 0x100
	s_addc_u32 s51, s41, 0
	s_mov_b32 s42, 0
	s_add_i32 s52, s42, 2
	s_add_u32 s40, s36, 0x100
	s_addc_u32 s41, s37, 0
	s_add_i32 s22, 0, 0x10000
	s_cmp_eq_u32 s11, s42
	s_cselect_b32 s45, s17, s41
	s_cselect_b32 s44, s16, s40
	v_add_u32_e32 v156, s22, v153
	s_cselect_b32 s43, s29, s51
	s_cselect_b32 s42, s28, s50
	s_add_i32 s23, 0, 0x14000
	ds_read_b128 v[182:185], v156
	ds_read_b128 v[186:189], v156 offset:1024
	ds_read_b128 v[190:193], v156 offset:2048
	ds_read_b128 v[194:197], v156 offset:3072
	v_add_u32_e32 v156, s23, v153
	ds_read_b128 v[198:201], v156
	ds_read_b128 v[202:205], v156 offset:1024
	ds_read_b128 v[206:209], v156 offset:2048
	ds_read_b128 v[210:213], v156 offset:3072
	s_add_i32 m0, s13, 0xc000
	ds_read_b128 v[214:217], v155
	ds_read_b128 v[218:221], v155 offset:1024
	ds_read_b128 v[222:225], v155 offset:2048
	ds_read_b128 v[226:229], v155 offset:3072
	ds_read_b128 v[230:233], v155 offset:4096
	ds_read_b128 v[234:237], v155 offset:5120
	ds_read_b128 v[238:241], v155 offset:6144
	ds_read_b128 v[242:245], v155 offset:7168
	global_load_lds_dwordx4 v148, s[36:37]
	s_add_i32 m0, s13, 0xe000
	s_nop 0
	global_load_lds_dwordx4 v150, s[36:37]
	s_waitcnt vmcnt(8)
	s_waitcnt lgkmcnt(0)
	s_barrier
	s_setprio 1
	s_waitcnt lgkmcnt(0)
	v_mfma_f32_16x16x32_bf16 v[124:127], v[182:185], v[214:217], 0
	v_mfma_f32_16x16x32_bf16 v[120:123], v[190:193], v[214:217], 0
	v_mfma_f32_16x16x32_bf16 v[116:119], v[182:185], v[222:225], 0
	v_mfma_f32_16x16x32_bf16 v[112:115], v[190:193], v[222:225], 0
	v_mfma_f32_16x16x32_bf16 v[100:103], v[182:185], v[230:233], 0
	v_mfma_f32_16x16x32_bf16 v[96:99], v[190:193], v[230:233], 0
	v_mfma_f32_16x16x32_bf16 v[84:87], v[182:185], v[238:241], 0
	v_mfma_f32_16x16x32_bf16 v[80:83], v[190:193], v[238:241], 0
	v_mfma_f32_16x16x32_bf16 v[124:127], v[186:189], v[218:221], v[124:127]
	v_mfma_f32_16x16x32_bf16 v[120:123], v[194:197], v[218:221], v[120:123]
	v_mfma_f32_16x16x32_bf16 v[116:119], v[186:189], v[226:229], v[116:119]
	v_mfma_f32_16x16x32_bf16 v[112:115], v[194:197], v[226:229], v[112:115]
	v_mfma_f32_16x16x32_bf16 v[100:103], v[186:189], v[234:237], v[100:103]
	v_mfma_f32_16x16x32_bf16 v[96:99], v[194:197], v[234:237], v[96:99]
	v_mfma_f32_16x16x32_bf16 v[84:87], v[186:189], v[242:245], v[84:87]
	v_mfma_f32_16x16x32_bf16 v[80:83], v[194:197], v[242:245], v[80:83]
	s_setprio 0
	s_setprio 1
	v_mfma_f32_16x16x32_bf16 v[108:111], v[198:201], v[214:217], 0
	v_mfma_f32_16x16x32_bf16 v[104:107], v[206:209], v[214:217], 0
	v_mfma_f32_16x16x32_bf16 v[92:95], v[198:201], v[222:225], 0
	v_mfma_f32_16x16x32_bf16 v[88:91], v[206:209], v[222:225], 0
	v_mfma_f32_16x16x32_bf16 v[76:79], v[198:201], v[230:233], 0
	v_mfma_f32_16x16x32_bf16 v[72:75], v[206:209], v[230:233], 0
	v_mfma_f32_16x16x32_bf16 v[68:71], v[198:201], v[238:241], 0
	v_mfma_f32_16x16x32_bf16 v[64:67], v[206:209], v[238:241], 0
	v_mfma_f32_16x16x32_bf16 v[108:111], v[202:205], v[218:221], v[108:111]
	v_mfma_f32_16x16x32_bf16 v[104:107], v[210:213], v[218:221], v[104:107]
	v_mfma_f32_16x16x32_bf16 v[92:95], v[202:205], v[226:229], v[92:95]
	v_mfma_f32_16x16x32_bf16 v[88:91], v[210:213], v[226:229], v[88:91]
	v_mfma_f32_16x16x32_bf16 v[76:79], v[202:205], v[234:237], v[76:79]
	v_mfma_f32_16x16x32_bf16 v[72:75], v[210:213], v[234:237], v[72:75]
	v_mfma_f32_16x16x32_bf16 v[68:71], v[202:205], v[242:245], v[68:71]
	v_mfma_f32_16x16x32_bf16 v[64:67], v[210:213], v[242:245], v[64:67]
	s_setprio 0
	s_barrier
	s_add_u32 s60, s42, 0x80
	s_addc_u32 s61, s43, 0
	s_add_u32 s62, s44, 0x80
	s_addc_u32 s63, s45, 0
	s_add_i32 s21, s22, s12
	s_mov_b32 m0, s21
	ds_read_b128 v[214:217], v155 offset:16384
	ds_read_b128 v[218:221], v155 offset:17408
	ds_read_b128 v[222:225], v155 offset:18432
	ds_read_b128 v[226:229], v155 offset:19456
	ds_read_b128 v[230:233], v155 offset:20480
	ds_read_b128 v[234:237], v155 offset:21504
	ds_read_b128 v[238:241], v155 offset:22528
	ds_read_b128 v[242:245], v155 offset:23552
	global_load_lds_dwordx4 v130, s[42:43]
	s_add_i32 m0, s21, 0x2000
	s_add_u32 s34, s42, 0xb0000
	s_addc_u32 s35, s43, 0
	s_add_i32 s21, s23, s12
	global_load_lds_dwordx4 v146, s[42:43]
	s_mov_b32 m0, s21
	s_nop 0
	global_load_lds_dwordx4 v130, s[34:35]
	s_add_i32 m0, s21, 0x2000
	s_nop 0
	global_load_lds_dwordx4 v146, s[34:35]
	s_mov_b32 m0, s13
	s_nop 0
	global_load_lds_dwordx4 v142, s[44:45]
	s_mov_b32 m0, s19
	s_nop 0
	global_load_lds_dwordx4 v144, s[44:45]
	s_waitcnt vmcnt(8)
	s_waitcnt lgkmcnt(0)
	s_barrier
	s_setprio 1
	s_waitcnt lgkmcnt(0)
	v_mfma_f32_16x16x32_bf16 v[60:63], v[182:185], v[214:217], 0
	v_mfma_f32_16x16x32_bf16 v[56:59], v[190:193], v[214:217], 0
	v_mfma_f32_16x16x32_bf16 v[52:55], v[182:185], v[222:225], 0
	v_mfma_f32_16x16x32_bf16 v[48:51], v[190:193], v[222:225], 0
	v_mfma_f32_16x16x32_bf16 v[36:39], v[182:185], v[230:233], 0
	v_mfma_f32_16x16x32_bf16 v[32:35], v[190:193], v[230:233], 0
	v_mfma_f32_16x16x32_bf16 v[20:23], v[182:185], v[238:241], 0
	v_mfma_f32_16x16x32_bf16 v[16:19], v[190:193], v[238:241], 0
	v_mfma_f32_16x16x32_bf16 v[60:63], v[186:189], v[218:221], v[60:63]
	v_mfma_f32_16x16x32_bf16 v[56:59], v[194:197], v[218:221], v[56:59]
	v_mfma_f32_16x16x32_bf16 v[52:55], v[186:189], v[226:229], v[52:55]
	v_mfma_f32_16x16x32_bf16 v[48:51], v[194:197], v[226:229], v[48:51]
	v_mfma_f32_16x16x32_bf16 v[36:39], v[186:189], v[234:237], v[36:39]
	v_mfma_f32_16x16x32_bf16 v[32:35], v[194:197], v[234:237], v[32:35]
	v_mfma_f32_16x16x32_bf16 v[20:23], v[186:189], v[242:245], v[20:23]
	v_mfma_f32_16x16x32_bf16 v[16:19], v[194:197], v[242:245], v[16:19]
	s_setprio 0
	s_setprio 1
	v_mfma_f32_16x16x32_bf16 v[44:47], v[198:201], v[214:217], 0
	v_mfma_f32_16x16x32_bf16 v[40:43], v[206:209], v[214:217], 0
	v_mfma_f32_16x16x32_bf16 v[28:31], v[198:201], v[222:225], 0
	v_mfma_f32_16x16x32_bf16 v[24:27], v[206:209], v[222:225], 0
	v_mfma_f32_16x16x32_bf16 v[12:15], v[198:201], v[230:233], 0
	v_mfma_f32_16x16x32_bf16 v[8:11], v[206:209], v[230:233], 0
	v_mfma_f32_16x16x32_bf16 v[4:7], v[198:201], v[238:241], 0
	v_mfma_f32_16x16x32_bf16 v[0:3], v[206:209], v[238:241], 0
	v_mfma_f32_16x16x32_bf16 v[44:47], v[202:205], v[218:221], v[44:47]
	v_mfma_f32_16x16x32_bf16 v[40:43], v[210:213], v[218:221], v[40:43]
	v_mfma_f32_16x16x32_bf16 v[28:31], v[202:205], v[226:229], v[28:31]
	v_mfma_f32_16x16x32_bf16 v[24:27], v[210:213], v[226:229], v[24:27]
	v_mfma_f32_16x16x32_bf16 v[12:15], v[202:205], v[234:237], v[12:15]
	v_mfma_f32_16x16x32_bf16 v[8:11], v[210:213], v[234:237], v[8:11]
	v_mfma_f32_16x16x32_bf16 v[4:7], v[202:205], v[242:245], v[4:7]
	v_mfma_f32_16x16x32_bf16 v[0:3], v[210:213], v[242:245], v[0:3]
	s_setprio 0
	s_barrier
	s_add_i32 s34, 0, 0x18000
	v_add_u32_e32 v181, s34, v153
	s_add_i32 s35, 0, 0x1c000
	ds_read_b128 v[182:185], v181
	ds_read_b128 v[186:189], v181 offset:1024
	ds_read_b128 v[190:193], v181 offset:2048
	ds_read_b128 v[194:197], v181 offset:3072
	v_add_u32_e32 v181, s35, v153
	ds_read_b128 v[198:201], v181
	ds_read_b128 v[202:205], v181 offset:1024
	ds_read_b128 v[206:209], v181 offset:2048
	ds_read_b128 v[210:213], v181 offset:3072
	s_add_u32 s36, s44, 0xb0000
	s_addc_u32 s37, s45, 0
	s_mov_b32 m0, s20
	ds_read_b128 v[214:217], v155 offset:32768
	ds_read_b128 v[218:221], v155 offset:33792
	ds_read_b128 v[222:225], v155 offset:34816
	ds_read_b128 v[226:229], v155 offset:35840
	ds_read_b128 v[230:233], v155 offset:36864
	ds_read_b128 v[234:237], v155 offset:37888
	ds_read_b128 v[238:241], v155 offset:38912
	ds_read_b128 v[242:245], v155 offset:39936
	global_load_lds_dwordx4 v142, s[36:37]
	s_mov_b32 m0, s26
	s_nop 0
	global_load_lds_dwordx4 v144, s[36:37]
	s_waitcnt vmcnt(8)
	s_waitcnt lgkmcnt(0)
	s_barrier
	s_setprio 1
	s_waitcnt lgkmcnt(0)
	v_mfma_f32_16x16x32_bf16 v[124:127], v[182:185], v[214:217], v[124:127]
	v_mfma_f32_16x16x32_bf16 v[120:123], v[190:193], v[214:217], v[120:123]
	v_mfma_f32_16x16x32_bf16 v[116:119], v[182:185], v[222:225], v[116:119]
	v_mfma_f32_16x16x32_bf16 v[112:115], v[190:193], v[222:225], v[112:115]
	v_mfma_f32_16x16x32_bf16 v[100:103], v[182:185], v[230:233], v[100:103]
	v_mfma_f32_16x16x32_bf16 v[96:99], v[190:193], v[230:233], v[96:99]
	v_mfma_f32_16x16x32_bf16 v[84:87], v[182:185], v[238:241], v[84:87]
	v_mfma_f32_16x16x32_bf16 v[80:83], v[190:193], v[238:241], v[80:83]
	v_mfma_f32_16x16x32_bf16 v[124:127], v[186:189], v[218:221], v[124:127]
	v_mfma_f32_16x16x32_bf16 v[120:123], v[194:197], v[218:221], v[120:123]
	v_mfma_f32_16x16x32_bf16 v[116:119], v[186:189], v[226:229], v[116:119]
	v_mfma_f32_16x16x32_bf16 v[112:115], v[194:197], v[226:229], v[112:115]
	v_mfma_f32_16x16x32_bf16 v[100:103], v[186:189], v[234:237], v[100:103]
	v_mfma_f32_16x16x32_bf16 v[96:99], v[194:197], v[234:237], v[96:99]
	v_mfma_f32_16x16x32_bf16 v[84:87], v[186:189], v[242:245], v[84:87]
	v_mfma_f32_16x16x32_bf16 v[80:83], v[194:197], v[242:245], v[80:83]
	s_setprio 0
	s_setprio 1
	v_mfma_f32_16x16x32_bf16 v[108:111], v[198:201], v[214:217], v[108:111]
	v_mfma_f32_16x16x32_bf16 v[104:107], v[206:209], v[214:217], v[104:107]
	v_mfma_f32_16x16x32_bf16 v[92:95], v[198:201], v[222:225], v[92:95]
	v_mfma_f32_16x16x32_bf16 v[88:91], v[206:209], v[222:225], v[88:91]
	v_mfma_f32_16x16x32_bf16 v[76:79], v[198:201], v[230:233], v[76:79]
	v_mfma_f32_16x16x32_bf16 v[72:75], v[206:209], v[230:233], v[72:75]
	v_mfma_f32_16x16x32_bf16 v[68:71], v[198:201], v[238:241], v[68:71]
	v_mfma_f32_16x16x32_bf16 v[64:67], v[206:209], v[238:241], v[64:67]
	v_mfma_f32_16x16x32_bf16 v[108:111], v[202:205], v[218:221], v[108:111]
	v_mfma_f32_16x16x32_bf16 v[104:107], v[210:213], v[218:221], v[104:107]
	v_mfma_f32_16x16x32_bf16 v[92:95], v[202:205], v[226:229], v[92:95]
	v_mfma_f32_16x16x32_bf16 v[88:91], v[210:213], v[226:229], v[88:91]
	v_mfma_f32_16x16x32_bf16 v[76:79], v[202:205], v[234:237], v[76:79]
	v_mfma_f32_16x16x32_bf16 v[72:75], v[210:213], v[234:237], v[72:75]
	v_mfma_f32_16x16x32_bf16 v[68:71], v[202:205], v[242:245], v[68:71]
	v_mfma_f32_16x16x32_bf16 v[64:67], v[210:213], v[242:245], v[64:67]
	s_setprio 0
	s_barrier
	s_add_i32 s21, s34, s12
	s_mov_b32 m0, s21
	ds_read_b128 v[214:217], v155 offset:49152
	ds_read_b128 v[218:221], v155 offset:50176
	ds_read_b128 v[222:225], v155 offset:51200
	ds_read_b128 v[226:229], v155 offset:52224
	ds_read_b128 v[230:233], v155 offset:53248
	ds_read_b128 v[234:237], v155 offset:54272
	ds_read_b128 v[238:241], v155 offset:55296
	ds_read_b128 v[242:245], v155 offset:56320
	global_load_lds_dwordx4 v130, s[60:61]
	s_add_i32 m0, s21, 0x2000
	s_add_u32 s36, s42, 0xb0080
	s_addc_u32 s37, s43, 0
	s_add_i32 s21, s35, s12
	global_load_lds_dwordx4 v146, s[60:61]
	s_mov_b32 m0, s21
	s_nop 0
	global_load_lds_dwordx4 v130, s[36:37]
	s_add_i32 m0, s21, 0x2000
	s_nop 0
	global_load_lds_dwordx4 v146, s[36:37]
	s_mov_b32 m0, s33
	s_nop 0
	global_load_lds_dwordx4 v142, s[62:63]
	s_mov_b32 m0, s38
	s_nop 0
	global_load_lds_dwordx4 v144, s[62:63]
	s_waitcnt vmcnt(8)
	s_waitcnt lgkmcnt(0)
	s_barrier
	s_setprio 1
	s_waitcnt lgkmcnt(0)
	v_mfma_f32_16x16x32_bf16 v[60:63], v[182:185], v[214:217], v[60:63]
	v_mfma_f32_16x16x32_bf16 v[56:59], v[190:193], v[214:217], v[56:59]
	v_mfma_f32_16x16x32_bf16 v[52:55], v[182:185], v[222:225], v[52:55]
	v_mfma_f32_16x16x32_bf16 v[48:51], v[190:193], v[222:225], v[48:51]
	v_mfma_f32_16x16x32_bf16 v[36:39], v[182:185], v[230:233], v[36:39]
	v_mfma_f32_16x16x32_bf16 v[32:35], v[190:193], v[230:233], v[32:35]
	v_mfma_f32_16x16x32_bf16 v[20:23], v[182:185], v[238:241], v[20:23]
	v_mfma_f32_16x16x32_bf16 v[16:19], v[190:193], v[238:241], v[16:19]
	v_mfma_f32_16x16x32_bf16 v[60:63], v[186:189], v[218:221], v[60:63]
	v_mfma_f32_16x16x32_bf16 v[56:59], v[194:197], v[218:221], v[56:59]
	v_mfma_f32_16x16x32_bf16 v[52:55], v[186:189], v[226:229], v[52:55]
	v_mfma_f32_16x16x32_bf16 v[48:51], v[194:197], v[226:229], v[48:51]
	v_mfma_f32_16x16x32_bf16 v[36:39], v[186:189], v[234:237], v[36:39]
	v_mfma_f32_16x16x32_bf16 v[32:35], v[194:197], v[234:237], v[32:35]
	v_mfma_f32_16x16x32_bf16 v[20:23], v[186:189], v[242:245], v[20:23]
	v_mfma_f32_16x16x32_bf16 v[16:19], v[194:197], v[242:245], v[16:19]
	s_setprio 0
	s_setprio 1
	v_mfma_f32_16x16x32_bf16 v[44:47], v[198:201], v[214:217], v[44:47]
	v_mfma_f32_16x16x32_bf16 v[40:43], v[206:209], v[214:217], v[40:43]
	v_mfma_f32_16x16x32_bf16 v[28:31], v[198:201], v[222:225], v[28:31]
	v_mfma_f32_16x16x32_bf16 v[24:27], v[206:209], v[222:225], v[24:27]
	v_mfma_f32_16x16x32_bf16 v[12:15], v[198:201], v[230:233], v[12:15]
	v_mfma_f32_16x16x32_bf16 v[8:11], v[206:209], v[230:233], v[8:11]
	v_mfma_f32_16x16x32_bf16 v[4:7], v[198:201], v[238:241], v[4:7]
	v_mfma_f32_16x16x32_bf16 v[0:3], v[206:209], v[238:241], v[0:3]
	v_mfma_f32_16x16x32_bf16 v[44:47], v[202:205], v[218:221], v[44:47]
	v_mfma_f32_16x16x32_bf16 v[40:43], v[210:213], v[218:221], v[40:43]
	v_mfma_f32_16x16x32_bf16 v[28:31], v[202:205], v[226:229], v[28:31]
	v_mfma_f32_16x16x32_bf16 v[24:27], v[210:213], v[226:229], v[24:27]
	v_mfma_f32_16x16x32_bf16 v[12:15], v[202:205], v[234:237], v[12:15]
	v_mfma_f32_16x16x32_bf16 v[8:11], v[210:213], v[234:237], v[8:11]
	v_mfma_f32_16x16x32_bf16 v[4:7], v[202:205], v[242:245], v[4:7]
	v_mfma_f32_16x16x32_bf16 v[0:3], v[210:213], v[242:245], v[0:3]
	s_setprio 0
	s_barrier
	s_add_u32 s50, s50, 0x100
	s_addc_u32 s51, s51, 0
	s_cmp_ge_i32 s52, s49
	s_mov_b64 s[36:37], s[40:41]
	s_mov_b32 s42, s52
	s_cbranch_scc1 .Lpeel_done_286
.LBB0_286:
	s_add_i32 s52, s42, 2
	s_add_u32 s40, s36, 0x100
	s_addc_u32 s41, s37, 0
	s_add_i32 s22, 0, 0x10000
	s_cmp_eq_u32 s11, s42
	s_cselect_b32 s45, s17, s41
	s_cselect_b32 s44, s16, s40
	v_add_u32_e32 v156, s22, v153
	s_cselect_b32 s43, s29, s51
	s_cselect_b32 s42, s28, s50
	s_add_i32 s23, 0, 0x14000
	ds_read_b128 v[182:185], v156
	ds_read_b128 v[186:189], v156 offset:1024
	ds_read_b128 v[190:193], v156 offset:2048
	ds_read_b128 v[194:197], v156 offset:3072
	v_add_u32_e32 v156, s23, v153
	ds_read_b128 v[198:201], v156
	ds_read_b128 v[202:205], v156 offset:1024
	ds_read_b128 v[206:209], v156 offset:2048
	ds_read_b128 v[210:213], v156 offset:3072
	s_add_i32 m0, s13, 0xc000
	ds_read_b128 v[214:217], v155
	ds_read_b128 v[218:221], v155 offset:1024
	ds_read_b128 v[222:225], v155 offset:2048
	ds_read_b128 v[226:229], v155 offset:3072
	ds_read_b128 v[230:233], v155 offset:4096
	ds_read_b128 v[234:237], v155 offset:5120
	ds_read_b128 v[238:241], v155 offset:6144
	ds_read_b128 v[242:245], v155 offset:7168
	global_load_lds_dwordx4 v148, s[36:37]
	s_add_i32 m0, s13, 0xe000
	s_nop 0
	global_load_lds_dwordx4 v150, s[36:37]
	s_waitcnt vmcnt(8)
	s_waitcnt lgkmcnt(0)
	s_barrier
	s_setprio 1
	s_waitcnt lgkmcnt(0)
	v_mfma_f32_16x16x32_bf16 v[124:127], v[182:185], v[214:217], v[124:127]
	v_mfma_f32_16x16x32_bf16 v[120:123], v[190:193], v[214:217], v[120:123]
	v_mfma_f32_16x16x32_bf16 v[116:119], v[182:185], v[222:225], v[116:119]
	v_mfma_f32_16x16x32_bf16 v[112:115], v[190:193], v[222:225], v[112:115]
	v_mfma_f32_16x16x32_bf16 v[100:103], v[182:185], v[230:233], v[100:103]
	v_mfma_f32_16x16x32_bf16 v[96:99], v[190:193], v[230:233], v[96:99]
	v_mfma_f32_16x16x32_bf16 v[84:87], v[182:185], v[238:241], v[84:87]
	v_mfma_f32_16x16x32_bf16 v[80:83], v[190:193], v[238:241], v[80:83]
	v_mfma_f32_16x16x32_bf16 v[124:127], v[186:189], v[218:221], v[124:127]
	v_mfma_f32_16x16x32_bf16 v[120:123], v[194:197], v[218:221], v[120:123]
	v_mfma_f32_16x16x32_bf16 v[116:119], v[186:189], v[226:229], v[116:119]
	v_mfma_f32_16x16x32_bf16 v[112:115], v[194:197], v[226:229], v[112:115]
	v_mfma_f32_16x16x32_bf16 v[100:103], v[186:189], v[234:237], v[100:103]
	v_mfma_f32_16x16x32_bf16 v[96:99], v[194:197], v[234:237], v[96:99]
	v_mfma_f32_16x16x32_bf16 v[84:87], v[186:189], v[242:245], v[84:87]
	v_mfma_f32_16x16x32_bf16 v[80:83], v[194:197], v[242:245], v[80:83]
	s_setprio 0
	s_setprio 1
	v_mfma_f32_16x16x32_bf16 v[108:111], v[198:201], v[214:217], v[108:111]
	v_mfma_f32_16x16x32_bf16 v[104:107], v[206:209], v[214:217], v[104:107]
	v_mfma_f32_16x16x32_bf16 v[92:95], v[198:201], v[222:225], v[92:95]
	v_mfma_f32_16x16x32_bf16 v[88:91], v[206:209], v[222:225], v[88:91]
	v_mfma_f32_16x16x32_bf16 v[76:79], v[198:201], v[230:233], v[76:79]
	v_mfma_f32_16x16x32_bf16 v[72:75], v[206:209], v[230:233], v[72:75]
	v_mfma_f32_16x16x32_bf16 v[68:71], v[198:201], v[238:241], v[68:71]
	v_mfma_f32_16x16x32_bf16 v[64:67], v[206:209], v[238:241], v[64:67]
	v_mfma_f32_16x16x32_bf16 v[108:111], v[202:205], v[218:221], v[108:111]
	v_mfma_f32_16x16x32_bf16 v[104:107], v[210:213], v[218:221], v[104:107]
	v_mfma_f32_16x16x32_bf16 v[92:95], v[202:205], v[226:229], v[92:95]
	v_mfma_f32_16x16x32_bf16 v[88:91], v[210:213], v[226:229], v[88:91]
	v_mfma_f32_16x16x32_bf16 v[76:79], v[202:205], v[234:237], v[76:79]
	v_mfma_f32_16x16x32_bf16 v[72:75], v[210:213], v[234:237], v[72:75]
	v_mfma_f32_16x16x32_bf16 v[68:71], v[202:205], v[242:245], v[68:71]
	v_mfma_f32_16x16x32_bf16 v[64:67], v[210:213], v[242:245], v[64:67]
	s_setprio 0
	s_barrier
	s_add_u32 s60, s42, 0x80
	s_addc_u32 s61, s43, 0
	s_add_u32 s62, s44, 0x80
	s_addc_u32 s63, s45, 0
	s_add_i32 s21, s22, s12
	s_mov_b32 m0, s21
	ds_read_b128 v[214:217], v155 offset:16384
	ds_read_b128 v[218:221], v155 offset:17408
	ds_read_b128 v[222:225], v155 offset:18432
	ds_read_b128 v[226:229], v155 offset:19456
	ds_read_b128 v[230:233], v155 offset:20480
	ds_read_b128 v[234:237], v155 offset:21504
	ds_read_b128 v[238:241], v155 offset:22528
	ds_read_b128 v[242:245], v155 offset:23552
	global_load_lds_dwordx4 v130, s[42:43]
	s_add_i32 m0, s21, 0x2000
	s_add_u32 s34, s42, 0xb0000
	s_addc_u32 s35, s43, 0
	s_add_i32 s21, s23, s12
	global_load_lds_dwordx4 v146, s[42:43]
	s_mov_b32 m0, s21
	s_nop 0
	global_load_lds_dwordx4 v130, s[34:35]
	s_add_i32 m0, s21, 0x2000
	s_nop 0
	global_load_lds_dwordx4 v146, s[34:35]
	s_mov_b32 m0, s13
	s_nop 0
	global_load_lds_dwordx4 v142, s[44:45]
	s_mov_b32 m0, s19
	s_nop 0
	global_load_lds_dwordx4 v144, s[44:45]
	s_waitcnt vmcnt(8)
	s_waitcnt lgkmcnt(0)
	s_barrier
	s_setprio 1
	s_waitcnt lgkmcnt(0)
	v_mfma_f32_16x16x32_bf16 v[60:63], v[182:185], v[214:217], v[60:63]
	v_mfma_f32_16x16x32_bf16 v[56:59], v[190:193], v[214:217], v[56:59]
	v_mfma_f32_16x16x32_bf16 v[52:55], v[182:185], v[222:225], v[52:55]
	v_mfma_f32_16x16x32_bf16 v[48:51], v[190:193], v[222:225], v[48:51]
	v_mfma_f32_16x16x32_bf16 v[36:39], v[182:185], v[230:233], v[36:39]
	v_mfma_f32_16x16x32_bf16 v[32:35], v[190:193], v[230:233], v[32:35]
	v_mfma_f32_16x16x32_bf16 v[20:23], v[182:185], v[238:241], v[20:23]
	v_mfma_f32_16x16x32_bf16 v[16:19], v[190:193], v[238:241], v[16:19]
	v_mfma_f32_16x16x32_bf16 v[60:63], v[186:189], v[218:221], v[60:63]
	v_mfma_f32_16x16x32_bf16 v[56:59], v[194:197], v[218:221], v[56:59]
	v_mfma_f32_16x16x32_bf16 v[52:55], v[186:189], v[226:229], v[52:55]
	v_mfma_f32_16x16x32_bf16 v[48:51], v[194:197], v[226:229], v[48:51]
	v_mfma_f32_16x16x32_bf16 v[36:39], v[186:189], v[234:237], v[36:39]
	v_mfma_f32_16x16x32_bf16 v[32:35], v[194:197], v[234:237], v[32:35]
	v_mfma_f32_16x16x32_bf16 v[20:23], v[186:189], v[242:245], v[20:23]
	v_mfma_f32_16x16x32_bf16 v[16:19], v[194:197], v[242:245], v[16:19]
	s_setprio 0
	s_setprio 1
	v_mfma_f32_16x16x32_bf16 v[44:47], v[198:201], v[214:217], v[44:47]
	v_mfma_f32_16x16x32_bf16 v[40:43], v[206:209], v[214:217], v[40:43]
	v_mfma_f32_16x16x32_bf16 v[28:31], v[198:201], v[222:225], v[28:31]
	v_mfma_f32_16x16x32_bf16 v[24:27], v[206:209], v[222:225], v[24:27]
	v_mfma_f32_16x16x32_bf16 v[12:15], v[198:201], v[230:233], v[12:15]
	v_mfma_f32_16x16x32_bf16 v[8:11], v[206:209], v[230:233], v[8:11]
	v_mfma_f32_16x16x32_bf16 v[4:7], v[198:201], v[238:241], v[4:7]
	v_mfma_f32_16x16x32_bf16 v[0:3], v[206:209], v[238:241], v[0:3]
	v_mfma_f32_16x16x32_bf16 v[44:47], v[202:205], v[218:221], v[44:47]
	v_mfma_f32_16x16x32_bf16 v[40:43], v[210:213], v[218:221], v[40:43]
	v_mfma_f32_16x16x32_bf16 v[28:31], v[202:205], v[226:229], v[28:31]
	v_mfma_f32_16x16x32_bf16 v[24:27], v[210:213], v[226:229], v[24:27]
	v_mfma_f32_16x16x32_bf16 v[12:15], v[202:205], v[234:237], v[12:15]
	v_mfma_f32_16x16x32_bf16 v[8:11], v[210:213], v[234:237], v[8:11]
	v_mfma_f32_16x16x32_bf16 v[4:7], v[202:205], v[242:245], v[4:7]
	v_mfma_f32_16x16x32_bf16 v[0:3], v[210:213], v[242:245], v[0:3]
	s_setprio 0
	s_barrier
	s_add_i32 s34, 0, 0x18000
	v_add_u32_e32 v181, s34, v153
	s_add_i32 s35, 0, 0x1c000
	ds_read_b128 v[182:185], v181
	ds_read_b128 v[186:189], v181 offset:1024
	ds_read_b128 v[190:193], v181 offset:2048
	ds_read_b128 v[194:197], v181 offset:3072
	v_add_u32_e32 v181, s35, v153
	ds_read_b128 v[198:201], v181
	ds_read_b128 v[202:205], v181 offset:1024
	ds_read_b128 v[206:209], v181 offset:2048
	ds_read_b128 v[210:213], v181 offset:3072
	s_add_u32 s36, s44, 0xb0000
	s_addc_u32 s37, s45, 0
	s_mov_b32 m0, s20
	ds_read_b128 v[214:217], v155 offset:32768
	ds_read_b128 v[218:221], v155 offset:33792
	ds_read_b128 v[222:225], v155 offset:34816
	ds_read_b128 v[226:229], v155 offset:35840
	ds_read_b128 v[230:233], v155 offset:36864
	ds_read_b128 v[234:237], v155 offset:37888
	ds_read_b128 v[238:241], v155 offset:38912
	ds_read_b128 v[242:245], v155 offset:39936
	global_load_lds_dwordx4 v142, s[36:37]
	s_mov_b32 m0, s26
	s_nop 0
	global_load_lds_dwordx4 v144, s[36:37]
	s_waitcnt vmcnt(8)
	s_waitcnt lgkmcnt(0)
	s_barrier
	s_setprio 1
	s_waitcnt lgkmcnt(0)
	v_mfma_f32_16x16x32_bf16 v[124:127], v[182:185], v[214:217], v[124:127]
	v_mfma_f32_16x16x32_bf16 v[120:123], v[190:193], v[214:217], v[120:123]
	v_mfma_f32_16x16x32_bf16 v[116:119], v[182:185], v[222:225], v[116:119]
	v_mfma_f32_16x16x32_bf16 v[112:115], v[190:193], v[222:225], v[112:115]
	v_mfma_f32_16x16x32_bf16 v[100:103], v[182:185], v[230:233], v[100:103]
	v_mfma_f32_16x16x32_bf16 v[96:99], v[190:193], v[230:233], v[96:99]
	v_mfma_f32_16x16x32_bf16 v[84:87], v[182:185], v[238:241], v[84:87]
	v_mfma_f32_16x16x32_bf16 v[80:83], v[190:193], v[238:241], v[80:83]
	v_mfma_f32_16x16x32_bf16 v[124:127], v[186:189], v[218:221], v[124:127]
	v_mfma_f32_16x16x32_bf16 v[120:123], v[194:197], v[218:221], v[120:123]
	v_mfma_f32_16x16x32_bf16 v[116:119], v[186:189], v[226:229], v[116:119]
	v_mfma_f32_16x16x32_bf16 v[112:115], v[194:197], v[226:229], v[112:115]
	v_mfma_f32_16x16x32_bf16 v[100:103], v[186:189], v[234:237], v[100:103]
	v_mfma_f32_16x16x32_bf16 v[96:99], v[194:197], v[234:237], v[96:99]
	v_mfma_f32_16x16x32_bf16 v[84:87], v[186:189], v[242:245], v[84:87]
	v_mfma_f32_16x16x32_bf16 v[80:83], v[194:197], v[242:245], v[80:83]
	s_setprio 0
	s_setprio 1
	v_mfma_f32_16x16x32_bf16 v[108:111], v[198:201], v[214:217], v[108:111]
	v_mfma_f32_16x16x32_bf16 v[104:107], v[206:209], v[214:217], v[104:107]
	v_mfma_f32_16x16x32_bf16 v[92:95], v[198:201], v[222:225], v[92:95]
	v_mfma_f32_16x16x32_bf16 v[88:91], v[206:209], v[222:225], v[88:91]
	v_mfma_f32_16x16x32_bf16 v[76:79], v[198:201], v[230:233], v[76:79]
	v_mfma_f32_16x16x32_bf16 v[72:75], v[206:209], v[230:233], v[72:75]
	v_mfma_f32_16x16x32_bf16 v[68:71], v[198:201], v[238:241], v[68:71]
	v_mfma_f32_16x16x32_bf16 v[64:67], v[206:209], v[238:241], v[64:67]
	v_mfma_f32_16x16x32_bf16 v[108:111], v[202:205], v[218:221], v[108:111]
	v_mfma_f32_16x16x32_bf16 v[104:107], v[210:213], v[218:221], v[104:107]
	v_mfma_f32_16x16x32_bf16 v[92:95], v[202:205], v[226:229], v[92:95]
	v_mfma_f32_16x16x32_bf16 v[88:91], v[210:213], v[226:229], v[88:91]
	v_mfma_f32_16x16x32_bf16 v[76:79], v[202:205], v[234:237], v[76:79]
	v_mfma_f32_16x16x32_bf16 v[72:75], v[210:213], v[234:237], v[72:75]
	v_mfma_f32_16x16x32_bf16 v[68:71], v[202:205], v[242:245], v[68:71]
	v_mfma_f32_16x16x32_bf16 v[64:67], v[210:213], v[242:245], v[64:67]
	s_setprio 0
	s_barrier
	s_add_i32 s21, s34, s12
	s_mov_b32 m0, s21
	ds_read_b128 v[214:217], v155 offset:49152
	ds_read_b128 v[218:221], v155 offset:50176
	ds_read_b128 v[222:225], v155 offset:51200
	ds_read_b128 v[226:229], v155 offset:52224
	ds_read_b128 v[230:233], v155 offset:53248
	ds_read_b128 v[234:237], v155 offset:54272
	ds_read_b128 v[238:241], v155 offset:55296
	ds_read_b128 v[242:245], v155 offset:56320
	global_load_lds_dwordx4 v130, s[60:61]
	s_add_i32 m0, s21, 0x2000
	s_add_u32 s36, s42, 0xb0080
	s_addc_u32 s37, s43, 0
	s_add_i32 s21, s35, s12
	global_load_lds_dwordx4 v146, s[60:61]
	s_mov_b32 m0, s21
	s_nop 0
	global_load_lds_dwordx4 v130, s[36:37]
	s_add_i32 m0, s21, 0x2000
	s_nop 0
	global_load_lds_dwordx4 v146, s[36:37]
	s_mov_b32 m0, s33
	s_nop 0
	global_load_lds_dwordx4 v142, s[62:63]
	s_mov_b32 m0, s38
	s_nop 0
	global_load_lds_dwordx4 v144, s[62:63]
	s_waitcnt vmcnt(8)
	s_waitcnt lgkmcnt(0)
	s_barrier
	s_setprio 1
	s_waitcnt lgkmcnt(0)
	v_mfma_f32_16x16x32_bf16 v[60:63], v[182:185], v[214:217], v[60:63]
	v_mfma_f32_16x16x32_bf16 v[56:59], v[190:193], v[214:217], v[56:59]
	v_mfma_f32_16x16x32_bf16 v[52:55], v[182:185], v[222:225], v[52:55]
	v_mfma_f32_16x16x32_bf16 v[48:51], v[190:193], v[222:225], v[48:51]
	v_mfma_f32_16x16x32_bf16 v[36:39], v[182:185], v[230:233], v[36:39]
	v_mfma_f32_16x16x32_bf16 v[32:35], v[190:193], v[230:233], v[32:35]
	v_mfma_f32_16x16x32_bf16 v[20:23], v[182:185], v[238:241], v[20:23]
	v_mfma_f32_16x16x32_bf16 v[16:19], v[190:193], v[238:241], v[16:19]
	v_mfma_f32_16x16x32_bf16 v[60:63], v[186:189], v[218:221], v[60:63]
	v_mfma_f32_16x16x32_bf16 v[56:59], v[194:197], v[218:221], v[56:59]
	v_mfma_f32_16x16x32_bf16 v[52:55], v[186:189], v[226:229], v[52:55]
	v_mfma_f32_16x16x32_bf16 v[48:51], v[194:197], v[226:229], v[48:51]
	v_mfma_f32_16x16x32_bf16 v[36:39], v[186:189], v[234:237], v[36:39]
	v_mfma_f32_16x16x32_bf16 v[32:35], v[194:197], v[234:237], v[32:35]
	v_mfma_f32_16x16x32_bf16 v[20:23], v[186:189], v[242:245], v[20:23]
	v_mfma_f32_16x16x32_bf16 v[16:19], v[194:197], v[242:245], v[16:19]
	s_setprio 0
	s_setprio 1
	v_mfma_f32_16x16x32_bf16 v[44:47], v[198:201], v[214:217], v[44:47]
	v_mfma_f32_16x16x32_bf16 v[40:43], v[206:209], v[214:217], v[40:43]
	v_mfma_f32_16x16x32_bf16 v[28:31], v[198:201], v[222:225], v[28:31]
	v_mfma_f32_16x16x32_bf16 v[24:27], v[206:209], v[222:225], v[24:27]
	v_mfma_f32_16x16x32_bf16 v[12:15], v[198:201], v[230:233], v[12:15]
	v_mfma_f32_16x16x32_bf16 v[8:11], v[206:209], v[230:233], v[8:11]
	v_mfma_f32_16x16x32_bf16 v[4:7], v[198:201], v[238:241], v[4:7]
	v_mfma_f32_16x16x32_bf16 v[0:3], v[206:209], v[238:241], v[0:3]
	v_mfma_f32_16x16x32_bf16 v[44:47], v[202:205], v[218:221], v[44:47]
	v_mfma_f32_16x16x32_bf16 v[40:43], v[210:213], v[218:221], v[40:43]
	v_mfma_f32_16x16x32_bf16 v[28:31], v[202:205], v[226:229], v[28:31]
	v_mfma_f32_16x16x32_bf16 v[24:27], v[210:213], v[226:229], v[24:27]
	v_mfma_f32_16x16x32_bf16 v[12:15], v[202:205], v[234:237], v[12:15]
	v_mfma_f32_16x16x32_bf16 v[8:11], v[210:213], v[234:237], v[8:11]
	v_mfma_f32_16x16x32_bf16 v[4:7], v[202:205], v[242:245], v[4:7]
	v_mfma_f32_16x16x32_bf16 v[0:3], v[210:213], v[242:245], v[0:3]
	s_setprio 0
	s_barrier
	s_add_u32 s50, s50, 0x100
	s_addc_u32 s51, s51, 0
	s_cmp_ge_i32 s52, s49
	s_mov_b64 s[36:37], s[40:41]
	s_mov_b32 s42, s52
	s_cbranch_scc0 .LBB0_286
.Lpeel_done_286:
	s_and_b64 vcc, exec, s[8:9]
	s_cbranch_vccz .LBB0_289
	s_barrier

.LBB0_510:
	s_ashr_i32 s17, s16, 31
	s_lshl_b64 s[18:19], s[16:17], 19
	v_readlane_b32 s24, v252, 27
	v_readlane_b32 s25, v252, 28
	s_add_u32 s28, s24, s18
	s_addc_u32 s29, s25, s19
	s_and_b64 s[18:19], s[4:5], exec
	s_cselect_b32 s17, s29, s41
	s_cselect_b32 s18, s28, s40
	s_ashr_i32 s11, s10, 31
	s_lshl_b64 s[36:37], s[10:11], 19
	v_readlane_b32 s11, v252, 8
	s_add_u32 s36, s11, s36
	v_readlane_b32 s11, v252, 9
	s_addc_u32 s37, s11, s37
	s_and_b64 s[38:39], s[4:5], exec
	s_cselect_b32 s11, s37, s43
	s_cselect_b32 s19, s36, s42
	s_add_u32 s40, s40, 0x40080
	s_addc_u32 s41, s41, 0
	s_add_u32 s38, s42, 0x100
	s_addc_u32 s39, s43, 0
	s_mov_b32 s46, -2
	v_add_u32_e32 v156, s22, v153
	ds_read_b128 v[182:185], v156
	ds_read_b128 v[186:189], v156 offset:1024
	ds_read_b128 v[190:193], v156 offset:2048
	ds_read_b128 v[194:197], v156 offset:3072
	v_add_u32_e32 v156, s23, v153
	ds_read_b128 v[198:201], v156
	ds_read_b128 v[202:205], v156 offset:1024
	ds_read_b128 v[206:209], v156 offset:2048
	ds_read_b128 v[210:213], v156 offset:3072
	s_add_u32 s21, s40, 0xfffc0080
	s_addc_u32 s24, s41, -1
	s_cmp_eq_u32 s46, 12
	s_cselect_b32 s45, s17, s24
	s_cselect_b32 s44, s18, s21
	s_cselect_b32 s43, s11, s39
	s_cselect_b32 s42, s19, s38
	s_add_i32 m0, s12, 0xc000
	ds_read_b128 v[214:217], v155
	ds_read_b128 v[218:221], v155 offset:1024
	ds_read_b128 v[222:225], v155 offset:2048
	ds_read_b128 v[226:229], v155 offset:3072
	ds_read_b128 v[230:233], v155 offset:4096
	ds_read_b128 v[234:237], v155 offset:5120
	ds_read_b128 v[238:241], v155 offset:6144
	ds_read_b128 v[242:245], v155 offset:7168
	global_load_lds_dwordx4 v148, s[40:41]
	s_add_i32 m0, s12, 0xe000
	s_nop 0
	global_load_lds_dwordx4 v150, s[40:41]
	s_waitcnt vmcnt(8)
	s_waitcnt lgkmcnt(0)
	s_barrier
	s_setprio 1
	s_waitcnt lgkmcnt(0)
	v_mfma_f32_16x16x32_bf16 v[124:127], v[182:185], v[214:217], 0
	v_mfma_f32_16x16x32_bf16 v[120:123], v[190:193], v[214:217], 0
	v_mfma_f32_16x16x32_bf16 v[116:119], v[182:185], v[222:225], 0
	v_mfma_f32_16x16x32_bf16 v[112:115], v[190:193], v[222:225], 0
	v_mfma_f32_16x16x32_bf16 v[100:103], v[182:185], v[230:233], 0
	v_mfma_f32_16x16x32_bf16 v[96:99], v[190:193], v[230:233], 0
	v_mfma_f32_16x16x32_bf16 v[84:87], v[182:185], v[238:241], 0
	v_mfma_f32_16x16x32_bf16 v[80:83], v[190:193], v[238:241], 0
	v_mfma_f32_16x16x32_bf16 v[124:127], v[186:189], v[218:221], v[124:127]
	v_mfma_f32_16x16x32_bf16 v[120:123], v[194:197], v[218:221], v[120:123]
	v_mfma_f32_16x16x32_bf16 v[116:119], v[186:189], v[226:229], v[116:119]
	v_mfma_f32_16x16x32_bf16 v[112:115], v[194:197], v[226:229], v[112:115]
	v_mfma_f32_16x16x32_bf16 v[100:103], v[186:189], v[234:237], v[100:103]
	v_mfma_f32_16x16x32_bf16 v[96:99], v[194:197], v[234:237], v[96:99]
	v_mfma_f32_16x16x32_bf16 v[84:87], v[186:189], v[242:245], v[84:87]
	v_mfma_f32_16x16x32_bf16 v[80:83], v[194:197], v[242:245], v[80:83]
	s_setprio 0
	s_setprio 1
	v_mfma_f32_16x16x32_bf16 v[108:111], v[198:201], v[214:217], 0
	v_mfma_f32_16x16x32_bf16 v[104:107], v[206:209], v[214:217], 0
	v_mfma_f32_16x16x32_bf16 v[92:95], v[198:201], v[222:225], 0
	v_mfma_f32_16x16x32_bf16 v[88:91], v[206:209], v[222:225], 0
	v_mfma_f32_16x16x32_bf16 v[76:79], v[198:201], v[230:233], 0
	v_mfma_f32_16x16x32_bf16 v[72:75], v[206:209], v[230:233], 0
	v_mfma_f32_16x16x32_bf16 v[68:71], v[198:201], v[238:241], 0
	v_mfma_f32_16x16x32_bf16 v[64:67], v[206:209], v[238:241], 0
	v_mfma_f32_16x16x32_bf16 v[108:111], v[202:205], v[218:221], v[108:111]
	v_mfma_f32_16x16x32_bf16 v[104:107], v[210:213], v[218:221], v[104:107]
	v_mfma_f32_16x16x32_bf16 v[92:95], v[202:205], v[226:229], v[92:95]
	v_mfma_f32_16x16x32_bf16 v[88:91], v[210:213], v[226:229], v[88:91]
	v_mfma_f32_16x16x32_bf16 v[76:79], v[202:205], v[234:237], v[76:79]
	v_mfma_f32_16x16x32_bf16 v[72:75], v[210:213], v[234:237], v[72:75]
	v_mfma_f32_16x16x32_bf16 v[68:71], v[202:205], v[242:245], v[68:71]
	v_mfma_f32_16x16x32_bf16 v[64:67], v[210:213], v[242:245], v[64:67]
	s_setprio 0
	s_barrier
	s_add_u32 s60, s42, 0x80
	s_addc_u32 s61, s43, 0
	s_add_u32 s62, s44, 0x80
	s_addc_u32 s63, s45, 0
	s_add_i32 s21, s22, s3
	s_mov_b32 m0, s21
	ds_read_b128 v[214:217], v155 offset:16384
	ds_read_b128 v[218:221], v155 offset:17408
	ds_read_b128 v[222:225], v155 offset:18432
	ds_read_b128 v[226:229], v155 offset:19456
	ds_read_b128 v[230:233], v155 offset:20480
	ds_read_b128 v[234:237], v155 offset:21504
	ds_read_b128 v[238:241], v155 offset:22528
	ds_read_b128 v[242:245], v155 offset:23552
	global_load_lds_dwordx4 v130, s[42:43]
	s_add_i32 m0, s21, 0x2000
	s_add_u32 s48, s42, 0x40000
	s_addc_u32 s49, s43, 0
	s_add_i32 s21, s23, s3
	global_load_lds_dwordx4 v142, s[42:43]
	s_mov_b32 m0, s21
	s_nop 0
	global_load_lds_dwordx4 v130, s[48:49]
	s_add_i32 m0, s21, 0x2000
	s_nop 0
	global_load_lds_dwordx4 v142, s[48:49]
	s_mov_b32 m0, s12
	s_nop 0
	global_load_lds_dwordx4 v146, s[44:45]
	s_mov_b32 m0, s13
	s_nop 0
	global_load_lds_dwordx4 v144, s[44:45]
	s_waitcnt vmcnt(8)
	s_waitcnt lgkmcnt(0)
	s_barrier
	s_setprio 1
	s_waitcnt lgkmcnt(0)
	v_mfma_f32_16x16x32_bf16 v[60:63], v[182:185], v[214:217], 0
	v_mfma_f32_16x16x32_bf16 v[56:59], v[190:193], v[214:217], 0
	v_mfma_f32_16x16x32_bf16 v[52:55], v[182:185], v[222:225], 0
	v_mfma_f32_16x16x32_bf16 v[48:51], v[190:193], v[222:225], 0
	v_mfma_f32_16x16x32_bf16 v[36:39], v[182:185], v[230:233], 0
	v_mfma_f32_16x16x32_bf16 v[32:35], v[190:193], v[230:233], 0
	v_mfma_f32_16x16x32_bf16 v[20:23], v[182:185], v[238:241], 0
	v_mfma_f32_16x16x32_bf16 v[16:19], v[190:193], v[238:241], 0
	v_mfma_f32_16x16x32_bf16 v[60:63], v[186:189], v[218:221], v[60:63]
	v_mfma_f32_16x16x32_bf16 v[56:59], v[194:197], v[218:221], v[56:59]
	v_mfma_f32_16x16x32_bf16 v[52:55], v[186:189], v[226:229], v[52:55]
	v_mfma_f32_16x16x32_bf16 v[48:51], v[194:197], v[226:229], v[48:51]
	v_mfma_f32_16x16x32_bf16 v[36:39], v[186:189], v[234:237], v[36:39]
	v_mfma_f32_16x16x32_bf16 v[32:35], v[194:197], v[234:237], v[32:35]
	v_mfma_f32_16x16x32_bf16 v[20:23], v[186:189], v[242:245], v[20:23]
	v_mfma_f32_16x16x32_bf16 v[16:19], v[194:197], v[242:245], v[16:19]
	s_setprio 0
	s_setprio 1
	v_mfma_f32_16x16x32_bf16 v[44:47], v[198:201], v[214:217], 0
	v_mfma_f32_16x16x32_bf16 v[40:43], v[206:209], v[214:217], 0
	v_mfma_f32_16x16x32_bf16 v[28:31], v[198:201], v[222:225], 0
	v_mfma_f32_16x16x32_bf16 v[24:27], v[206:209], v[222:225], 0
	v_mfma_f32_16x16x32_bf16 v[12:15], v[198:201], v[230:233], 0
	v_mfma_f32_16x16x32_bf16 v[8:11], v[206:209], v[230:233], 0
	v_mfma_f32_16x16x32_bf16 v[4:7], v[198:201], v[238:241], 0
	v_mfma_f32_16x16x32_bf16 v[0:3], v[206:209], v[238:241], 0
	v_mfma_f32_16x16x32_bf16 v[44:47], v[202:205], v[218:221], v[44:47]
	v_mfma_f32_16x16x32_bf16 v[40:43], v[210:213], v[218:221], v[40:43]
	v_mfma_f32_16x16x32_bf16 v[28:31], v[202:205], v[226:229], v[28:31]
	v_mfma_f32_16x16x32_bf16 v[24:27], v[210:213], v[226:229], v[24:27]
	v_mfma_f32_16x16x32_bf16 v[12:15], v[202:205], v[234:237], v[12:15]
	v_mfma_f32_16x16x32_bf16 v[8:11], v[210:213], v[234:237], v[8:11]
	v_mfma_f32_16x16x32_bf16 v[4:7], v[202:205], v[242:245], v[4:7]
	v_mfma_f32_16x16x32_bf16 v[0:3], v[210:213], v[242:245], v[0:3]
	s_setprio 0
	s_barrier
	v_add_u32_e32 v181, s34, v153
	ds_read_b128 v[182:185], v181
	ds_read_b128 v[186:189], v181 offset:1024
	ds_read_b128 v[190:193], v181 offset:2048
	ds_read_b128 v[194:197], v181 offset:3072
	v_add_u32_e32 v181, s35, v153
	ds_read_b128 v[198:201], v181
	ds_read_b128 v[202:205], v181 offset:1024
	ds_read_b128 v[206:209], v181 offset:2048
	ds_read_b128 v[210:213], v181 offset:3072
	s_add_u32 s44, s44, 0x40000
	s_addc_u32 s45, s45, 0
	s_mov_b32 m0, s20
	ds_read_b128 v[214:217], v155 offset:32768
	ds_read_b128 v[218:221], v155 offset:33792
	ds_read_b128 v[222:225], v155 offset:34816
	ds_read_b128 v[226:229], v155 offset:35840
	ds_read_b128 v[230:233], v155 offset:36864
	ds_read_b128 v[234:237], v155 offset:37888
	ds_read_b128 v[238:241], v155 offset:38912
	ds_read_b128 v[242:245], v155 offset:39936
	global_load_lds_dwordx4 v146, s[44:45]
	s_mov_b32 m0, s26
	s_nop 0
	global_load_lds_dwordx4 v144, s[44:45]
	s_waitcnt vmcnt(8)
	s_waitcnt lgkmcnt(0)
	s_barrier
	s_setprio 1
	s_waitcnt lgkmcnt(0)
	v_mfma_f32_16x16x32_bf16 v[124:127], v[182:185], v[214:217], v[124:127]
	v_mfma_f32_16x16x32_bf16 v[120:123], v[190:193], v[214:217], v[120:123]
	v_mfma_f32_16x16x32_bf16 v[116:119], v[182:185], v[222:225], v[116:119]
	v_mfma_f32_16x16x32_bf16 v[112:115], v[190:193], v[222:225], v[112:115]
	v_mfma_f32_16x16x32_bf16 v[100:103], v[182:185], v[230:233], v[100:103]
	v_mfma_f32_16x16x32_bf16 v[96:99], v[190:193], v[230:233], v[96:99]
	v_mfma_f32_16x16x32_bf16 v[84:87], v[182:185], v[238:241], v[84:87]
	v_mfma_f32_16x16x32_bf16 v[80:83], v[190:193], v[238:241], v[80:83]
	v_mfma_f32_16x16x32_bf16 v[124:127], v[186:189], v[218:221], v[124:127]
	v_mfma_f32_16x16x32_bf16 v[120:123], v[194:197], v[218:221], v[120:123]
	v_mfma_f32_16x16x32_bf16 v[116:119], v[186:189], v[226:229], v[116:119]
	v_mfma_f32_16x16x32_bf16 v[112:115], v[194:197], v[226:229], v[112:115]
	v_mfma_f32_16x16x32_bf16 v[100:103], v[186:189], v[234:237], v[100:103]
	v_mfma_f32_16x16x32_bf16 v[96:99], v[194:197], v[234:237], v[96:99]
	v_mfma_f32_16x16x32_bf16 v[84:87], v[186:189], v[242:245], v[84:87]
	v_mfma_f32_16x16x32_bf16 v[80:83], v[194:197], v[242:245], v[80:83]
	s_setprio 0
	s_setprio 1
	v_mfma_f32_16x16x32_bf16 v[108:111], v[198:201], v[214:217], v[108:111]
	v_mfma_f32_16x16x32_bf16 v[104:107], v[206:209], v[214:217], v[104:107]
	v_mfma_f32_16x16x32_bf16 v[92:95], v[198:201], v[222:225], v[92:95]
	v_mfma_f32_16x16x32_bf16 v[88:91], v[206:209], v[222:225], v[88:91]
	v_mfma_f32_16x16x32_bf16 v[76:79], v[198:201], v[230:233], v[76:79]
	v_mfma_f32_16x16x32_bf16 v[72:75], v[206:209], v[230:233], v[72:75]
	v_mfma_f32_16x16x32_bf16 v[68:71], v[198:201], v[238:241], v[68:71]
	v_mfma_f32_16x16x32_bf16 v[64:67], v[206:209], v[238:241], v[64:67]
	v_mfma_f32_16x16x32_bf16 v[108:111], v[202:205], v[218:221], v[108:111]
	v_mfma_f32_16x16x32_bf16 v[104:107], v[210:213], v[218:221], v[104:107]
	v_mfma_f32_16x16x32_bf16 v[92:95], v[202:205], v[226:229], v[92:95]
	v_mfma_f32_16x16x32_bf16 v[88:91], v[210:213], v[226:229], v[88:91]
	v_mfma_f32_16x16x32_bf16 v[76:79], v[202:205], v[234:237], v[76:79]
	v_mfma_f32_16x16x32_bf16 v[72:75], v[210:213], v[234:237], v[72:75]
	v_mfma_f32_16x16x32_bf16 v[68:71], v[202:205], v[242:245], v[68:71]
	v_mfma_f32_16x16x32_bf16 v[64:67], v[210:213], v[242:245], v[64:67]
	s_setprio 0
	s_barrier
	s_add_i32 s21, s34, s3
	s_mov_b32 m0, s21
	ds_read_b128 v[214:217], v155 offset:49152
	ds_read_b128 v[218:221], v155 offset:50176
	ds_read_b128 v[222:225], v155 offset:51200
	ds_read_b128 v[226:229], v155 offset:52224
	ds_read_b128 v[230:233], v155 offset:53248
	ds_read_b128 v[234:237], v155 offset:54272
	ds_read_b128 v[238:241], v155 offset:55296
	ds_read_b128 v[242:245], v155 offset:56320
	global_load_lds_dwordx4 v130, s[60:61]
	s_add_i32 m0, s21, 0x2000
	s_add_u32 s42, s42, 0x40080
	s_addc_u32 s43, s43, 0
	s_add_i32 s21, s35, s3
	global_load_lds_dwordx4 v142, s[60:61]
	s_mov_b32 m0, s21
	s_nop 0
	global_load_lds_dwordx4 v130, s[42:43]
	s_add_i32 m0, s21, 0x2000
	s_nop 0
	global_load_lds_dwordx4 v142, s[42:43]
	s_mov_b32 m0, s0
	s_nop 0
	global_load_lds_dwordx4 v146, s[62:63]
	s_mov_b32 m0, s1
	s_nop 0
	global_load_lds_dwordx4 v144, s[62:63]
	s_waitcnt vmcnt(8)
	s_waitcnt lgkmcnt(0)
	s_barrier
	s_setprio 1
	s_waitcnt lgkmcnt(0)
	v_mfma_f32_16x16x32_bf16 v[60:63], v[182:185], v[214:217], v[60:63]
	v_mfma_f32_16x16x32_bf16 v[56:59], v[190:193], v[214:217], v[56:59]
	v_mfma_f32_16x16x32_bf16 v[52:55], v[182:185], v[222:225], v[52:55]
	v_mfma_f32_16x16x32_bf16 v[48:51], v[190:193], v[222:225], v[48:51]
	v_mfma_f32_16x16x32_bf16 v[36:39], v[182:185], v[230:233], v[36:39]
	v_mfma_f32_16x16x32_bf16 v[32:35], v[190:193], v[230:233], v[32:35]
	v_mfma_f32_16x16x32_bf16 v[20:23], v[182:185], v[238:241], v[20:23]
	v_mfma_f32_16x16x32_bf16 v[16:19], v[190:193], v[238:241], v[16:19]
	v_mfma_f32_16x16x32_bf16 v[60:63], v[186:189], v[218:221], v[60:63]
	v_mfma_f32_16x16x32_bf16 v[56:59], v[194:197], v[218:221], v[56:59]
	v_mfma_f32_16x16x32_bf16 v[52:55], v[186:189], v[226:229], v[52:55]
	v_mfma_f32_16x16x32_bf16 v[48:51], v[194:197], v[226:229], v[48:51]
	v_mfma_f32_16x16x32_bf16 v[36:39], v[186:189], v[234:237], v[36:39]
	v_mfma_f32_16x16x32_bf16 v[32:35], v[194:197], v[234:237], v[32:35]
	v_mfma_f32_16x16x32_bf16 v[20:23], v[186:189], v[242:245], v[20:23]
	v_mfma_f32_16x16x32_bf16 v[16:19], v[194:197], v[242:245], v[16:19]
	s_setprio 0
	s_setprio 1
	v_mfma_f32_16x16x32_bf16 v[44:47], v[198:201], v[214:217], v[44:47]
	v_mfma_f32_16x16x32_bf16 v[40:43], v[206:209], v[214:217], v[40:43]
	v_mfma_f32_16x16x32_bf16 v[28:31], v[198:201], v[222:225], v[28:31]
	v_mfma_f32_16x16x32_bf16 v[24:27], v[206:209], v[222:225], v[24:27]
	v_mfma_f32_16x16x32_bf16 v[12:15], v[198:201], v[230:233], v[12:15]
	v_mfma_f32_16x16x32_bf16 v[8:11], v[206:209], v[230:233], v[8:11]
	v_mfma_f32_16x16x32_bf16 v[4:7], v[198:201], v[238:241], v[4:7]
	v_mfma_f32_16x16x32_bf16 v[0:3], v[206:209], v[238:241], v[0:3]
	v_mfma_f32_16x16x32_bf16 v[44:47], v[202:205], v[218:221], v[44:47]
	v_mfma_f32_16x16x32_bf16 v[40:43], v[210:213], v[218:221], v[40:43]
	v_mfma_f32_16x16x32_bf16 v[28:31], v[202:205], v[226:229], v[28:31]
	v_mfma_f32_16x16x32_bf16 v[24:27], v[210:213], v[226:229], v[24:27]
	v_mfma_f32_16x16x32_bf16 v[12:15], v[202:205], v[234:237], v[12:15]
	v_mfma_f32_16x16x32_bf16 v[8:11], v[210:213], v[234:237], v[8:11]
	v_mfma_f32_16x16x32_bf16 v[4:7], v[202:205], v[242:245], v[4:7]
	v_mfma_f32_16x16x32_bf16 v[0:3], v[210:213], v[242:245], v[0:3]
	s_setprio 0
	s_barrier
	s_add_i32 s46, s46, 2
	s_add_u32 s40, s40, 0x100
	s_addc_u32 s41, s41, 0
	s_add_u32 s38, s38, 0x100
	s_addc_u32 s39, s39, 0
	s_cmp_gt_u32 s46, 13
	s_cbranch_scc1 .Lpeel_done_511
.LBB0_511:
	v_add_u32_e32 v156, s22, v153
	ds_read_b128 v[182:185], v156
	ds_read_b128 v[186:189], v156 offset:1024
	ds_read_b128 v[190:193], v156 offset:2048
	ds_read_b128 v[194:197], v156 offset:3072
	v_add_u32_e32 v156, s23, v153
	ds_read_b128 v[198:201], v156
	ds_read_b128 v[202:205], v156 offset:1024
	ds_read_b128 v[206:209], v156 offset:2048
	ds_read_b128 v[210:213], v156 offset:3072
	s_add_u32 s21, s40, 0xfffc0080
	s_addc_u32 s24, s41, -1
	s_cmp_eq_u32 s46, 12
	s_cselect_b32 s45, s17, s24
	s_cselect_b32 s44, s18, s21
	s_cselect_b32 s43, s11, s39
	s_cselect_b32 s42, s19, s38
	s_add_i32 m0, s12, 0xc000
	ds_read_b128 v[214:217], v155
	ds_read_b128 v[218:221], v155 offset:1024
	ds_read_b128 v[222:225], v155 offset:2048
	ds_read_b128 v[226:229], v155 offset:3072
	ds_read_b128 v[230:233], v155 offset:4096
	ds_read_b128 v[234:237], v155 offset:5120
	ds_read_b128 v[238:241], v155 offset:6144
	ds_read_b128 v[242:245], v155 offset:7168
	global_load_lds_dwordx4 v148, s[40:41]
	s_add_i32 m0, s12, 0xe000
	s_nop 0
	global_load_lds_dwordx4 v150, s[40:41]
	s_waitcnt vmcnt(8)
	s_waitcnt lgkmcnt(0)
	s_barrier
	s_setprio 1
	s_waitcnt lgkmcnt(0)
	v_mfma_f32_16x16x32_bf16 v[124:127], v[182:185], v[214:217], v[124:127]
	v_mfma_f32_16x16x32_bf16 v[120:123], v[190:193], v[214:217], v[120:123]
	v_mfma_f32_16x16x32_bf16 v[116:119], v[182:185], v[222:225], v[116:119]
	v_mfma_f32_16x16x32_bf16 v[112:115], v[190:193], v[222:225], v[112:115]
	v_mfma_f32_16x16x32_bf16 v[100:103], v[182:185], v[230:233], v[100:103]
	v_mfma_f32_16x16x32_bf16 v[96:99], v[190:193], v[230:233], v[96:99]
	v_mfma_f32_16x16x32_bf16 v[84:87], v[182:185], v[238:241], v[84:87]
	v_mfma_f32_16x16x32_bf16 v[80:83], v[190:193], v[238:241], v[80:83]
	v_mfma_f32_16x16x32_bf16 v[124:127], v[186:189], v[218:221], v[124:127]
	v_mfma_f32_16x16x32_bf16 v[120:123], v[194:197], v[218:221], v[120:123]
	v_mfma_f32_16x16x32_bf16 v[116:119], v[186:189], v[226:229], v[116:119]
	v_mfma_f32_16x16x32_bf16 v[112:115], v[194:197], v[226:229], v[112:115]
	v_mfma_f32_16x16x32_bf16 v[100:103], v[186:189], v[234:237], v[100:103]
	v_mfma_f32_16x16x32_bf16 v[96:99], v[194:197], v[234:237], v[96:99]
	v_mfma_f32_16x16x32_bf16 v[84:87], v[186:189], v[242:245], v[84:87]
	v_mfma_f32_16x16x32_bf16 v[80:83], v[194:197], v[242:245], v[80:83]
	s_setprio 0
	s_setprio 1
	v_mfma_f32_16x16x32_bf16 v[108:111], v[198:201], v[214:217], v[108:111]
	v_mfma_f32_16x16x32_bf16 v[104:107], v[206:209], v[214:217], v[104:107]
	v_mfma_f32_16x16x32_bf16 v[92:95], v[198:201], v[222:225], v[92:95]
	v_mfma_f32_16x16x32_bf16 v[88:91], v[206:209], v[222:225], v[88:91]
	v_mfma_f32_16x16x32_bf16 v[76:79], v[198:201], v[230:233], v[76:79]
	v_mfma_f32_16x16x32_bf16 v[72:75], v[206:209], v[230:233], v[72:75]
	v_mfma_f32_16x16x32_bf16 v[68:71], v[198:201], v[238:241], v[68:71]
	v_mfma_f32_16x16x32_bf16 v[64:67], v[206:209], v[238:241], v[64:67]
	v_mfma_f32_16x16x32_bf16 v[108:111], v[202:205], v[218:221], v[108:111]
	v_mfma_f32_16x16x32_bf16 v[104:107], v[210:213], v[218:221], v[104:107]
	v_mfma_f32_16x16x32_bf16 v[92:95], v[202:205], v[226:229], v[92:95]
	v_mfma_f32_16x16x32_bf16 v[88:91], v[210:213], v[226:229], v[88:91]
	v_mfma_f32_16x16x32_bf16 v[76:79], v[202:205], v[234:237], v[76:79]
	v_mfma_f32_16x16x32_bf16 v[72:75], v[210:213], v[234:237], v[72:75]
	v_mfma_f32_16x16x32_bf16 v[68:71], v[202:205], v[242:245], v[68:71]
	v_mfma_f32_16x16x32_bf16 v[64:67], v[210:213], v[242:245], v[64:67]
	s_setprio 0
	s_barrier
	s_add_u32 s60, s42, 0x80
	s_addc_u32 s61, s43, 0
	s_add_u32 s62, s44, 0x80
	s_addc_u32 s63, s45, 0
	s_add_i32 s21, s22, s3
	s_mov_b32 m0, s21
	ds_read_b128 v[214:217], v155 offset:16384
	ds_read_b128 v[218:221], v155 offset:17408
	ds_read_b128 v[222:225], v155 offset:18432
	ds_read_b128 v[226:229], v155 offset:19456
	ds_read_b128 v[230:233], v155 offset:20480
	ds_read_b128 v[234:237], v155 offset:21504
	ds_read_b128 v[238:241], v155 offset:22528
	ds_read_b128 v[242:245], v155 offset:23552
	global_load_lds_dwordx4 v130, s[42:43]
	s_add_i32 m0, s21, 0x2000
	s_add_u32 s48, s42, 0x40000
	s_addc_u32 s49, s43, 0
	s_add_i32 s21, s23, s3
	global_load_lds_dwordx4 v142, s[42:43]
	s_mov_b32 m0, s21
	s_nop 0
	global_load_lds_dwordx4 v130, s[48:49]
	s_add_i32 m0, s21, 0x2000
	s_nop 0
	global_load_lds_dwordx4 v142, s[48:49]
	s_mov_b32 m0, s12
	s_nop 0
	global_load_lds_dwordx4 v146, s[44:45]
	s_mov_b32 m0, s13
	s_nop 0
	global_load_lds_dwordx4 v144, s[44:45]
	s_waitcnt vmcnt(8)
	s_waitcnt lgkmcnt(0)
	s_barrier
	s_setprio 1
	s_waitcnt lgkmcnt(0)
	v_mfma_f32_16x16x32_bf16 v[60:63], v[182:185], v[214:217], v[60:63]
	v_mfma_f32_16x16x32_bf16 v[56:59], v[190:193], v[214:217], v[56:59]
	v_mfma_f32_16x16x32_bf16 v[52:55], v[182:185], v[222:225], v[52:55]
	v_mfma_f32_16x16x32_bf16 v[48:51], v[190:193], v[222:225], v[48:51]
	v_mfma_f32_16x16x32_bf16 v[36:39], v[182:185], v[230:233], v[36:39]
	v_mfma_f32_16x16x32_bf16 v[32:35], v[190:193], v[230:233], v[32:35]
	v_mfma_f32_16x16x32_bf16 v[20:23], v[182:185], v[238:241], v[20:23]
	v_mfma_f32_16x16x32_bf16 v[16:19], v[190:193], v[238:241], v[16:19]
	v_mfma_f32_16x16x32_bf16 v[60:63], v[186:189], v[218:221], v[60:63]
	v_mfma_f32_16x16x32_bf16 v[56:59], v[194:197], v[218:221], v[56:59]
	v_mfma_f32_16x16x32_bf16 v[52:55], v[186:189], v[226:229], v[52:55]
	v_mfma_f32_16x16x32_bf16 v[48:51], v[194:197], v[226:229], v[48:51]
	v_mfma_f32_16x16x32_bf16 v[36:39], v[186:189], v[234:237], v[36:39]
	v_mfma_f32_16x16x32_bf16 v[32:35], v[194:197], v[234:237], v[32:35]
	v_mfma_f32_16x16x32_bf16 v[20:23], v[186:189], v[242:245], v[20:23]
	v_mfma_f32_16x16x32_bf16 v[16:19], v[194:197], v[242:245], v[16:19]
	s_setprio 0
	s_setprio 1
	v_mfma_f32_16x16x32_bf16 v[44:47], v[198:201], v[214:217], v[44:47]
	v_mfma_f32_16x16x32_bf16 v[40:43], v[206:209], v[214:217], v[40:43]
	v_mfma_f32_16x16x32_bf16 v[28:31], v[198:201], v[222:225], v[28:31]
	v_mfma_f32_16x16x32_bf16 v[24:27], v[206:209], v[222:225], v[24:27]
	v_mfma_f32_16x16x32_bf16 v[12:15], v[198:201], v[230:233], v[12:15]
	v_mfma_f32_16x16x32_bf16 v[8:11], v[206:209], v[230:233], v[8:11]
	v_mfma_f32_16x16x32_bf16 v[4:7], v[198:201], v[238:241], v[4:7]
	v_mfma_f32_16x16x32_bf16 v[0:3], v[206:209], v[238:241], v[0:3]
	v_mfma_f32_16x16x32_bf16 v[44:47], v[202:205], v[218:221], v[44:47]
	v_mfma_f32_16x16x32_bf16 v[40:43], v[210:213], v[218:221], v[40:43]
	v_mfma_f32_16x16x32_bf16 v[28:31], v[202:205], v[226:229], v[28:31]
	v_mfma_f32_16x16x32_bf16 v[24:27], v[210:213], v[226:229], v[24:27]
	v_mfma_f32_16x16x32_bf16 v[12:15], v[202:205], v[234:237], v[12:15]
	v_mfma_f32_16x16x32_bf16 v[8:11], v[210:213], v[234:237], v[8:11]
	v_mfma_f32_16x16x32_bf16 v[4:7], v[202:205], v[242:245], v[4:7]
	v_mfma_f32_16x16x32_bf16 v[0:3], v[210:213], v[242:245], v[0:3]
	s_setprio 0
	s_barrier
	v_add_u32_e32 v181, s34, v153
	ds_read_b128 v[182:185], v181
	ds_read_b128 v[186:189], v181 offset:1024
	ds_read_b128 v[190:193], v181 offset:2048
	ds_read_b128 v[194:197], v181 offset:3072
	v_add_u32_e32 v181, s35, v153
	ds_read_b128 v[198:201], v181
	ds_read_b128 v[202:205], v181 offset:1024
	ds_read_b128 v[206:209], v181 offset:2048
	ds_read_b128 v[210:213], v181 offset:3072
	s_add_u32 s44, s44, 0x40000
	s_addc_u32 s45, s45, 0
	s_mov_b32 m0, s20
	ds_read_b128 v[214:217], v155 offset:32768
	ds_read_b128 v[218:221], v155 offset:33792
	ds_read_b128 v[222:225], v155 offset:34816
	ds_read_b128 v[226:229], v155 offset:35840
	ds_read_b128 v[230:233], v155 offset:36864
	ds_read_b128 v[234:237], v155 offset:37888
	ds_read_b128 v[238:241], v155 offset:38912
	ds_read_b128 v[242:245], v155 offset:39936
	global_load_lds_dwordx4 v146, s[44:45]
	s_mov_b32 m0, s26
	s_nop 0
	global_load_lds_dwordx4 v144, s[44:45]
	s_waitcnt vmcnt(8)
	s_waitcnt lgkmcnt(0)
	s_barrier
	s_setprio 1
	s_waitcnt lgkmcnt(0)
	v_mfma_f32_16x16x32_bf16 v[124:127], v[182:185], v[214:217], v[124:127]
	v_mfma_f32_16x16x32_bf16 v[120:123], v[190:193], v[214:217], v[120:123]
	v_mfma_f32_16x16x32_bf16 v[116:119], v[182:185], v[222:225], v[116:119]
	v_mfma_f32_16x16x32_bf16 v[112:115], v[190:193], v[222:225], v[112:115]
	v_mfma_f32_16x16x32_bf16 v[100:103], v[182:185], v[230:233], v[100:103]
	v_mfma_f32_16x16x32_bf16 v[96:99], v[190:193], v[230:233], v[96:99]
	v_mfma_f32_16x16x32_bf16 v[84:87], v[182:185], v[238:241], v[84:87]
	v_mfma_f32_16x16x32_bf16 v[80:83], v[190:193], v[238:241], v[80:83]
	v_mfma_f32_16x16x32_bf16 v[124:127], v[186:189], v[218:221], v[124:127]
	v_mfma_f32_16x16x32_bf16 v[120:123], v[194:197], v[218:221], v[120:123]
	v_mfma_f32_16x16x32_bf16 v[116:119], v[186:189], v[226:229], v[116:119]
	v_mfma_f32_16x16x32_bf16 v[112:115], v[194:197], v[226:229], v[112:115]
	v_mfma_f32_16x16x32_bf16 v[100:103], v[186:189], v[234:237], v[100:103]
	v_mfma_f32_16x16x32_bf16 v[96:99], v[194:197], v[234:237], v[96:99]
	v_mfma_f32_16x16x32_bf16 v[84:87], v[186:189], v[242:245], v[84:87]
	v_mfma_f32_16x16x32_bf16 v[80:83], v[194:197], v[242:245], v[80:83]
	s_setprio 0
	s_setprio 1
	v_mfma_f32_16x16x32_bf16 v[108:111], v[198:201], v[214:217], v[108:111]
	v_mfma_f32_16x16x32_bf16 v[104:107], v[206:209], v[214:217], v[104:107]
	v_mfma_f32_16x16x32_bf16 v[92:95], v[198:201], v[222:225], v[92:95]
	v_mfma_f32_16x16x32_bf16 v[88:91], v[206:209], v[222:225], v[88:91]
	v_mfma_f32_16x16x32_bf16 v[76:79], v[198:201], v[230:233], v[76:79]
	v_mfma_f32_16x16x32_bf16 v[72:75], v[206:209], v[230:233], v[72:75]
	v_mfma_f32_16x16x32_bf16 v[68:71], v[198:201], v[238:241], v[68:71]
	v_mfma_f32_16x16x32_bf16 v[64:67], v[206:209], v[238:241], v[64:67]
	v_mfma_f32_16x16x32_bf16 v[108:111], v[202:205], v[218:221], v[108:111]
	v_mfma_f32_16x16x32_bf16 v[104:107], v[210:213], v[218:221], v[104:107]
	v_mfma_f32_16x16x32_bf16 v[92:95], v[202:205], v[226:229], v[92:95]
	v_mfma_f32_16x16x32_bf16 v[88:91], v[210:213], v[226:229], v[88:91]
	v_mfma_f32_16x16x32_bf16 v[76:79], v[202:205], v[234:237], v[76:79]
	v_mfma_f32_16x16x32_bf16 v[72:75], v[210:213], v[234:237], v[72:75]
	v_mfma_f32_16x16x32_bf16 v[68:71], v[202:205], v[242:245], v[68:71]
	v_mfma_f32_16x16x32_bf16 v[64:67], v[210:213], v[242:245], v[64:67]
	s_setprio 0
	s_barrier
	s_add_i32 s21, s34, s3
	s_mov_b32 m0, s21
	ds_read_b128 v[214:217], v155 offset:49152
	ds_read_b128 v[218:221], v155 offset:50176
	ds_read_b128 v[222:225], v155 offset:51200
	ds_read_b128 v[226:229], v155 offset:52224
	ds_read_b128 v[230:233], v155 offset:53248
	ds_read_b128 v[234:237], v155 offset:54272
	ds_read_b128 v[238:241], v155 offset:55296
	ds_read_b128 v[242:245], v155 offset:56320
	global_load_lds_dwordx4 v130, s[60:61]
	s_add_i32 m0, s21, 0x2000
	s_add_u32 s42, s42, 0x40080
	s_addc_u32 s43, s43, 0
	s_add_i32 s21, s35, s3
	global_load_lds_dwordx4 v142, s[60:61]
	s_mov_b32 m0, s21
	s_nop 0
	global_load_lds_dwordx4 v130, s[42:43]
	s_add_i32 m0, s21, 0x2000
	s_nop 0
	global_load_lds_dwordx4 v142, s[42:43]
	s_mov_b32 m0, s0
	s_nop 0
	global_load_lds_dwordx4 v146, s[62:63]
	s_mov_b32 m0, s1
	s_nop 0
	global_load_lds_dwordx4 v144, s[62:63]
	s_waitcnt vmcnt(8)
	s_waitcnt lgkmcnt(0)
	s_barrier
	s_setprio 1
	s_waitcnt lgkmcnt(0)
	v_mfma_f32_16x16x32_bf16 v[60:63], v[182:185], v[214:217], v[60:63]
	v_mfma_f32_16x16x32_bf16 v[56:59], v[190:193], v[214:217], v[56:59]
	v_mfma_f32_16x16x32_bf16 v[52:55], v[182:185], v[222:225], v[52:55]
	v_mfma_f32_16x16x32_bf16 v[48:51], v[190:193], v[222:225], v[48:51]
	v_mfma_f32_16x16x32_bf16 v[36:39], v[182:185], v[230:233], v[36:39]
	v_mfma_f32_16x16x32_bf16 v[32:35], v[190:193], v[230:233], v[32:35]
	v_mfma_f32_16x16x32_bf16 v[20:23], v[182:185], v[238:241], v[20:23]
	v_mfma_f32_16x16x32_bf16 v[16:19], v[190:193], v[238:241], v[16:19]
	v_mfma_f32_16x16x32_bf16 v[60:63], v[186:189], v[218:221], v[60:63]
	v_mfma_f32_16x16x32_bf16 v[56:59], v[194:197], v[218:221], v[56:59]
	v_mfma_f32_16x16x32_bf16 v[52:55], v[186:189], v[226:229], v[52:55]
	v_mfma_f32_16x16x32_bf16 v[48:51], v[194:197], v[226:229], v[48:51]
	v_mfma_f32_16x16x32_bf16 v[36:39], v[186:189], v[234:237], v[36:39]
	v_mfma_f32_16x16x32_bf16 v[32:35], v[194:197], v[234:237], v[32:35]
	v_mfma_f32_16x16x32_bf16 v[20:23], v[186:189], v[242:245], v[20:23]
	v_mfma_f32_16x16x32_bf16 v[16:19], v[194:197], v[242:245], v[16:19]
	s_setprio 0
	s_setprio 1
	v_mfma_f32_16x16x32_bf16 v[44:47], v[198:201], v[214:217], v[44:47]
	v_mfma_f32_16x16x32_bf16 v[40:43], v[206:209], v[214:217], v[40:43]
	v_mfma_f32_16x16x32_bf16 v[28:31], v[198:201], v[222:225], v[28:31]
	v_mfma_f32_16x16x32_bf16 v[24:27], v[206:209], v[222:225], v[24:27]
	v_mfma_f32_16x16x32_bf16 v[12:15], v[198:201], v[230:233], v[12:15]
	v_mfma_f32_16x16x32_bf16 v[8:11], v[206:209], v[230:233], v[8:11]
	v_mfma_f32_16x16x32_bf16 v[4:7], v[198:201], v[238:241], v[4:7]
	v_mfma_f32_16x16x32_bf16 v[0:3], v[206:209], v[238:241], v[0:3]
	v_mfma_f32_16x16x32_bf16 v[44:47], v[202:205], v[218:221], v[44:47]
	v_mfma_f32_16x16x32_bf16 v[40:43], v[210:213], v[218:221], v[40:43]
	v_mfma_f32_16x16x32_bf16 v[28:31], v[202:205], v[226:229], v[28:31]
	v_mfma_f32_16x16x32_bf16 v[24:27], v[210:213], v[226:229], v[24:27]
	v_mfma_f32_16x16x32_bf16 v[12:15], v[202:205], v[234:237], v[12:15]
	v_mfma_f32_16x16x32_bf16 v[8:11], v[210:213], v[234:237], v[8:11]
	v_mfma_f32_16x16x32_bf16 v[4:7], v[202:205], v[242:245], v[4:7]
	v_mfma_f32_16x16x32_bf16 v[0:3], v[210:213], v[242:245], v[0:3]
	s_setprio 0
	s_barrier
	s_add_i32 s46, s46, 2
	s_add_u32 s40, s40, 0x100
	s_addc_u32 s41, s41, 0
	s_add_u32 s38, s38, 0x100
	s_addc_u32 s39, s39, 0
	s_cmp_gt_u32 s46, 13
	s_cbranch_scc0 .LBB0_511

.LBB0_726:
	s_mul_i32 s24, s15, 0x4800
	s_add_i32 s26, s24, 0
	v_add_u32_e32 v103, s26, v99
	ds_read_b128 v[32:35], v103
	ds_read_b128 v[104:107], v103 offset:32
	v_add_u32_e32 v108, s26, v100
	s_andn2_b64 vcc, exec, s[18:19]
	s_waitcnt lgkmcnt(1)
	v_mfma_f32_32x32x16_bf16 v[48:63], v[32:35], v[64:67], 0
	ds_read_b128 v[32:35], v108
	s_waitcnt lgkmcnt(1)
	v_mfma_f32_32x32x16_bf16 v[48:63], v[104:107], v[68:71], v[48:63]
	ds_read_b128 v[104:107], v108 offset:32
	s_waitcnt lgkmcnt(1)
	v_mfma_f32_32x32x16_bf16 v[32:47], v[32:35], v[64:67], 0
	s_waitcnt lgkmcnt(0)
	v_mfma_f32_32x32x16_bf16 v[32:47], v[104:107], v[68:71], v[32:47]
	ds_read_b128 v[104:107], v103 offset:64
	s_waitcnt lgkmcnt(0)
	v_mfma_f32_32x32x16_bf16 v[48:63], v[104:107], v[72:75], v[48:63]
	ds_read_b128 v[104:107], v108 offset:64
	s_waitcnt lgkmcnt(0)
	v_mfma_f32_32x32x16_bf16 v[32:47], v[104:107], v[72:75], v[32:47]
	ds_read_b128 v[104:107], v103 offset:96
	s_waitcnt lgkmcnt(0)
	v_mfma_f32_32x32x16_bf16 v[48:63], v[104:107], v[76:79], v[48:63]
	ds_read_b128 v[104:107], v108 offset:96
	s_waitcnt lgkmcnt(0)
	v_mfma_f32_32x32x16_bf16 v[32:47], v[104:107], v[76:79], v[32:47]
	s_cbranch_vccnz .LBB0_792
	v_lshl_add_u32 v104, s0, 2, v101
	v_lshl_add_u32 v105, v97, 2, v104
	ds_read_b32 v104, v105 offset:41020
	ds_read_b32 v103, v105 offset:41148
	ds_read_b32 v107, v105 offset:41024
	ds_read_b32 v106, v105 offset:41152
	ds_read_b32 v109, v105 offset:41028
	ds_read_b32 v108, v105 offset:41156
	ds_read_b32 v111, v105 offset:41032
	ds_read_b32 v110, v105 offset:41160
	ds_read_b32 v113, v105 offset:41052
	ds_read_b32 v112, v105 offset:41180
	ds_read_b32 v115, v105 offset:41056
	ds_read_b32 v114, v105 offset:41184
	ds_read_b32 v117, v105 offset:41060
	ds_read_b32 v116, v105 offset:41188
	ds_read_b32 v119, v105 offset:41064
	ds_read_b32 v118, v105 offset:41192
	ds_read_b32 v121, v105 offset:41084
	ds_read_b32 v120, v105 offset:41212
	ds_read_b32 v123, v105 offset:41088
	ds_read_b32 v122, v105 offset:41216
	ds_read_b32 v125, v105 offset:41092
	ds_read_b32 v124, v105 offset:41220
	ds_read_b32 v127, v105 offset:41096
	ds_read_b32 v126, v105 offset:41224
	ds_read_b32 v143, v105 offset:41116
	ds_read_b32 v142, v105 offset:41244
	ds_read_b32 v145, v105 offset:41120
	ds_read_b32 v144, v105 offset:41248
	ds_read_b32 v147, v105 offset:41124
	ds_read_b32 v146, v105 offset:41252
	ds_read_b32 v149, v105 offset:41128
	ds_read_b32 v148, v105 offset:41256
	s_waitcnt lgkmcnt(0)
	v_add_f32_e32 v48, v48, v104
	v_add_f32_e32 v32, v32, v103
	v_add_f32_e32 v49, v49, v107
	v_add_f32_e32 v33, v33, v106
	v_add_f32_e32 v50, v50, v109
	v_add_f32_e32 v34, v34, v108
	v_add_f32_e32 v51, v51, v111
	v_add_f32_e32 v35, v35, v110
	v_add_f32_e32 v52, v52, v113
	v_add_f32_e32 v36, v36, v112
	v_add_f32_e32 v53, v53, v115
	v_add_f32_e32 v37, v37, v114
	v_add_f32_e32 v54, v54, v117
	v_add_f32_e32 v38, v38, v116
	v_add_f32_e32 v55, v55, v119
	v_add_f32_e32 v39, v39, v118
	v_add_f32_e32 v56, v56, v121
	v_add_f32_e32 v40, v40, v120
	v_add_f32_e32 v57, v57, v123
	v_add_f32_e32 v41, v41, v122
	v_add_f32_e32 v58, v58, v125
	v_add_f32_e32 v42, v42, v124
	v_add_f32_e32 v59, v59, v127
	v_add_f32_e32 v43, v43, v126
	v_add_f32_e32 v60, v60, v143
	v_add_f32_e32 v44, v44, v142
	v_add_f32_e32 v61, v61, v145
	v_add_f32_e32 v45, v45, v144
	v_add_f32_e32 v62, v62, v147
	v_add_f32_e32 v46, v46, v146
	v_add_f32_e32 v63, v63, v149
	v_add_f32_e32 v47, v47, v148
	v_cndmask_b32_e64 v48, v169, v48, s[42:43]
	v_cndmask_b32_e64 v32, v169, v32, s[44:45]
	v_cndmask_b32_e64 v49, v169, v49, s[46:47]
	v_cndmask_b32_e64 v33, v169, v33, s[48:49]
	v_cndmask_b32_e64 v50, v169, v50, s[50:51]
	v_cndmask_b32_e64 v34, v169, v34, s[52:53]
	v_cndmask_b32_e64 v51, v169, v51, s[54:55]
	v_cndmask_b32_e64 v35, v169, v35, s[56:57]
	v_cndmask_b32_e64 v52, v169, v52, s[58:59]
	v_cndmask_b32_e64 v36, v169, v36, s[60:61]
	v_cndmask_b32_e64 v53, v169, v53, s[62:63]
	v_cndmask_b32_e64 v37, v169, v37, s[64:65]
	v_cndmask_b32_e64 v54, v169, v54, s[66:67]
	v_cndmask_b32_e64 v38, v169, v38, s[68:69]
	v_cndmask_b32_e64 v55, v169, v55, s[70:71]
	v_cndmask_b32_e64 v39, v169, v39, s[72:73]
	v_cndmask_b32_e64 v56, v169, v56, s[74:75]
	v_cndmask_b32_e64 v40, v169, v40, s[76:77]
	v_cndmask_b32_e64 v57, v169, v57, s[78:79]
	v_cndmask_b32_e64 v41, v169, v41, s[80:81]
	v_cndmask_b32_e64 v58, v169, v58, s[82:83]
	v_cndmask_b32_e64 v42, v169, v42, s[84:85]
	v_cndmask_b32_e64 v59, v169, v59, s[86:87]
	v_cndmask_b32_e64 v43, v169, v43, s[88:89]
	v_cndmask_b32_e64 v60, v169, v60, s[90:91]
	v_cndmask_b32_e64 v44, v169, v44, s[92:93]
	v_cndmask_b32_e64 v61, v169, v61, s[94:95]
	v_cndmask_b32_e64 v45, v169, v45, s[96:97]
	v_cndmask_b32_e64 v62, v169, v62, s[4:5]
	v_cndmask_b32_e64 v46, v169, v46, s[6:7]
	v_cndmask_b32_e64 v63, v169, v63, s[8:9]
	v_cndmask_b32_e64 v47, v169, v47, s[10:11]

.LBB0_854:
	s_add_i32 s11, s48, -2
	s_add_u32 s29, s42, 0x100
	s_addc_u32 s49, s43, 0
	s_mov_b32 s44, 0
	v_add_u32_e32 v156, s22, v153
	ds_read_b128 v[182:185], v156
	ds_read_b128 v[186:189], v156 offset:1024
	ds_read_b128 v[190:193], v156 offset:2048
	ds_read_b128 v[194:197], v156 offset:3072
	v_add_u32_e32 v156, s23, v153
	ds_read_b128 v[198:201], v156
	ds_read_b128 v[202:205], v156 offset:1024
	ds_read_b128 v[206:209], v156 offset:2048
	ds_read_b128 v[210:213], v156 offset:3072
	s_add_i32 s50, s44, 2
	s_add_u32 s42, s40, 0x100
	s_addc_u32 s43, s41, 0
	s_cmp_eq_u32 s11, s44
	s_cselect_b32 s44, s36, s29
	s_cselect_b32 s47, s17, s43
	s_cselect_b32 s46, s16, s42
	s_cselect_b32 s45, s37, s49
	s_add_i32 m0, s12, 0xc000
	ds_read_b128 v[214:217], v155
	ds_read_b128 v[218:221], v155 offset:1024
	ds_read_b128 v[222:225], v155 offset:2048
	ds_read_b128 v[226:229], v155 offset:3072
	ds_read_b128 v[230:233], v155 offset:4096
	ds_read_b128 v[234:237], v155 offset:5120
	ds_read_b128 v[238:241], v155 offset:6144
	ds_read_b128 v[242:245], v155 offset:7168
	global_load_lds_dwordx4 v148, s[40:41]
	s_add_i32 m0, s12, 0xe000
	s_nop 0
	global_load_lds_dwordx4 v150, s[40:41]
	s_waitcnt vmcnt(8)
	s_waitcnt lgkmcnt(0)
	s_barrier
	s_setprio 1
	s_waitcnt lgkmcnt(0)
	v_mfma_f32_16x16x32_bf16 v[124:127], v[182:185], v[214:217], 0
	v_mfma_f32_16x16x32_bf16 v[120:123], v[190:193], v[214:217], 0
	v_mfma_f32_16x16x32_bf16 v[116:119], v[182:185], v[222:225], 0
	v_mfma_f32_16x16x32_bf16 v[112:115], v[190:193], v[222:225], 0
	v_mfma_f32_16x16x32_bf16 v[100:103], v[182:185], v[230:233], 0
	v_mfma_f32_16x16x32_bf16 v[96:99], v[190:193], v[230:233], 0
	v_mfma_f32_16x16x32_bf16 v[84:87], v[182:185], v[238:241], 0
	v_mfma_f32_16x16x32_bf16 v[80:83], v[190:193], v[238:241], 0
	v_mfma_f32_16x16x32_bf16 v[124:127], v[186:189], v[218:221], v[124:127]
	v_mfma_f32_16x16x32_bf16 v[120:123], v[194:197], v[218:221], v[120:123]
	v_mfma_f32_16x16x32_bf16 v[116:119], v[186:189], v[226:229], v[116:119]
	v_mfma_f32_16x16x32_bf16 v[112:115], v[194:197], v[226:229], v[112:115]
	v_mfma_f32_16x16x32_bf16 v[100:103], v[186:189], v[234:237], v[100:103]
	v_mfma_f32_16x16x32_bf16 v[96:99], v[194:197], v[234:237], v[96:99]
	v_mfma_f32_16x16x32_bf16 v[84:87], v[186:189], v[242:245], v[84:87]
	v_mfma_f32_16x16x32_bf16 v[80:83], v[194:197], v[242:245], v[80:83]
	s_setprio 0
	s_setprio 1
	v_mfma_f32_16x16x32_bf16 v[108:111], v[198:201], v[214:217], 0
	v_mfma_f32_16x16x32_bf16 v[104:107], v[206:209], v[214:217], 0
	v_mfma_f32_16x16x32_bf16 v[92:95], v[198:201], v[222:225], 0
	v_mfma_f32_16x16x32_bf16 v[88:91], v[206:209], v[222:225], 0
	v_mfma_f32_16x16x32_bf16 v[76:79], v[198:201], v[230:233], 0
	v_mfma_f32_16x16x32_bf16 v[72:75], v[206:209], v[230:233], 0
	v_mfma_f32_16x16x32_bf16 v[68:71], v[198:201], v[238:241], 0
	v_mfma_f32_16x16x32_bf16 v[64:67], v[206:209], v[238:241], 0
	v_mfma_f32_16x16x32_bf16 v[108:111], v[202:205], v[218:221], v[108:111]
	v_mfma_f32_16x16x32_bf16 v[104:107], v[210:213], v[218:221], v[104:107]
	v_mfma_f32_16x16x32_bf16 v[92:95], v[202:205], v[226:229], v[92:95]
	v_mfma_f32_16x16x32_bf16 v[88:91], v[210:213], v[226:229], v[88:91]
	v_mfma_f32_16x16x32_bf16 v[76:79], v[202:205], v[234:237], v[76:79]
	v_mfma_f32_16x16x32_bf16 v[72:75], v[210:213], v[234:237], v[72:75]
	v_mfma_f32_16x16x32_bf16 v[68:71], v[202:205], v[242:245], v[68:71]
	v_mfma_f32_16x16x32_bf16 v[64:67], v[210:213], v[242:245], v[64:67]
	s_setprio 0
	s_barrier
	s_add_u32 s60, s44, 0x80
	s_addc_u32 s61, s45, 0
	s_add_u32 s62, s46, 0x80
	s_addc_u32 s63, s47, 0
	s_add_i32 s21, s22, s3
	s_mov_b32 m0, s21
	ds_read_b128 v[214:217], v155 offset:16384
	ds_read_b128 v[218:221], v155 offset:17408
	ds_read_b128 v[222:225], v155 offset:18432
	ds_read_b128 v[226:229], v155 offset:19456
	ds_read_b128 v[230:233], v155 offset:20480
	ds_read_b128 v[234:237], v155 offset:21504
	ds_read_b128 v[238:241], v155 offset:22528
	ds_read_b128 v[242:245], v155 offset:23552
	global_load_lds_dwordx4 v130, s[44:45]
	s_add_i32 m0, s21, 0x2000
	s_add_u32 s24, s44, 0x40000
	s_addc_u32 s25, s45, 0
	s_add_i32 s21, s23, s3
	global_load_lds_dwordx4 v146, s[44:45]
	s_mov_b32 m0, s21
	s_nop 0
	global_load_lds_dwordx4 v130, s[24:25]
	s_add_i32 m0, s21, 0x2000
	s_nop 0
	global_load_lds_dwordx4 v146, s[24:25]
	s_mov_b32 m0, s12
	s_nop 0
	global_load_lds_dwordx4 v142, s[46:47]
	s_mov_b32 m0, s13
	s_nop 0
	global_load_lds_dwordx4 v144, s[46:47]
	s_waitcnt vmcnt(8)
	s_waitcnt lgkmcnt(0)
	s_barrier
	s_setprio 1
	s_waitcnt lgkmcnt(0)
	v_mfma_f32_16x16x32_bf16 v[60:63], v[182:185], v[214:217], 0
	v_mfma_f32_16x16x32_bf16 v[56:59], v[190:193], v[214:217], 0
	v_mfma_f32_16x16x32_bf16 v[52:55], v[182:185], v[222:225], 0
	v_mfma_f32_16x16x32_bf16 v[48:51], v[190:193], v[222:225], 0
	v_mfma_f32_16x16x32_bf16 v[36:39], v[182:185], v[230:233], 0
	v_mfma_f32_16x16x32_bf16 v[32:35], v[190:193], v[230:233], 0
	v_mfma_f32_16x16x32_bf16 v[20:23], v[182:185], v[238:241], 0
	v_mfma_f32_16x16x32_bf16 v[16:19], v[190:193], v[238:241], 0
	v_mfma_f32_16x16x32_bf16 v[60:63], v[186:189], v[218:221], v[60:63]
	v_mfma_f32_16x16x32_bf16 v[56:59], v[194:197], v[218:221], v[56:59]
	v_mfma_f32_16x16x32_bf16 v[52:55], v[186:189], v[226:229], v[52:55]
	v_mfma_f32_16x16x32_bf16 v[48:51], v[194:197], v[226:229], v[48:51]
	v_mfma_f32_16x16x32_bf16 v[36:39], v[186:189], v[234:237], v[36:39]
	v_mfma_f32_16x16x32_bf16 v[32:35], v[194:197], v[234:237], v[32:35]
	v_mfma_f32_16x16x32_bf16 v[20:23], v[186:189], v[242:245], v[20:23]
	v_mfma_f32_16x16x32_bf16 v[16:19], v[194:197], v[242:245], v[16:19]
	s_setprio 0
	s_setprio 1
	v_mfma_f32_16x16x32_bf16 v[44:47], v[198:201], v[214:217], 0
	v_mfma_f32_16x16x32_bf16 v[40:43], v[206:209], v[214:217], 0
	v_mfma_f32_16x16x32_bf16 v[28:31], v[198:201], v[222:225], 0
	v_mfma_f32_16x16x32_bf16 v[24:27], v[206:209], v[222:225], 0
	v_mfma_f32_16x16x32_bf16 v[12:15], v[198:201], v[230:233], 0
	v_mfma_f32_16x16x32_bf16 v[8:11], v[206:209], v[230:233], 0
	v_mfma_f32_16x16x32_bf16 v[4:7], v[198:201], v[238:241], 0
	v_mfma_f32_16x16x32_bf16 v[0:3], v[206:209], v[238:241], 0
	v_mfma_f32_16x16x32_bf16 v[44:47], v[202:205], v[218:221], v[44:47]
	v_mfma_f32_16x16x32_bf16 v[40:43], v[210:213], v[218:221], v[40:43]
	v_mfma_f32_16x16x32_bf16 v[28:31], v[202:205], v[226:229], v[28:31]
	v_mfma_f32_16x16x32_bf16 v[24:27], v[210:213], v[226:229], v[24:27]
	v_mfma_f32_16x16x32_bf16 v[12:15], v[202:205], v[234:237], v[12:15]
	v_mfma_f32_16x16x32_bf16 v[8:11], v[210:213], v[234:237], v[8:11]
	v_mfma_f32_16x16x32_bf16 v[4:7], v[202:205], v[242:245], v[4:7]
	v_mfma_f32_16x16x32_bf16 v[0:3], v[210:213], v[242:245], v[0:3]
	s_setprio 0
	s_barrier
	v_add_u32_e32 v181, s34, v153
	ds_read_b128 v[182:185], v181
	ds_read_b128 v[186:189], v181 offset:1024
	ds_read_b128 v[190:193], v181 offset:2048
	ds_read_b128 v[194:197], v181 offset:3072
	v_add_u32_e32 v181, s35, v153
	ds_read_b128 v[198:201], v181
	ds_read_b128 v[202:205], v181 offset:1024
	ds_read_b128 v[206:209], v181 offset:2048
	ds_read_b128 v[210:213], v181 offset:3072
	s_add_u32 s24, s46, 0xc0000
	s_addc_u32 s25, s47, 0
	s_mov_b32 m0, s18
	ds_read_b128 v[214:217], v155 offset:32768
	ds_read_b128 v[218:221], v155 offset:33792
	ds_read_b128 v[222:225], v155 offset:34816
	ds_read_b128 v[226:229], v155 offset:35840
	ds_read_b128 v[230:233], v155 offset:36864
	ds_read_b128 v[234:237], v155 offset:37888
	ds_read_b128 v[238:241], v155 offset:38912
	ds_read_b128 v[242:245], v155 offset:39936
	global_load_lds_dwordx4 v142, s[24:25]
	s_mov_b32 m0, s19
	s_nop 0
	global_load_lds_dwordx4 v144, s[24:25]
	s_waitcnt vmcnt(8)
	s_waitcnt lgkmcnt(0)
	s_barrier
	s_setprio 1
	s_waitcnt lgkmcnt(0)
	v_mfma_f32_16x16x32_bf16 v[124:127], v[182:185], v[214:217], v[124:127]
	v_mfma_f32_16x16x32_bf16 v[120:123], v[190:193], v[214:217], v[120:123]
	v_mfma_f32_16x16x32_bf16 v[116:119], v[182:185], v[222:225], v[116:119]
	v_mfma_f32_16x16x32_bf16 v[112:115], v[190:193], v[222:225], v[112:115]
	v_mfma_f32_16x16x32_bf16 v[100:103], v[182:185], v[230:233], v[100:103]
	v_mfma_f32_16x16x32_bf16 v[96:99], v[190:193], v[230:233], v[96:99]
	v_mfma_f32_16x16x32_bf16 v[84:87], v[182:185], v[238:241], v[84:87]
	v_mfma_f32_16x16x32_bf16 v[80:83], v[190:193], v[238:241], v[80:83]
	v_mfma_f32_16x16x32_bf16 v[124:127], v[186:189], v[218:221], v[124:127]
	v_mfma_f32_16x16x32_bf16 v[120:123], v[194:197], v[218:221], v[120:123]
	v_mfma_f32_16x16x32_bf16 v[116:119], v[186:189], v[226:229], v[116:119]
	v_mfma_f32_16x16x32_bf16 v[112:115], v[194:197], v[226:229], v[112:115]
	v_mfma_f32_16x16x32_bf16 v[100:103], v[186:189], v[234:237], v[100:103]
	v_mfma_f32_16x16x32_bf16 v[96:99], v[194:197], v[234:237], v[96:99]
	v_mfma_f32_16x16x32_bf16 v[84:87], v[186:189], v[242:245], v[84:87]
	v_mfma_f32_16x16x32_bf16 v[80:83], v[194:197], v[242:245], v[80:83]
	s_setprio 0
	s_setprio 1
	v_mfma_f32_16x16x32_bf16 v[108:111], v[198:201], v[214:217], v[108:111]
	v_mfma_f32_16x16x32_bf16 v[104:107], v[206:209], v[214:217], v[104:107]
	v_mfma_f32_16x16x32_bf16 v[92:95], v[198:201], v[222:225], v[92:95]
	v_mfma_f32_16x16x32_bf16 v[88:91], v[206:209], v[222:225], v[88:91]
	v_mfma_f32_16x16x32_bf16 v[76:79], v[198:201], v[230:233], v[76:79]
	v_mfma_f32_16x16x32_bf16 v[72:75], v[206:209], v[230:233], v[72:75]
	v_mfma_f32_16x16x32_bf16 v[68:71], v[198:201], v[238:241], v[68:71]
	v_mfma_f32_16x16x32_bf16 v[64:67], v[206:209], v[238:241], v[64:67]
	v_mfma_f32_16x16x32_bf16 v[108:111], v[202:205], v[218:221], v[108:111]
	v_mfma_f32_16x16x32_bf16 v[104:107], v[210:213], v[218:221], v[104:107]
	v_mfma_f32_16x16x32_bf16 v[92:95], v[202:205], v[226:229], v[92:95]
	v_mfma_f32_16x16x32_bf16 v[88:91], v[210:213], v[226:229], v[88:91]
	v_mfma_f32_16x16x32_bf16 v[76:79], v[202:205], v[234:237], v[76:79]
	v_mfma_f32_16x16x32_bf16 v[72:75], v[210:213], v[234:237], v[72:75]
	v_mfma_f32_16x16x32_bf16 v[68:71], v[202:205], v[242:245], v[68:71]
	v_mfma_f32_16x16x32_bf16 v[64:67], v[210:213], v[242:245], v[64:67]
	s_setprio 0
	s_barrier
	s_add_i32 s21, s34, s3
	s_mov_b32 m0, s21
	ds_read_b128 v[214:217], v155 offset:49152
	ds_read_b128 v[218:221], v155 offset:50176
	ds_read_b128 v[222:225], v155 offset:51200
	ds_read_b128 v[226:229], v155 offset:52224
	ds_read_b128 v[230:233], v155 offset:53248
	ds_read_b128 v[234:237], v155 offset:54272
	ds_read_b128 v[238:241], v155 offset:55296
	ds_read_b128 v[242:245], v155 offset:56320
	global_load_lds_dwordx4 v130, s[60:61]
	s_add_i32 m0, s21, 0x2000
	s_add_u32 s24, s44, 0x40080
	s_addc_u32 s25, s45, 0
	s_add_i32 s21, s35, s3
	global_load_lds_dwordx4 v146, s[60:61]
	s_mov_b32 m0, s21
	s_nop 0
	global_load_lds_dwordx4 v130, s[24:25]
	s_add_i32 m0, s21, 0x2000
	s_nop 0
	global_load_lds_dwordx4 v146, s[24:25]
	s_mov_b32 m0, s20
	s_nop 0
	global_load_lds_dwordx4 v142, s[62:63]
	s_mov_b32 m0, s26
	s_nop 0
	global_load_lds_dwordx4 v144, s[62:63]
	s_waitcnt vmcnt(8)
	s_waitcnt lgkmcnt(0)
	s_barrier
	s_setprio 1
	s_waitcnt lgkmcnt(0)
	v_mfma_f32_16x16x32_bf16 v[60:63], v[182:185], v[214:217], v[60:63]
	v_mfma_f32_16x16x32_bf16 v[56:59], v[190:193], v[214:217], v[56:59]
	v_mfma_f32_16x16x32_bf16 v[52:55], v[182:185], v[222:225], v[52:55]
	v_mfma_f32_16x16x32_bf16 v[48:51], v[190:193], v[222:225], v[48:51]
	v_mfma_f32_16x16x32_bf16 v[36:39], v[182:185], v[230:233], v[36:39]
	v_mfma_f32_16x16x32_bf16 v[32:35], v[190:193], v[230:233], v[32:35]
	v_mfma_f32_16x16x32_bf16 v[20:23], v[182:185], v[238:241], v[20:23]
	v_mfma_f32_16x16x32_bf16 v[16:19], v[190:193], v[238:241], v[16:19]
	v_mfma_f32_16x16x32_bf16 v[60:63], v[186:189], v[218:221], v[60:63]
	v_mfma_f32_16x16x32_bf16 v[56:59], v[194:197], v[218:221], v[56:59]
	v_mfma_f32_16x16x32_bf16 v[52:55], v[186:189], v[226:229], v[52:55]
	v_mfma_f32_16x16x32_bf16 v[48:51], v[194:197], v[226:229], v[48:51]
	v_mfma_f32_16x16x32_bf16 v[36:39], v[186:189], v[234:237], v[36:39]
	v_mfma_f32_16x16x32_bf16 v[32:35], v[194:197], v[234:237], v[32:35]
	v_mfma_f32_16x16x32_bf16 v[20:23], v[186:189], v[242:245], v[20:23]
	v_mfma_f32_16x16x32_bf16 v[16:19], v[194:197], v[242:245], v[16:19]
	s_setprio 0
	s_setprio 1
	v_mfma_f32_16x16x32_bf16 v[44:47], v[198:201], v[214:217], v[44:47]
	v_mfma_f32_16x16x32_bf16 v[40:43], v[206:209], v[214:217], v[40:43]
	v_mfma_f32_16x16x32_bf16 v[28:31], v[198:201], v[222:225], v[28:31]
	v_mfma_f32_16x16x32_bf16 v[24:27], v[206:209], v[222:225], v[24:27]
	v_mfma_f32_16x16x32_bf16 v[12:15], v[198:201], v[230:233], v[12:15]
	v_mfma_f32_16x16x32_bf16 v[8:11], v[206:209], v[230:233], v[8:11]
	v_mfma_f32_16x16x32_bf16 v[4:7], v[198:201], v[238:241], v[4:7]
	v_mfma_f32_16x16x32_bf16 v[0:3], v[206:209], v[238:241], v[0:3]
	v_mfma_f32_16x16x32_bf16 v[44:47], v[202:205], v[218:221], v[44:47]
	v_mfma_f32_16x16x32_bf16 v[40:43], v[210:213], v[218:221], v[40:43]
	v_mfma_f32_16x16x32_bf16 v[28:31], v[202:205], v[226:229], v[28:31]
	v_mfma_f32_16x16x32_bf16 v[24:27], v[210:213], v[226:229], v[24:27]
	v_mfma_f32_16x16x32_bf16 v[12:15], v[202:205], v[234:237], v[12:15]
	v_mfma_f32_16x16x32_bf16 v[8:11], v[210:213], v[234:237], v[8:11]
	v_mfma_f32_16x16x32_bf16 v[4:7], v[202:205], v[242:245], v[4:7]
	v_mfma_f32_16x16x32_bf16 v[0:3], v[210:213], v[242:245], v[0:3]
	s_setprio 0
	s_barrier
	s_add_u32 s29, s29, 0x100
	s_addc_u32 s49, s49, 0
	s_cmp_ge_i32 s50, s48
	s_mov_b64 s[40:41], s[42:43]
	s_mov_b32 s44, s50
	s_cbranch_scc1 .Lpeel_done_855
.LBB0_855:
	v_add_u32_e32 v156, s22, v153
	ds_read_b128 v[182:185], v156
	ds_read_b128 v[186:189], v156 offset:1024
	ds_read_b128 v[190:193], v156 offset:2048
	ds_read_b128 v[194:197], v156 offset:3072
	v_add_u32_e32 v156, s23, v153
	ds_read_b128 v[198:201], v156
	ds_read_b128 v[202:205], v156 offset:1024
	ds_read_b128 v[206:209], v156 offset:2048
	ds_read_b128 v[210:213], v156 offset:3072
	s_add_i32 s50, s44, 2
	s_add_u32 s42, s40, 0x100
	s_addc_u32 s43, s41, 0
	s_cmp_eq_u32 s11, s44
	s_cselect_b32 s44, s36, s29
	s_cselect_b32 s47, s17, s43
	s_cselect_b32 s46, s16, s42
	s_cselect_b32 s45, s37, s49
	s_add_i32 m0, s12, 0xc000
	ds_read_b128 v[214:217], v155
	ds_read_b128 v[218:221], v155 offset:1024
	ds_read_b128 v[222:225], v155 offset:2048
	ds_read_b128 v[226:229], v155 offset:3072
	ds_read_b128 v[230:233], v155 offset:4096
	ds_read_b128 v[234:237], v155 offset:5120
	ds_read_b128 v[238:241], v155 offset:6144
	ds_read_b128 v[242:245], v155 offset:7168
	global_load_lds_dwordx4 v148, s[40:41]
	s_add_i32 m0, s12, 0xe000
	s_nop 0
	global_load_lds_dwordx4 v150, s[40:41]
	s_waitcnt vmcnt(8)
	s_waitcnt lgkmcnt(0)
	s_barrier
	s_setprio 1
	s_waitcnt lgkmcnt(0)
	v_mfma_f32_16x16x32_bf16 v[124:127], v[182:185], v[214:217], v[124:127]
	v_mfma_f32_16x16x32_bf16 v[120:123], v[190:193], v[214:217], v[120:123]
	v_mfma_f32_16x16x32_bf16 v[116:119], v[182:185], v[222:225], v[116:119]
	v_mfma_f32_16x16x32_bf16 v[112:115], v[190:193], v[222:225], v[112:115]
	v_mfma_f32_16x16x32_bf16 v[100:103], v[182:185], v[230:233], v[100:103]
	v_mfma_f32_16x16x32_bf16 v[96:99], v[190:193], v[230:233], v[96:99]
	v_mfma_f32_16x16x32_bf16 v[84:87], v[182:185], v[238:241], v[84:87]
	v_mfma_f32_16x16x32_bf16 v[80:83], v[190:193], v[238:241], v[80:83]
	v_mfma_f32_16x16x32_bf16 v[124:127], v[186:189], v[218:221], v[124:127]
	v_mfma_f32_16x16x32_bf16 v[120:123], v[194:197], v[218:221], v[120:123]
	v_mfma_f32_16x16x32_bf16 v[116:119], v[186:189], v[226:229], v[116:119]
	v_mfma_f32_16x16x32_bf16 v[112:115], v[194:197], v[226:229], v[112:115]
	v_mfma_f32_16x16x32_bf16 v[100:103], v[186:189], v[234:237], v[100:103]
	v_mfma_f32_16x16x32_bf16 v[96:99], v[194:197], v[234:237], v[96:99]
	v_mfma_f32_16x16x32_bf16 v[84:87], v[186:189], v[242:245], v[84:87]
	v_mfma_f32_16x16x32_bf16 v[80:83], v[194:197], v[242:245], v[80:83]
	s_setprio 0
	s_setprio 1
	v_mfma_f32_16x16x32_bf16 v[108:111], v[198:201], v[214:217], v[108:111]
	v_mfma_f32_16x16x32_bf16 v[104:107], v[206:209], v[214:217], v[104:107]
	v_mfma_f32_16x16x32_bf16 v[92:95], v[198:201], v[222:225], v[92:95]
	v_mfma_f32_16x16x32_bf16 v[88:91], v[206:209], v[222:225], v[88:91]
	v_mfma_f32_16x16x32_bf16 v[76:79], v[198:201], v[230:233], v[76:79]
	v_mfma_f32_16x16x32_bf16 v[72:75], v[206:209], v[230:233], v[72:75]
	v_mfma_f32_16x16x32_bf16 v[68:71], v[198:201], v[238:241], v[68:71]
	v_mfma_f32_16x16x32_bf16 v[64:67], v[206:209], v[238:241], v[64:67]
	v_mfma_f32_16x16x32_bf16 v[108:111], v[202:205], v[218:221], v[108:111]
	v_mfma_f32_16x16x32_bf16 v[104:107], v[210:213], v[218:221], v[104:107]
	v_mfma_f32_16x16x32_bf16 v[92:95], v[202:205], v[226:229], v[92:95]
	v_mfma_f32_16x16x32_bf16 v[88:91], v[210:213], v[226:229], v[88:91]
	v_mfma_f32_16x16x32_bf16 v[76:79], v[202:205], v[234:237], v[76:79]
	v_mfma_f32_16x16x32_bf16 v[72:75], v[210:213], v[234:237], v[72:75]
	v_mfma_f32_16x16x32_bf16 v[68:71], v[202:205], v[242:245], v[68:71]
	v_mfma_f32_16x16x32_bf16 v[64:67], v[210:213], v[242:245], v[64:67]
	s_setprio 0
	s_barrier
	s_add_u32 s60, s44, 0x80
	s_addc_u32 s61, s45, 0
	s_add_u32 s62, s46, 0x80
	s_addc_u32 s63, s47, 0
	s_add_i32 s21, s22, s3
	s_mov_b32 m0, s21
	ds_read_b128 v[214:217], v155 offset:16384
	ds_read_b128 v[218:221], v155 offset:17408
	ds_read_b128 v[222:225], v155 offset:18432
	ds_read_b128 v[226:229], v155 offset:19456
	ds_read_b128 v[230:233], v155 offset:20480
	ds_read_b128 v[234:237], v155 offset:21504
	ds_read_b128 v[238:241], v155 offset:22528
	ds_read_b128 v[242:245], v155 offset:23552
	global_load_lds_dwordx4 v130, s[44:45]
	s_add_i32 m0, s21, 0x2000
	s_add_u32 s24, s44, 0x40000
	s_addc_u32 s25, s45, 0
	s_add_i32 s21, s23, s3
	global_load_lds_dwordx4 v146, s[44:45]
	s_mov_b32 m0, s21
	s_nop 0
	global_load_lds_dwordx4 v130, s[24:25]
	s_add_i32 m0, s21, 0x2000
	s_nop 0
	global_load_lds_dwordx4 v146, s[24:25]
	s_mov_b32 m0, s12
	s_nop 0
	global_load_lds_dwordx4 v142, s[46:47]
	s_mov_b32 m0, s13
	s_nop 0
	global_load_lds_dwordx4 v144, s[46:47]
	s_waitcnt vmcnt(8)
	s_waitcnt lgkmcnt(0)
	s_barrier
	s_setprio 1
	s_waitcnt lgkmcnt(0)
	v_mfma_f32_16x16x32_bf16 v[60:63], v[182:185], v[214:217], v[60:63]
	v_mfma_f32_16x16x32_bf16 v[56:59], v[190:193], v[214:217], v[56:59]
	v_mfma_f32_16x16x32_bf16 v[52:55], v[182:185], v[222:225], v[52:55]
	v_mfma_f32_16x16x32_bf16 v[48:51], v[190:193], v[222:225], v[48:51]
	v_mfma_f32_16x16x32_bf16 v[36:39], v[182:185], v[230:233], v[36:39]
	v_mfma_f32_16x16x32_bf16 v[32:35], v[190:193], v[230:233], v[32:35]
	v_mfma_f32_16x16x32_bf16 v[20:23], v[182:185], v[238:241], v[20:23]
	v_mfma_f32_16x16x32_bf16 v[16:19], v[190:193], v[238:241], v[16:19]
	v_mfma_f32_16x16x32_bf16 v[60:63], v[186:189], v[218:221], v[60:63]
	v_mfma_f32_16x16x32_bf16 v[56:59], v[194:197], v[218:221], v[56:59]
	v_mfma_f32_16x16x32_bf16 v[52:55], v[186:189], v[226:229], v[52:55]
	v_mfma_f32_16x16x32_bf16 v[48:51], v[194:197], v[226:229], v[48:51]
	v_mfma_f32_16x16x32_bf16 v[36:39], v[186:189], v[234:237], v[36:39]
	v_mfma_f32_16x16x32_bf16 v[32:35], v[194:197], v[234:237], v[32:35]
	v_mfma_f32_16x16x32_bf16 v[20:23], v[186:189], v[242:245], v[20:23]
	v_mfma_f32_16x16x32_bf16 v[16:19], v[194:197], v[242:245], v[16:19]
	s_setprio 0
	s_setprio 1
	v_mfma_f32_16x16x32_bf16 v[44:47], v[198:201], v[214:217], v[44:47]
	v_mfma_f32_16x16x32_bf16 v[40:43], v[206:209], v[214:217], v[40:43]
	v_mfma_f32_16x16x32_bf16 v[28:31], v[198:201], v[222:225], v[28:31]
	v_mfma_f32_16x16x32_bf16 v[24:27], v[206:209], v[222:225], v[24:27]
	v_mfma_f32_16x16x32_bf16 v[12:15], v[198:201], v[230:233], v[12:15]
	v_mfma_f32_16x16x32_bf16 v[8:11], v[206:209], v[230:233], v[8:11]
	v_mfma_f32_16x16x32_bf16 v[4:7], v[198:201], v[238:241], v[4:7]
	v_mfma_f32_16x16x32_bf16 v[0:3], v[206:209], v[238:241], v[0:3]
	v_mfma_f32_16x16x32_bf16 v[44:47], v[202:205], v[218:221], v[44:47]
	v_mfma_f32_16x16x32_bf16 v[40:43], v[210:213], v[218:221], v[40:43]
	v_mfma_f32_16x16x32_bf16 v[28:31], v[202:205], v[226:229], v[28:31]
	v_mfma_f32_16x16x32_bf16 v[24:27], v[210:213], v[226:229], v[24:27]
	v_mfma_f32_16x16x32_bf16 v[12:15], v[202:205], v[234:237], v[12:15]
	v_mfma_f32_16x16x32_bf16 v[8:11], v[210:213], v[234:237], v[8:11]
	v_mfma_f32_16x16x32_bf16 v[4:7], v[202:205], v[242:245], v[4:7]
	v_mfma_f32_16x16x32_bf16 v[0:3], v[210:213], v[242:245], v[0:3]
	s_setprio 0
	s_barrier
	v_add_u32_e32 v181, s34, v153
	ds_read_b128 v[182:185], v181
	ds_read_b128 v[186:189], v181 offset:1024
	ds_read_b128 v[190:193], v181 offset:2048
	ds_read_b128 v[194:197], v181 offset:3072
	v_add_u32_e32 v181, s35, v153
	ds_read_b128 v[198:201], v181
	ds_read_b128 v[202:205], v181 offset:1024
	ds_read_b128 v[206:209], v181 offset:2048
	ds_read_b128 v[210:213], v181 offset:3072
	s_add_u32 s24, s46, 0xc0000
	s_addc_u32 s25, s47, 0
	s_mov_b32 m0, s18
	ds_read_b128 v[214:217], v155 offset:32768
	ds_read_b128 v[218:221], v155 offset:33792
	ds_read_b128 v[222:225], v155 offset:34816
	ds_read_b128 v[226:229], v155 offset:35840
	ds_read_b128 v[230:233], v155 offset:36864
	ds_read_b128 v[234:237], v155 offset:37888
	ds_read_b128 v[238:241], v155 offset:38912
	ds_read_b128 v[242:245], v155 offset:39936
	global_load_lds_dwordx4 v142, s[24:25]
	s_mov_b32 m0, s19
	s_nop 0
	global_load_lds_dwordx4 v144, s[24:25]
	s_waitcnt vmcnt(8)
	s_waitcnt lgkmcnt(0)
	s_barrier
	s_setprio 1
	s_waitcnt lgkmcnt(0)
	v_mfma_f32_16x16x32_bf16 v[124:127], v[182:185], v[214:217], v[124:127]
	v_mfma_f32_16x16x32_bf16 v[120:123], v[190:193], v[214:217], v[120:123]
	v_mfma_f32_16x16x32_bf16 v[116:119], v[182:185], v[222:225], v[116:119]
	v_mfma_f32_16x16x32_bf16 v[112:115], v[190:193], v[222:225], v[112:115]
	v_mfma_f32_16x16x32_bf16 v[100:103], v[182:185], v[230:233], v[100:103]
	v_mfma_f32_16x16x32_bf16 v[96:99], v[190:193], v[230:233], v[96:99]
	v_mfma_f32_16x16x32_bf16 v[84:87], v[182:185], v[238:241], v[84:87]
	v_mfma_f32_16x16x32_bf16 v[80:83], v[190:193], v[238:241], v[80:83]
	v_mfma_f32_16x16x32_bf16 v[124:127], v[186:189], v[218:221], v[124:127]
	v_mfma_f32_16x16x32_bf16 v[120:123], v[194:197], v[218:221], v[120:123]
	v_mfma_f32_16x16x32_bf16 v[116:119], v[186:189], v[226:229], v[116:119]
	v_mfma_f32_16x16x32_bf16 v[112:115], v[194:197], v[226:229], v[112:115]
	v_mfma_f32_16x16x32_bf16 v[100:103], v[186:189], v[234:237], v[100:103]
	v_mfma_f32_16x16x32_bf16 v[96:99], v[194:197], v[234:237], v[96:99]
	v_mfma_f32_16x16x32_bf16 v[84:87], v[186:189], v[242:245], v[84:87]
	v_mfma_f32_16x16x32_bf16 v[80:83], v[194:197], v[242:245], v[80:83]
	s_setprio 0
	s_setprio 1
	v_mfma_f32_16x16x32_bf16 v[108:111], v[198:201], v[214:217], v[108:111]
	v_mfma_f32_16x16x32_bf16 v[104:107], v[206:209], v[214:217], v[104:107]
	v_mfma_f32_16x16x32_bf16 v[92:95], v[198:201], v[222:225], v[92:95]
	v_mfma_f32_16x16x32_bf16 v[88:91], v[206:209], v[222:225], v[88:91]
	v_mfma_f32_16x16x32_bf16 v[76:79], v[198:201], v[230:233], v[76:79]
	v_mfma_f32_16x16x32_bf16 v[72:75], v[206:209], v[230:233], v[72:75]
	v_mfma_f32_16x16x32_bf16 v[68:71], v[198:201], v[238:241], v[68:71]
	v_mfma_f32_16x16x32_bf16 v[64:67], v[206:209], v[238:241], v[64:67]
	v_mfma_f32_16x16x32_bf16 v[108:111], v[202:205], v[218:221], v[108:111]
	v_mfma_f32_16x16x32_bf16 v[104:107], v[210:213], v[218:221], v[104:107]
	v_mfma_f32_16x16x32_bf16 v[92:95], v[202:205], v[226:229], v[92:95]
	v_mfma_f32_16x16x32_bf16 v[88:91], v[210:213], v[226:229], v[88:91]
	v_mfma_f32_16x16x32_bf16 v[76:79], v[202:205], v[234:237], v[76:79]
	v_mfma_f32_16x16x32_bf16 v[72:75], v[210:213], v[234:237], v[72:75]
	v_mfma_f32_16x16x32_bf16 v[68:71], v[202:205], v[242:245], v[68:71]
	v_mfma_f32_16x16x32_bf16 v[64:67], v[210:213], v[242:245], v[64:67]
	s_setprio 0
	s_barrier
	s_add_i32 s21, s34, s3
	s_mov_b32 m0, s21
	ds_read_b128 v[214:217], v155 offset:49152
	ds_read_b128 v[218:221], v155 offset:50176
	ds_read_b128 v[222:225], v155 offset:51200
	ds_read_b128 v[226:229], v155 offset:52224
	ds_read_b128 v[230:233], v155 offset:53248
	ds_read_b128 v[234:237], v155 offset:54272
	ds_read_b128 v[238:241], v155 offset:55296
	ds_read_b128 v[242:245], v155 offset:56320
	global_load_lds_dwordx4 v130, s[60:61]
	s_add_i32 m0, s21, 0x2000
	s_add_u32 s24, s44, 0x40080
	s_addc_u32 s25, s45, 0
	s_add_i32 s21, s35, s3
	global_load_lds_dwordx4 v146, s[60:61]
	s_mov_b32 m0, s21
	s_nop 0
	global_load_lds_dwordx4 v130, s[24:25]
	s_add_i32 m0, s21, 0x2000
	s_nop 0
	global_load_lds_dwordx4 v146, s[24:25]
	s_mov_b32 m0, s20
	s_nop 0
	global_load_lds_dwordx4 v142, s[62:63]
	s_mov_b32 m0, s26
	s_nop 0
	global_load_lds_dwordx4 v144, s[62:63]
	s_waitcnt vmcnt(8)
	s_waitcnt lgkmcnt(0)
	s_barrier
	s_setprio 1
	s_waitcnt lgkmcnt(0)
	v_mfma_f32_16x16x32_bf16 v[60:63], v[182:185], v[214:217], v[60:63]
	v_mfma_f32_16x16x32_bf16 v[56:59], v[190:193], v[214:217], v[56:59]
	v_mfma_f32_16x16x32_bf16 v[52:55], v[182:185], v[222:225], v[52:55]
	v_mfma_f32_16x16x32_bf16 v[48:51], v[190:193], v[222:225], v[48:51]
	v_mfma_f32_16x16x32_bf16 v[36:39], v[182:185], v[230:233], v[36:39]
	v_mfma_f32_16x16x32_bf16 v[32:35], v[190:193], v[230:233], v[32:35]
	v_mfma_f32_16x16x32_bf16 v[20:23], v[182:185], v[238:241], v[20:23]
	v_mfma_f32_16x16x32_bf16 v[16:19], v[190:193], v[238:241], v[16:19]
	v_mfma_f32_16x16x32_bf16 v[60:63], v[186:189], v[218:221], v[60:63]
	v_mfma_f32_16x16x32_bf16 v[56:59], v[194:197], v[218:221], v[56:59]
	v_mfma_f32_16x16x32_bf16 v[52:55], v[186:189], v[226:229], v[52:55]
	v_mfma_f32_16x16x32_bf16 v[48:51], v[194:197], v[226:229], v[48:51]
	v_mfma_f32_16x16x32_bf16 v[36:39], v[186:189], v[234:237], v[36:39]
	v_mfma_f32_16x16x32_bf16 v[32:35], v[194:197], v[234:237], v[32:35]
	v_mfma_f32_16x16x32_bf16 v[20:23], v[186:189], v[242:245], v[20:23]
	v_mfma_f32_16x16x32_bf16 v[16:19], v[194:197], v[242:245], v[16:19]
	s_setprio 0
	s_setprio 1
	v_mfma_f32_16x16x32_bf16 v[44:47], v[198:201], v[214:217], v[44:47]
	v_mfma_f32_16x16x32_bf16 v[40:43], v[206:209], v[214:217], v[40:43]
	v_mfma_f32_16x16x32_bf16 v[28:31], v[198:201], v[222:225], v[28:31]
	v_mfma_f32_16x16x32_bf16 v[24:27], v[206:209], v[222:225], v[24:27]
	v_mfma_f32_16x16x32_bf16 v[12:15], v[198:201], v[230:233], v[12:15]
	v_mfma_f32_16x16x32_bf16 v[8:11], v[206:209], v[230:233], v[8:11]
	v_mfma_f32_16x16x32_bf16 v[4:7], v[198:201], v[238:241], v[4:7]
	v_mfma_f32_16x16x32_bf16 v[0:3], v[206:209], v[238:241], v[0:3]
	v_mfma_f32_16x16x32_bf16 v[44:47], v[202:205], v[218:221], v[44:47]
	v_mfma_f32_16x16x32_bf16 v[40:43], v[210:213], v[218:221], v[40:43]
	v_mfma_f32_16x16x32_bf16 v[28:31], v[202:205], v[226:229], v[28:31]
	v_mfma_f32_16x16x32_bf16 v[24:27], v[210:213], v[226:229], v[24:27]
	v_mfma_f32_16x16x32_bf16 v[12:15], v[202:205], v[234:237], v[12:15]
	v_mfma_f32_16x16x32_bf16 v[8:11], v[210:213], v[234:237], v[8:11]
	v_mfma_f32_16x16x32_bf16 v[4:7], v[202:205], v[242:245], v[4:7]
	v_mfma_f32_16x16x32_bf16 v[0:3], v[210:213], v[242:245], v[0:3]
	s_setprio 0
	s_barrier
	s_add_u32 s29, s29, 0x100
	s_addc_u32 s49, s49, 0
	s_cmp_ge_i32 s50, s48
	s_mov_b64 s[40:41], s[42:43]
	s_mov_b32 s44, s50
	s_cbranch_scc0 .LBB0_855

.LBB0_871:
	s_ashr_i32 s17, s16, 31
	s_lshl_b64 s[18:19], s[16:17], 19
	v_readlane_b32 s24, v252, 27
	v_readlane_b32 s25, v252, 28
	s_add_u32 s28, s24, s18
	s_addc_u32 s29, s25, s19
	s_and_b64 s[18:19], s[4:5], exec
	s_cselect_b32 s17, s29, s41
	s_cselect_b32 s18, s28, s40
	s_ashr_i32 s11, s10, 31
	s_lshl_b64 s[36:37], s[10:11], 19
	v_readlane_b32 s11, v252, 23
	s_add_u32 s36, s11, s36
	v_readlane_b32 s11, v252, 24
	s_addc_u32 s37, s11, s37
	s_and_b64 s[38:39], s[4:5], exec
	s_cselect_b32 s11, s37, s43
	s_cselect_b32 s19, s36, s42
	s_add_u32 s40, s40, 0x40080
	s_addc_u32 s41, s41, 0
	s_add_u32 s38, s42, 0x100
	s_addc_u32 s39, s43, 0
	s_mov_b32 s46, -2
	v_add_u32_e32 v156, s22, v153
	ds_read_b128 v[182:185], v156
	ds_read_b128 v[186:189], v156 offset:1024
	ds_read_b128 v[190:193], v156 offset:2048
	ds_read_b128 v[194:197], v156 offset:3072
	v_add_u32_e32 v156, s23, v153
	ds_read_b128 v[198:201], v156
	ds_read_b128 v[202:205], v156 offset:1024
	ds_read_b128 v[206:209], v156 offset:2048
	ds_read_b128 v[210:213], v156 offset:3072
	s_add_u32 s21, s40, 0xfffc0080
	s_addc_u32 s24, s41, -1
	s_cmp_eq_u32 s46, 12
	s_cselect_b32 s45, s17, s24
	s_cselect_b32 s44, s18, s21
	s_cselect_b32 s43, s11, s39
	s_cselect_b32 s42, s19, s38
	s_add_i32 m0, s12, 0xc000
	ds_read_b128 v[214:217], v155
	ds_read_b128 v[218:221], v155 offset:1024
	ds_read_b128 v[222:225], v155 offset:2048
	ds_read_b128 v[226:229], v155 offset:3072
	ds_read_b128 v[230:233], v155 offset:4096
	ds_read_b128 v[234:237], v155 offset:5120
	ds_read_b128 v[238:241], v155 offset:6144
	ds_read_b128 v[242:245], v155 offset:7168
	global_load_lds_dwordx4 v148, s[40:41]
	s_add_i32 m0, s12, 0xe000
	s_nop 0
	global_load_lds_dwordx4 v150, s[40:41]
	s_waitcnt vmcnt(8)
	s_waitcnt lgkmcnt(0)
	s_barrier
	s_setprio 1
	s_waitcnt lgkmcnt(0)
	v_mfma_f32_16x16x32_bf16 v[124:127], v[182:185], v[214:217], 0
	v_mfma_f32_16x16x32_bf16 v[120:123], v[190:193], v[214:217], 0
	v_mfma_f32_16x16x32_bf16 v[116:119], v[182:185], v[222:225], 0
	v_mfma_f32_16x16x32_bf16 v[112:115], v[190:193], v[222:225], 0
	v_mfma_f32_16x16x32_bf16 v[100:103], v[182:185], v[230:233], 0
	v_mfma_f32_16x16x32_bf16 v[96:99], v[190:193], v[230:233], 0
	v_mfma_f32_16x16x32_bf16 v[84:87], v[182:185], v[238:241], 0
	v_mfma_f32_16x16x32_bf16 v[80:83], v[190:193], v[238:241], 0
	v_mfma_f32_16x16x32_bf16 v[124:127], v[186:189], v[218:221], v[124:127]
	v_mfma_f32_16x16x32_bf16 v[120:123], v[194:197], v[218:221], v[120:123]
	v_mfma_f32_16x16x32_bf16 v[116:119], v[186:189], v[226:229], v[116:119]
	v_mfma_f32_16x16x32_bf16 v[112:115], v[194:197], v[226:229], v[112:115]
	v_mfma_f32_16x16x32_bf16 v[100:103], v[186:189], v[234:237], v[100:103]
	v_mfma_f32_16x16x32_bf16 v[96:99], v[194:197], v[234:237], v[96:99]
	v_mfma_f32_16x16x32_bf16 v[84:87], v[186:189], v[242:245], v[84:87]
	v_mfma_f32_16x16x32_bf16 v[80:83], v[194:197], v[242:245], v[80:83]
	s_setprio 0
	s_setprio 1
	v_mfma_f32_16x16x32_bf16 v[108:111], v[198:201], v[214:217], 0
	v_mfma_f32_16x16x32_bf16 v[104:107], v[206:209], v[214:217], 0
	v_mfma_f32_16x16x32_bf16 v[92:95], v[198:201], v[222:225], 0
	v_mfma_f32_16x16x32_bf16 v[88:91], v[206:209], v[222:225], 0
	v_mfma_f32_16x16x32_bf16 v[76:79], v[198:201], v[230:233], 0
	v_mfma_f32_16x16x32_bf16 v[72:75], v[206:209], v[230:233], 0
	v_mfma_f32_16x16x32_bf16 v[68:71], v[198:201], v[238:241], 0
	v_mfma_f32_16x16x32_bf16 v[64:67], v[206:209], v[238:241], 0
	v_mfma_f32_16x16x32_bf16 v[108:111], v[202:205], v[218:221], v[108:111]
	v_mfma_f32_16x16x32_bf16 v[104:107], v[210:213], v[218:221], v[104:107]
	v_mfma_f32_16x16x32_bf16 v[92:95], v[202:205], v[226:229], v[92:95]
	v_mfma_f32_16x16x32_bf16 v[88:91], v[210:213], v[226:229], v[88:91]
	v_mfma_f32_16x16x32_bf16 v[76:79], v[202:205], v[234:237], v[76:79]
	v_mfma_f32_16x16x32_bf16 v[72:75], v[210:213], v[234:237], v[72:75]
	v_mfma_f32_16x16x32_bf16 v[68:71], v[202:205], v[242:245], v[68:71]
	v_mfma_f32_16x16x32_bf16 v[64:67], v[210:213], v[242:245], v[64:67]
	s_setprio 0
	s_barrier
	s_add_u32 s60, s42, 0x80
	s_addc_u32 s61, s43, 0
	s_add_u32 s62, s44, 0x80
	s_addc_u32 s63, s45, 0
	s_add_i32 s21, s22, s3
	s_mov_b32 m0, s21
	ds_read_b128 v[214:217], v155 offset:16384
	ds_read_b128 v[218:221], v155 offset:17408
	ds_read_b128 v[222:225], v155 offset:18432
	ds_read_b128 v[226:229], v155 offset:19456
	ds_read_b128 v[230:233], v155 offset:20480
	ds_read_b128 v[234:237], v155 offset:21504
	ds_read_b128 v[238:241], v155 offset:22528
	ds_read_b128 v[242:245], v155 offset:23552
	global_load_lds_dwordx4 v130, s[42:43]
	s_add_i32 m0, s21, 0x2000
	s_add_u32 s48, s42, 0x40000
	s_addc_u32 s49, s43, 0
	s_add_i32 s21, s23, s3
	global_load_lds_dwordx4 v142, s[42:43]
	s_mov_b32 m0, s21
	s_nop 0
	global_load_lds_dwordx4 v130, s[48:49]
	s_add_i32 m0, s21, 0x2000
	s_nop 0
	global_load_lds_dwordx4 v142, s[48:49]
	s_mov_b32 m0, s12
	s_nop 0
	global_load_lds_dwordx4 v146, s[44:45]
	s_mov_b32 m0, s13
	s_nop 0
	global_load_lds_dwordx4 v144, s[44:45]
	s_waitcnt vmcnt(8)
	s_waitcnt lgkmcnt(0)
	s_barrier
	s_setprio 1
	s_waitcnt lgkmcnt(0)
	v_mfma_f32_16x16x32_bf16 v[60:63], v[182:185], v[214:217], 0
	v_mfma_f32_16x16x32_bf16 v[56:59], v[190:193], v[214:217], 0
	v_mfma_f32_16x16x32_bf16 v[52:55], v[182:185], v[222:225], 0
	v_mfma_f32_16x16x32_bf16 v[48:51], v[190:193], v[222:225], 0
	v_mfma_f32_16x16x32_bf16 v[36:39], v[182:185], v[230:233], 0
	v_mfma_f32_16x16x32_bf16 v[32:35], v[190:193], v[230:233], 0
	v_mfma_f32_16x16x32_bf16 v[20:23], v[182:185], v[238:241], 0
	v_mfma_f32_16x16x32_bf16 v[16:19], v[190:193], v[238:241], 0
	v_mfma_f32_16x16x32_bf16 v[60:63], v[186:189], v[218:221], v[60:63]
	v_mfma_f32_16x16x32_bf16 v[56:59], v[194:197], v[218:221], v[56:59]
	v_mfma_f32_16x16x32_bf16 v[52:55], v[186:189], v[226:229], v[52:55]
	v_mfma_f32_16x16x32_bf16 v[48:51], v[194:197], v[226:229], v[48:51]
	v_mfma_f32_16x16x32_bf16 v[36:39], v[186:189], v[234:237], v[36:39]
	v_mfma_f32_16x16x32_bf16 v[32:35], v[194:197], v[234:237], v[32:35]
	v_mfma_f32_16x16x32_bf16 v[20:23], v[186:189], v[242:245], v[20:23]
	v_mfma_f32_16x16x32_bf16 v[16:19], v[194:197], v[242:245], v[16:19]
	s_setprio 0
	s_setprio 1
	v_mfma_f32_16x16x32_bf16 v[44:47], v[198:201], v[214:217], 0
	v_mfma_f32_16x16x32_bf16 v[40:43], v[206:209], v[214:217], 0
	v_mfma_f32_16x16x32_bf16 v[28:31], v[198:201], v[222:225], 0
	v_mfma_f32_16x16x32_bf16 v[24:27], v[206:209], v[222:225], 0
	v_mfma_f32_16x16x32_bf16 v[12:15], v[198:201], v[230:233], 0
	v_mfma_f32_16x16x32_bf16 v[8:11], v[206:209], v[230:233], 0
	v_mfma_f32_16x16x32_bf16 v[4:7], v[198:201], v[238:241], 0
	v_mfma_f32_16x16x32_bf16 v[0:3], v[206:209], v[238:241], 0
	v_mfma_f32_16x16x32_bf16 v[44:47], v[202:205], v[218:221], v[44:47]
	v_mfma_f32_16x16x32_bf16 v[40:43], v[210:213], v[218:221], v[40:43]
	v_mfma_f32_16x16x32_bf16 v[28:31], v[202:205], v[226:229], v[28:31]
	v_mfma_f32_16x16x32_bf16 v[24:27], v[210:213], v[226:229], v[24:27]
	v_mfma_f32_16x16x32_bf16 v[12:15], v[202:205], v[234:237], v[12:15]
	v_mfma_f32_16x16x32_bf16 v[8:11], v[210:213], v[234:237], v[8:11]
	v_mfma_f32_16x16x32_bf16 v[4:7], v[202:205], v[242:245], v[4:7]
	v_mfma_f32_16x16x32_bf16 v[0:3], v[210:213], v[242:245], v[0:3]
	s_setprio 0
	s_barrier
	v_add_u32_e32 v181, s34, v153
	ds_read_b128 v[182:185], v181
	ds_read_b128 v[186:189], v181 offset:1024
	ds_read_b128 v[190:193], v181 offset:2048
	ds_read_b128 v[194:197], v181 offset:3072
	v_add_u32_e32 v181, s35, v153
	ds_read_b128 v[198:201], v181
	ds_read_b128 v[202:205], v181 offset:1024
	ds_read_b128 v[206:209], v181 offset:2048
	ds_read_b128 v[210:213], v181 offset:3072
	s_add_u32 s44, s44, 0x40000
	s_addc_u32 s45, s45, 0
	s_mov_b32 m0, s20
	ds_read_b128 v[214:217], v155 offset:32768
	ds_read_b128 v[218:221], v155 offset:33792
	ds_read_b128 v[222:225], v155 offset:34816
	ds_read_b128 v[226:229], v155 offset:35840
	ds_read_b128 v[230:233], v155 offset:36864
	ds_read_b128 v[234:237], v155 offset:37888
	ds_read_b128 v[238:241], v155 offset:38912
	ds_read_b128 v[242:245], v155 offset:39936
	global_load_lds_dwordx4 v146, s[44:45]
	s_mov_b32 m0, s26
	s_nop 0
	global_load_lds_dwordx4 v144, s[44:45]
	s_waitcnt vmcnt(8)
	s_waitcnt lgkmcnt(0)
	s_barrier
	s_setprio 1
	s_waitcnt lgkmcnt(0)
	v_mfma_f32_16x16x32_bf16 v[124:127], v[182:185], v[214:217], v[124:127]
	v_mfma_f32_16x16x32_bf16 v[120:123], v[190:193], v[214:217], v[120:123]
	v_mfma_f32_16x16x32_bf16 v[116:119], v[182:185], v[222:225], v[116:119]
	v_mfma_f32_16x16x32_bf16 v[112:115], v[190:193], v[222:225], v[112:115]
	v_mfma_f32_16x16x32_bf16 v[100:103], v[182:185], v[230:233], v[100:103]
	v_mfma_f32_16x16x32_bf16 v[96:99], v[190:193], v[230:233], v[96:99]
	v_mfma_f32_16x16x32_bf16 v[84:87], v[182:185], v[238:241], v[84:87]
	v_mfma_f32_16x16x32_bf16 v[80:83], v[190:193], v[238:241], v[80:83]
	v_mfma_f32_16x16x32_bf16 v[124:127], v[186:189], v[218:221], v[124:127]
	v_mfma_f32_16x16x32_bf16 v[120:123], v[194:197], v[218:221], v[120:123]
	v_mfma_f32_16x16x32_bf16 v[116:119], v[186:189], v[226:229], v[116:119]
	v_mfma_f32_16x16x32_bf16 v[112:115], v[194:197], v[226:229], v[112:115]
	v_mfma_f32_16x16x32_bf16 v[100:103], v[186:189], v[234:237], v[100:103]
	v_mfma_f32_16x16x32_bf16 v[96:99], v[194:197], v[234:237], v[96:99]
	v_mfma_f32_16x16x32_bf16 v[84:87], v[186:189], v[242:245], v[84:87]
	v_mfma_f32_16x16x32_bf16 v[80:83], v[194:197], v[242:245], v[80:83]
	s_setprio 0
	s_setprio 1
	v_mfma_f32_16x16x32_bf16 v[108:111], v[198:201], v[214:217], v[108:111]
	v_mfma_f32_16x16x32_bf16 v[104:107], v[206:209], v[214:217], v[104:107]
	v_mfma_f32_16x16x32_bf16 v[92:95], v[198:201], v[222:225], v[92:95]
	v_mfma_f32_16x16x32_bf16 v[88:91], v[206:209], v[222:225], v[88:91]
	v_mfma_f32_16x16x32_bf16 v[76:79], v[198:201], v[230:233], v[76:79]
	v_mfma_f32_16x16x32_bf16 v[72:75], v[206:209], v[230:233], v[72:75]
	v_mfma_f32_16x16x32_bf16 v[68:71], v[198:201], v[238:241], v[68:71]
	v_mfma_f32_16x16x32_bf16 v[64:67], v[206:209], v[238:241], v[64:67]
	v_mfma_f32_16x16x32_bf16 v[108:111], v[202:205], v[218:221], v[108:111]
	v_mfma_f32_16x16x32_bf16 v[104:107], v[210:213], v[218:221], v[104:107]
	v_mfma_f32_16x16x32_bf16 v[92:95], v[202:205], v[226:229], v[92:95]
	v_mfma_f32_16x16x32_bf16 v[88:91], v[210:213], v[226:229], v[88:91]
	v_mfma_f32_16x16x32_bf16 v[76:79], v[202:205], v[234:237], v[76:79]
	v_mfma_f32_16x16x32_bf16 v[72:75], v[210:213], v[234:237], v[72:75]
	v_mfma_f32_16x16x32_bf16 v[68:71], v[202:205], v[242:245], v[68:71]
	v_mfma_f32_16x16x32_bf16 v[64:67], v[210:213], v[242:245], v[64:67]
	s_setprio 0
	s_barrier
	s_add_i32 s21, s34, s3
	s_mov_b32 m0, s21
	ds_read_b128 v[214:217], v155 offset:49152
	ds_read_b128 v[218:221], v155 offset:50176
	ds_read_b128 v[222:225], v155 offset:51200
	ds_read_b128 v[226:229], v155 offset:52224
	ds_read_b128 v[230:233], v155 offset:53248
	ds_read_b128 v[234:237], v155 offset:54272
	ds_read_b128 v[238:241], v155 offset:55296
	ds_read_b128 v[242:245], v155 offset:56320
	global_load_lds_dwordx4 v130, s[60:61]
	s_add_i32 m0, s21, 0x2000
	s_add_u32 s42, s42, 0x40080
	s_addc_u32 s43, s43, 0
	s_add_i32 s21, s35, s3
	global_load_lds_dwordx4 v142, s[60:61]
	s_mov_b32 m0, s21
	s_nop 0
	global_load_lds_dwordx4 v130, s[42:43]
	s_add_i32 m0, s21, 0x2000
	s_nop 0
	global_load_lds_dwordx4 v142, s[42:43]
	s_mov_b32 m0, s0
	s_nop 0
	global_load_lds_dwordx4 v146, s[62:63]
	s_mov_b32 m0, s1
	s_nop 0
	global_load_lds_dwordx4 v144, s[62:63]
	s_waitcnt vmcnt(8)
	s_waitcnt lgkmcnt(0)
	s_barrier
	s_setprio 1
	s_waitcnt lgkmcnt(0)
	v_mfma_f32_16x16x32_bf16 v[60:63], v[182:185], v[214:217], v[60:63]
	v_mfma_f32_16x16x32_bf16 v[56:59], v[190:193], v[214:217], v[56:59]
	v_mfma_f32_16x16x32_bf16 v[52:55], v[182:185], v[222:225], v[52:55]
	v_mfma_f32_16x16x32_bf16 v[48:51], v[190:193], v[222:225], v[48:51]
	v_mfma_f32_16x16x32_bf16 v[36:39], v[182:185], v[230:233], v[36:39]
	v_mfma_f32_16x16x32_bf16 v[32:35], v[190:193], v[230:233], v[32:35]
	v_mfma_f32_16x16x32_bf16 v[20:23], v[182:185], v[238:241], v[20:23]
	v_mfma_f32_16x16x32_bf16 v[16:19], v[190:193], v[238:241], v[16:19]
	v_mfma_f32_16x16x32_bf16 v[60:63], v[186:189], v[218:221], v[60:63]
	v_mfma_f32_16x16x32_bf16 v[56:59], v[194:197], v[218:221], v[56:59]
	v_mfma_f32_16x16x32_bf16 v[52:55], v[186:189], v[226:229], v[52:55]
	v_mfma_f32_16x16x32_bf16 v[48:51], v[194:197], v[226:229], v[48:51]
	v_mfma_f32_16x16x32_bf16 v[36:39], v[186:189], v[234:237], v[36:39]
	v_mfma_f32_16x16x32_bf16 v[32:35], v[194:197], v[234:237], v[32:35]
	v_mfma_f32_16x16x32_bf16 v[20:23], v[186:189], v[242:245], v[20:23]
	v_mfma_f32_16x16x32_bf16 v[16:19], v[194:197], v[242:245], v[16:19]
	s_setprio 0
	s_setprio 1
	v_mfma_f32_16x16x32_bf16 v[44:47], v[198:201], v[214:217], v[44:47]
	v_mfma_f32_16x16x32_bf16 v[40:43], v[206:209], v[214:217], v[40:43]
	v_mfma_f32_16x16x32_bf16 v[28:31], v[198:201], v[222:225], v[28:31]
	v_mfma_f32_16x16x32_bf16 v[24:27], v[206:209], v[222:225], v[24:27]
	v_mfma_f32_16x16x32_bf16 v[12:15], v[198:201], v[230:233], v[12:15]
	v_mfma_f32_16x16x32_bf16 v[8:11], v[206:209], v[230:233], v[8:11]
	v_mfma_f32_16x16x32_bf16 v[4:7], v[198:201], v[238:241], v[4:7]
	v_mfma_f32_16x16x32_bf16 v[0:3], v[206:209], v[238:241], v[0:3]
	v_mfma_f32_16x16x32_bf16 v[44:47], v[202:205], v[218:221], v[44:47]
	v_mfma_f32_16x16x32_bf16 v[40:43], v[210:213], v[218:221], v[40:43]
	v_mfma_f32_16x16x32_bf16 v[28:31], v[202:205], v[226:229], v[28:31]
	v_mfma_f32_16x16x32_bf16 v[24:27], v[210:213], v[226:229], v[24:27]
	v_mfma_f32_16x16x32_bf16 v[12:15], v[202:205], v[234:237], v[12:15]
	v_mfma_f32_16x16x32_bf16 v[8:11], v[210:213], v[234:237], v[8:11]
	v_mfma_f32_16x16x32_bf16 v[4:7], v[202:205], v[242:245], v[4:7]
	v_mfma_f32_16x16x32_bf16 v[0:3], v[210:213], v[242:245], v[0:3]
	s_setprio 0
	s_barrier
	s_add_i32 s46, s46, 2
	s_add_u32 s40, s40, 0x100
	s_addc_u32 s41, s41, 0
	s_add_u32 s38, s38, 0x100
	s_addc_u32 s39, s39, 0
	s_cmp_gt_u32 s46, 13
	s_cbranch_scc1 .Lpeel_done_872

.LBB0_1271:
	s_add_i32 s11, s48, -2
	s_add_u32 s29, s42, 0x100
	s_addc_u32 s49, s43, 0
	s_mov_b32 s44, 0
	v_add_u32_e32 v156, s22, v153
	ds_read_b128 v[182:185], v156
	ds_read_b128 v[186:189], v156 offset:1024
	ds_read_b128 v[190:193], v156 offset:2048
	ds_read_b128 v[194:197], v156 offset:3072
	v_add_u32_e32 v156, s23, v153
	ds_read_b128 v[198:201], v156
	ds_read_b128 v[202:205], v156 offset:1024
	ds_read_b128 v[206:209], v156 offset:2048
	ds_read_b128 v[210:213], v156 offset:3072
	s_add_i32 s50, s44, 2
	s_add_u32 s42, s40, 0x100
	s_addc_u32 s43, s41, 0
	s_cmp_eq_u32 s11, s44
	s_cselect_b32 s44, s36, s29
	s_cselect_b32 s47, s17, s43
	s_cselect_b32 s46, s16, s42
	s_cselect_b32 s45, s37, s49
	s_add_i32 m0, s12, 0xc000
	ds_read_b128 v[214:217], v155
	ds_read_b128 v[218:221], v155 offset:1024
	ds_read_b128 v[222:225], v155 offset:2048
	ds_read_b128 v[226:229], v155 offset:3072
	ds_read_b128 v[230:233], v155 offset:4096
	ds_read_b128 v[234:237], v155 offset:5120
	ds_read_b128 v[238:241], v155 offset:6144
	ds_read_b128 v[242:245], v155 offset:7168
	global_load_lds_dwordx4 v148, s[40:41]
	s_add_i32 m0, s12, 0xe000
	s_nop 0
	global_load_lds_dwordx4 v150, s[40:41]
	s_waitcnt vmcnt(8)
	s_waitcnt lgkmcnt(0)
	s_barrier
	s_setprio 1
	s_waitcnt lgkmcnt(0)
	v_mfma_f32_16x16x32_bf16 v[124:127], v[182:185], v[214:217], 0
	v_mfma_f32_16x16x32_bf16 v[120:123], v[190:193], v[214:217], 0
	v_mfma_f32_16x16x32_bf16 v[116:119], v[182:185], v[222:225], 0
	v_mfma_f32_16x16x32_bf16 v[112:115], v[190:193], v[222:225], 0
	v_mfma_f32_16x16x32_bf16 v[100:103], v[182:185], v[230:233], 0
	v_mfma_f32_16x16x32_bf16 v[96:99], v[190:193], v[230:233], 0
	v_mfma_f32_16x16x32_bf16 v[84:87], v[182:185], v[238:241], 0
	v_mfma_f32_16x16x32_bf16 v[80:83], v[190:193], v[238:241], 0
	v_mfma_f32_16x16x32_bf16 v[124:127], v[186:189], v[218:221], v[124:127]
	v_mfma_f32_16x16x32_bf16 v[120:123], v[194:197], v[218:221], v[120:123]
	v_mfma_f32_16x16x32_bf16 v[116:119], v[186:189], v[226:229], v[116:119]
	v_mfma_f32_16x16x32_bf16 v[112:115], v[194:197], v[226:229], v[112:115]
	v_mfma_f32_16x16x32_bf16 v[100:103], v[186:189], v[234:237], v[100:103]
	v_mfma_f32_16x16x32_bf16 v[96:99], v[194:197], v[234:237], v[96:99]
	v_mfma_f32_16x16x32_bf16 v[84:87], v[186:189], v[242:245], v[84:87]
	v_mfma_f32_16x16x32_bf16 v[80:83], v[194:197], v[242:245], v[80:83]
	s_setprio 0
	s_setprio 1
	v_mfma_f32_16x16x32_bf16 v[108:111], v[198:201], v[214:217], 0
	v_mfma_f32_16x16x32_bf16 v[104:107], v[206:209], v[214:217], 0
	v_mfma_f32_16x16x32_bf16 v[92:95], v[198:201], v[222:225], 0
	v_mfma_f32_16x16x32_bf16 v[88:91], v[206:209], v[222:225], 0
	v_mfma_f32_16x16x32_bf16 v[76:79], v[198:201], v[230:233], 0
	v_mfma_f32_16x16x32_bf16 v[72:75], v[206:209], v[230:233], 0
	v_mfma_f32_16x16x32_bf16 v[68:71], v[198:201], v[238:241], 0
	v_mfma_f32_16x16x32_bf16 v[64:67], v[206:209], v[238:241], 0
	v_mfma_f32_16x16x32_bf16 v[108:111], v[202:205], v[218:221], v[108:111]
	v_mfma_f32_16x16x32_bf16 v[104:107], v[210:213], v[218:221], v[104:107]
	v_mfma_f32_16x16x32_bf16 v[92:95], v[202:205], v[226:229], v[92:95]
	v_mfma_f32_16x16x32_bf16 v[88:91], v[210:213], v[226:229], v[88:91]
	v_mfma_f32_16x16x32_bf16 v[76:79], v[202:205], v[234:237], v[76:79]
	v_mfma_f32_16x16x32_bf16 v[72:75], v[210:213], v[234:237], v[72:75]
	v_mfma_f32_16x16x32_bf16 v[68:71], v[202:205], v[242:245], v[68:71]
	v_mfma_f32_16x16x32_bf16 v[64:67], v[210:213], v[242:245], v[64:67]
	s_setprio 0
	s_barrier
	s_add_u32 s60, s44, 0x80
	s_addc_u32 s61, s45, 0
	s_add_u32 s62, s46, 0x80
	s_addc_u32 s63, s47, 0
	s_add_i32 s21, s22, s3
	s_mov_b32 m0, s21
	ds_read_b128 v[214:217], v155 offset:16384
	ds_read_b128 v[218:221], v155 offset:17408
	ds_read_b128 v[222:225], v155 offset:18432
	ds_read_b128 v[226:229], v155 offset:19456
	ds_read_b128 v[230:233], v155 offset:20480
	ds_read_b128 v[234:237], v155 offset:21504
	ds_read_b128 v[238:241], v155 offset:22528
	ds_read_b128 v[242:245], v155 offset:23552
	global_load_lds_dwordx4 v130, s[44:45]
	s_add_i32 m0, s21, 0x2000
	s_add_u32 s40, s44, 0x40000
	s_addc_u32 s41, s45, 0
	s_add_i32 s21, s23, s3
	global_load_lds_dwordx4 v146, s[44:45]
	s_mov_b32 m0, s21
	s_nop 0
	global_load_lds_dwordx4 v130, s[40:41]
	s_add_i32 m0, s21, 0x2000
	s_nop 0
	global_load_lds_dwordx4 v146, s[40:41]
	s_mov_b32 m0, s12
	s_nop 0
	global_load_lds_dwordx4 v142, s[46:47]
	s_mov_b32 m0, s13
	s_nop 0
	global_load_lds_dwordx4 v144, s[46:47]
	s_waitcnt vmcnt(8)
	s_waitcnt lgkmcnt(0)
	s_barrier
	s_setprio 1
	s_waitcnt lgkmcnt(0)
	v_mfma_f32_16x16x32_bf16 v[60:63], v[182:185], v[214:217], 0
	v_mfma_f32_16x16x32_bf16 v[56:59], v[190:193], v[214:217], 0
	v_mfma_f32_16x16x32_bf16 v[52:55], v[182:185], v[222:225], 0
	v_mfma_f32_16x16x32_bf16 v[48:51], v[190:193], v[222:225], 0
	v_mfma_f32_16x16x32_bf16 v[36:39], v[182:185], v[230:233], 0
	v_mfma_f32_16x16x32_bf16 v[32:35], v[190:193], v[230:233], 0
	v_mfma_f32_16x16x32_bf16 v[20:23], v[182:185], v[238:241], 0
	v_mfma_f32_16x16x32_bf16 v[16:19], v[190:193], v[238:241], 0
	v_mfma_f32_16x16x32_bf16 v[60:63], v[186:189], v[218:221], v[60:63]
	v_mfma_f32_16x16x32_bf16 v[56:59], v[194:197], v[218:221], v[56:59]
	v_mfma_f32_16x16x32_bf16 v[52:55], v[186:189], v[226:229], v[52:55]
	v_mfma_f32_16x16x32_bf16 v[48:51], v[194:197], v[226:229], v[48:51]
	v_mfma_f32_16x16x32_bf16 v[36:39], v[186:189], v[234:237], v[36:39]
	v_mfma_f32_16x16x32_bf16 v[32:35], v[194:197], v[234:237], v[32:35]
	v_mfma_f32_16x16x32_bf16 v[20:23], v[186:189], v[242:245], v[20:23]
	v_mfma_f32_16x16x32_bf16 v[16:19], v[194:197], v[242:245], v[16:19]
	s_setprio 0
	s_setprio 1
	v_mfma_f32_16x16x32_bf16 v[44:47], v[198:201], v[214:217], 0
	v_mfma_f32_16x16x32_bf16 v[40:43], v[206:209], v[214:217], 0
	v_mfma_f32_16x16x32_bf16 v[28:31], v[198:201], v[222:225], 0
	v_mfma_f32_16x16x32_bf16 v[24:27], v[206:209], v[222:225], 0
	v_mfma_f32_16x16x32_bf16 v[12:15], v[198:201], v[230:233], 0
	v_mfma_f32_16x16x32_bf16 v[8:11], v[206:209], v[230:233], 0
	v_mfma_f32_16x16x32_bf16 v[4:7], v[198:201], v[238:241], 0
	v_mfma_f32_16x16x32_bf16 v[0:3], v[206:209], v[238:241], 0
	v_mfma_f32_16x16x32_bf16 v[44:47], v[202:205], v[218:221], v[44:47]
	v_mfma_f32_16x16x32_bf16 v[40:43], v[210:213], v[218:221], v[40:43]
	v_mfma_f32_16x16x32_bf16 v[28:31], v[202:205], v[226:229], v[28:31]
	v_mfma_f32_16x16x32_bf16 v[24:27], v[210:213], v[226:229], v[24:27]
	v_mfma_f32_16x16x32_bf16 v[12:15], v[202:205], v[234:237], v[12:15]
	v_mfma_f32_16x16x32_bf16 v[8:11], v[210:213], v[234:237], v[8:11]
	v_mfma_f32_16x16x32_bf16 v[4:7], v[202:205], v[242:245], v[4:7]
	v_mfma_f32_16x16x32_bf16 v[0:3], v[210:213], v[242:245], v[0:3]
	s_setprio 0
	s_barrier
	v_add_u32_e32 v181, s34, v153
	ds_read_b128 v[182:185], v181
	ds_read_b128 v[186:189], v181 offset:1024
	ds_read_b128 v[190:193], v181 offset:2048
	ds_read_b128 v[194:197], v181 offset:3072
	v_add_u32_e32 v181, s35, v153
	ds_read_b128 v[198:201], v181
	ds_read_b128 v[202:205], v181 offset:1024
	ds_read_b128 v[206:209], v181 offset:2048
	ds_read_b128 v[210:213], v181 offset:3072
	s_add_u32 s40, s46, 0xb0000
	s_addc_u32 s41, s47, 0
	s_mov_b32 m0, s18
	ds_read_b128 v[214:217], v155 offset:32768
	ds_read_b128 v[218:221], v155 offset:33792
	ds_read_b128 v[222:225], v155 offset:34816
	ds_read_b128 v[226:229], v155 offset:35840
	ds_read_b128 v[230:233], v155 offset:36864
	ds_read_b128 v[234:237], v155 offset:37888
	ds_read_b128 v[238:241], v155 offset:38912
	ds_read_b128 v[242:245], v155 offset:39936
	global_load_lds_dwordx4 v142, s[40:41]
	s_mov_b32 m0, s19
	s_nop 0
	global_load_lds_dwordx4 v144, s[40:41]
	s_waitcnt vmcnt(8)
	s_waitcnt lgkmcnt(0)
	s_barrier
	s_setprio 1
	s_waitcnt lgkmcnt(0)
	v_mfma_f32_16x16x32_bf16 v[124:127], v[182:185], v[214:217], v[124:127]
	v_mfma_f32_16x16x32_bf16 v[120:123], v[190:193], v[214:217], v[120:123]
	v_mfma_f32_16x16x32_bf16 v[116:119], v[182:185], v[222:225], v[116:119]
	v_mfma_f32_16x16x32_bf16 v[112:115], v[190:193], v[222:225], v[112:115]
	v_mfma_f32_16x16x32_bf16 v[100:103], v[182:185], v[230:233], v[100:103]
	v_mfma_f32_16x16x32_bf16 v[96:99], v[190:193], v[230:233], v[96:99]
	v_mfma_f32_16x16x32_bf16 v[84:87], v[182:185], v[238:241], v[84:87]
	v_mfma_f32_16x16x32_bf16 v[80:83], v[190:193], v[238:241], v[80:83]
	v_mfma_f32_16x16x32_bf16 v[124:127], v[186:189], v[218:221], v[124:127]
	v_mfma_f32_16x16x32_bf16 v[120:123], v[194:197], v[218:221], v[120:123]
	v_mfma_f32_16x16x32_bf16 v[116:119], v[186:189], v[226:229], v[116:119]
	v_mfma_f32_16x16x32_bf16 v[112:115], v[194:197], v[226:229], v[112:115]
	v_mfma_f32_16x16x32_bf16 v[100:103], v[186:189], v[234:237], v[100:103]
	v_mfma_f32_16x16x32_bf16 v[96:99], v[194:197], v[234:237], v[96:99]
	v_mfma_f32_16x16x32_bf16 v[84:87], v[186:189], v[242:245], v[84:87]
	v_mfma_f32_16x16x32_bf16 v[80:83], v[194:197], v[242:245], v[80:83]
	s_setprio 0
	s_setprio 1
	v_mfma_f32_16x16x32_bf16 v[108:111], v[198:201], v[214:217], v[108:111]
	v_mfma_f32_16x16x32_bf16 v[104:107], v[206:209], v[214:217], v[104:107]
	v_mfma_f32_16x16x32_bf16 v[92:95], v[198:201], v[222:225], v[92:95]
	v_mfma_f32_16x16x32_bf16 v[88:91], v[206:209], v[222:225], v[88:91]
	v_mfma_f32_16x16x32_bf16 v[76:79], v[198:201], v[230:233], v[76:79]
	v_mfma_f32_16x16x32_bf16 v[72:75], v[206:209], v[230:233], v[72:75]
	v_mfma_f32_16x16x32_bf16 v[68:71], v[198:201], v[238:241], v[68:71]
	v_mfma_f32_16x16x32_bf16 v[64:67], v[206:209], v[238:241], v[64:67]
	v_mfma_f32_16x16x32_bf16 v[108:111], v[202:205], v[218:221], v[108:111]
	v_mfma_f32_16x16x32_bf16 v[104:107], v[210:213], v[218:221], v[104:107]
	v_mfma_f32_16x16x32_bf16 v[92:95], v[202:205], v[226:229], v[92:95]
	v_mfma_f32_16x16x32_bf16 v[88:91], v[210:213], v[226:229], v[88:91]
	v_mfma_f32_16x16x32_bf16 v[76:79], v[202:205], v[234:237], v[76:79]
	v_mfma_f32_16x16x32_bf16 v[72:75], v[210:213], v[234:237], v[72:75]
	v_mfma_f32_16x16x32_bf16 v[68:71], v[202:205], v[242:245], v[68:71]
	v_mfma_f32_16x16x32_bf16 v[64:67], v[210:213], v[242:245], v[64:67]
	s_setprio 0
	s_barrier
	s_add_i32 s21, s34, s3
	s_mov_b32 m0, s21
	ds_read_b128 v[214:217], v155 offset:49152
	ds_read_b128 v[218:221], v155 offset:50176
	ds_read_b128 v[222:225], v155 offset:51200
	ds_read_b128 v[226:229], v155 offset:52224
	ds_read_b128 v[230:233], v155 offset:53248
	ds_read_b128 v[234:237], v155 offset:54272
	ds_read_b128 v[238:241], v155 offset:55296
	ds_read_b128 v[242:245], v155 offset:56320
	global_load_lds_dwordx4 v130, s[60:61]
	s_add_i32 m0, s21, 0x2000
	s_add_u32 s40, s44, 0x40080
	s_addc_u32 s41, s45, 0
	s_add_i32 s21, s35, s3
	global_load_lds_dwordx4 v146, s[60:61]
	s_mov_b32 m0, s21
	s_nop 0
	global_load_lds_dwordx4 v130, s[40:41]
	s_add_i32 m0, s21, 0x2000
	s_nop 0
	global_load_lds_dwordx4 v146, s[40:41]
	s_mov_b32 m0, s20
	s_nop 0
	global_load_lds_dwordx4 v142, s[62:63]
	s_mov_b32 m0, s26
	s_nop 0
	global_load_lds_dwordx4 v144, s[62:63]
	s_waitcnt vmcnt(8)
	s_waitcnt lgkmcnt(0)
	s_barrier
	s_setprio 1
	s_waitcnt lgkmcnt(0)
	v_mfma_f32_16x16x32_bf16 v[60:63], v[182:185], v[214:217], v[60:63]
	v_mfma_f32_16x16x32_bf16 v[56:59], v[190:193], v[214:217], v[56:59]
	v_mfma_f32_16x16x32_bf16 v[52:55], v[182:185], v[222:225], v[52:55]
	v_mfma_f32_16x16x32_bf16 v[48:51], v[190:193], v[222:225], v[48:51]
	v_mfma_f32_16x16x32_bf16 v[36:39], v[182:185], v[230:233], v[36:39]
	v_mfma_f32_16x16x32_bf16 v[32:35], v[190:193], v[230:233], v[32:35]
	v_mfma_f32_16x16x32_bf16 v[20:23], v[182:185], v[238:241], v[20:23]
	v_mfma_f32_16x16x32_bf16 v[16:19], v[190:193], v[238:241], v[16:19]
	v_mfma_f32_16x16x32_bf16 v[60:63], v[186:189], v[218:221], v[60:63]
	v_mfma_f32_16x16x32_bf16 v[56:59], v[194:197], v[218:221], v[56:59]
	v_mfma_f32_16x16x32_bf16 v[52:55], v[186:189], v[226:229], v[52:55]
	v_mfma_f32_16x16x32_bf16 v[48:51], v[194:197], v[226:229], v[48:51]
	v_mfma_f32_16x16x32_bf16 v[36:39], v[186:189], v[234:237], v[36:39]
	v_mfma_f32_16x16x32_bf16 v[32:35], v[194:197], v[234:237], v[32:35]
	v_mfma_f32_16x16x32_bf16 v[20:23], v[186:189], v[242:245], v[20:23]
	v_mfma_f32_16x16x32_bf16 v[16:19], v[194:197], v[242:245], v[16:19]
	s_setprio 0
	s_setprio 1
	v_mfma_f32_16x16x32_bf16 v[44:47], v[198:201], v[214:217], v[44:47]
	v_mfma_f32_16x16x32_bf16 v[40:43], v[206:209], v[214:217], v[40:43]
	v_mfma_f32_16x16x32_bf16 v[28:31], v[198:201], v[222:225], v[28:31]
	v_mfma_f32_16x16x32_bf16 v[24:27], v[206:209], v[222:225], v[24:27]
	v_mfma_f32_16x16x32_bf16 v[12:15], v[198:201], v[230:233], v[12:15]
	v_mfma_f32_16x16x32_bf16 v[8:11], v[206:209], v[230:233], v[8:11]
	v_mfma_f32_16x16x32_bf16 v[4:7], v[198:201], v[238:241], v[4:7]
	v_mfma_f32_16x16x32_bf16 v[0:3], v[206:209], v[238:241], v[0:3]
	v_mfma_f32_16x16x32_bf16 v[44:47], v[202:205], v[218:221], v[44:47]
	v_mfma_f32_16x16x32_bf16 v[40:43], v[210:213], v[218:221], v[40:43]
	v_mfma_f32_16x16x32_bf16 v[28:31], v[202:205], v[226:229], v[28:31]
	v_mfma_f32_16x16x32_bf16 v[24:27], v[210:213], v[226:229], v[24:27]
	v_mfma_f32_16x16x32_bf16 v[12:15], v[202:205], v[234:237], v[12:15]
	v_mfma_f32_16x16x32_bf16 v[8:11], v[210:213], v[234:237], v[8:11]
	v_mfma_f32_16x16x32_bf16 v[4:7], v[202:205], v[242:245], v[4:7]
	v_mfma_f32_16x16x32_bf16 v[0:3], v[210:213], v[242:245], v[0:3]
	s_setprio 0
	s_barrier
	s_add_u32 s29, s29, 0x100
	s_addc_u32 s49, s49, 0
	s_cmp_ge_i32 s50, s48
	s_mov_b64 s[40:41], s[42:43]
	s_mov_b32 s44, s50
	s_cbranch_scc1 .Lpeel_done_1272
.LBB0_1272:
	v_add_u32_e32 v156, s22, v153
	ds_read_b128 v[182:185], v156
	ds_read_b128 v[186:189], v156 offset:1024
	ds_read_b128 v[190:193], v156 offset:2048
	ds_read_b128 v[194:197], v156 offset:3072
	v_add_u32_e32 v156, s23, v153
	ds_read_b128 v[198:201], v156
	ds_read_b128 v[202:205], v156 offset:1024
	ds_read_b128 v[206:209], v156 offset:2048
	ds_read_b128 v[210:213], v156 offset:3072
	s_add_i32 s50, s44, 2
	s_add_u32 s42, s40, 0x100
	s_addc_u32 s43, s41, 0
	s_cmp_eq_u32 s11, s44
	s_cselect_b32 s44, s36, s29
	s_cselect_b32 s47, s17, s43
	s_cselect_b32 s46, s16, s42
	s_cselect_b32 s45, s37, s49
	s_add_i32 m0, s12, 0xc000
	ds_read_b128 v[214:217], v155
	ds_read_b128 v[218:221], v155 offset:1024
	ds_read_b128 v[222:225], v155 offset:2048
	ds_read_b128 v[226:229], v155 offset:3072
	ds_read_b128 v[230:233], v155 offset:4096
	ds_read_b128 v[234:237], v155 offset:5120
	ds_read_b128 v[238:241], v155 offset:6144
	ds_read_b128 v[242:245], v155 offset:7168
	global_load_lds_dwordx4 v148, s[40:41]
	s_add_i32 m0, s12, 0xe000
	s_nop 0
	global_load_lds_dwordx4 v150, s[40:41]
	s_waitcnt vmcnt(8)
	s_waitcnt lgkmcnt(0)
	s_barrier
	s_setprio 1
	s_waitcnt lgkmcnt(0)
	v_mfma_f32_16x16x32_bf16 v[124:127], v[182:185], v[214:217], v[124:127]
	v_mfma_f32_16x16x32_bf16 v[120:123], v[190:193], v[214:217], v[120:123]
	v_mfma_f32_16x16x32_bf16 v[116:119], v[182:185], v[222:225], v[116:119]
	v_mfma_f32_16x16x32_bf16 v[112:115], v[190:193], v[222:225], v[112:115]
	v_mfma_f32_16x16x32_bf16 v[100:103], v[182:185], v[230:233], v[100:103]
	v_mfma_f32_16x16x32_bf16 v[96:99], v[190:193], v[230:233], v[96:99]
	v_mfma_f32_16x16x32_bf16 v[84:87], v[182:185], v[238:241], v[84:87]
	v_mfma_f32_16x16x32_bf16 v[80:83], v[190:193], v[238:241], v[80:83]
	v_mfma_f32_16x16x32_bf16 v[124:127], v[186:189], v[218:221], v[124:127]
	v_mfma_f32_16x16x32_bf16 v[120:123], v[194:197], v[218:221], v[120:123]
	v_mfma_f32_16x16x32_bf16 v[116:119], v[186:189], v[226:229], v[116:119]
	v_mfma_f32_16x16x32_bf16 v[112:115], v[194:197], v[226:229], v[112:115]
	v_mfma_f32_16x16x32_bf16 v[100:103], v[186:189], v[234:237], v[100:103]
	v_mfma_f32_16x16x32_bf16 v[96:99], v[194:197], v[234:237], v[96:99]
	v_mfma_f32_16x16x32_bf16 v[84:87], v[186:189], v[242:245], v[84:87]
	v_mfma_f32_16x16x32_bf16 v[80:83], v[194:197], v[242:245], v[80:83]
	s_setprio 0
	s_setprio 1
	v_mfma_f32_16x16x32_bf16 v[108:111], v[198:201], v[214:217], v[108:111]
	v_mfma_f32_16x16x32_bf16 v[104:107], v[206:209], v[214:217], v[104:107]
	v_mfma_f32_16x16x32_bf16 v[92:95], v[198:201], v[222:225], v[92:95]
	v_mfma_f32_16x16x32_bf16 v[88:91], v[206:209], v[222:225], v[88:91]
	v_mfma_f32_16x16x32_bf16 v[76:79], v[198:201], v[230:233], v[76:79]
	v_mfma_f32_16x16x32_bf16 v[72:75], v[206:209], v[230:233], v[72:75]
	v_mfma_f32_16x16x32_bf16 v[68:71], v[198:201], v[238:241], v[68:71]
	v_mfma_f32_16x16x32_bf16 v[64:67], v[206:209], v[238:241], v[64:67]
	v_mfma_f32_16x16x32_bf16 v[108:111], v[202:205], v[218:221], v[108:111]
	v_mfma_f32_16x16x32_bf16 v[104:107], v[210:213], v[218:221], v[104:107]
	v_mfma_f32_16x16x32_bf16 v[92:95], v[202:205], v[226:229], v[92:95]
	v_mfma_f32_16x16x32_bf16 v[88:91], v[210:213], v[226:229], v[88:91]
	v_mfma_f32_16x16x32_bf16 v[76:79], v[202:205], v[234:237], v[76:79]
	v_mfma_f32_16x16x32_bf16 v[72:75], v[210:213], v[234:237], v[72:75]
	v_mfma_f32_16x16x32_bf16 v[68:71], v[202:205], v[242:245], v[68:71]
	v_mfma_f32_16x16x32_bf16 v[64:67], v[210:213], v[242:245], v[64:67]
	s_setprio 0
	s_barrier
	s_add_u32 s60, s44, 0x80
	s_addc_u32 s61, s45, 0
	s_add_u32 s62, s46, 0x80
	s_addc_u32 s63, s47, 0
	s_add_i32 s21, s22, s3
	s_mov_b32 m0, s21
	ds_read_b128 v[214:217], v155 offset:16384
	ds_read_b128 v[218:221], v155 offset:17408
	ds_read_b128 v[222:225], v155 offset:18432
	ds_read_b128 v[226:229], v155 offset:19456
	ds_read_b128 v[230:233], v155 offset:20480
	ds_read_b128 v[234:237], v155 offset:21504
	ds_read_b128 v[238:241], v155 offset:22528
	ds_read_b128 v[242:245], v155 offset:23552
	global_load_lds_dwordx4 v130, s[44:45]
	s_add_i32 m0, s21, 0x2000
	s_add_u32 s40, s44, 0x40000
	s_addc_u32 s41, s45, 0
	s_add_i32 s21, s23, s3
	global_load_lds_dwordx4 v146, s[44:45]
	s_mov_b32 m0, s21
	s_nop 0
	global_load_lds_dwordx4 v130, s[40:41]
	s_add_i32 m0, s21, 0x2000
	s_nop 0
	global_load_lds_dwordx4 v146, s[40:41]
	s_mov_b32 m0, s12
	s_nop 0
	global_load_lds_dwordx4 v142, s[46:47]
	s_mov_b32 m0, s13
	s_nop 0
	global_load_lds_dwordx4 v144, s[46:47]
	s_waitcnt vmcnt(8)
	s_waitcnt lgkmcnt(0)
	s_barrier
	s_setprio 1
	s_waitcnt lgkmcnt(0)
	v_mfma_f32_16x16x32_bf16 v[60:63], v[182:185], v[214:217], v[60:63]
	v_mfma_f32_16x16x32_bf16 v[56:59], v[190:193], v[214:217], v[56:59]
	v_mfma_f32_16x16x32_bf16 v[52:55], v[182:185], v[222:225], v[52:55]
	v_mfma_f32_16x16x32_bf16 v[48:51], v[190:193], v[222:225], v[48:51]
	v_mfma_f32_16x16x32_bf16 v[36:39], v[182:185], v[230:233], v[36:39]
	v_mfma_f32_16x16x32_bf16 v[32:35], v[190:193], v[230:233], v[32:35]
	v_mfma_f32_16x16x32_bf16 v[20:23], v[182:185], v[238:241], v[20:23]
	v_mfma_f32_16x16x32_bf16 v[16:19], v[190:193], v[238:241], v[16:19]
	v_mfma_f32_16x16x32_bf16 v[60:63], v[186:189], v[218:221], v[60:63]
	v_mfma_f32_16x16x32_bf16 v[56:59], v[194:197], v[218:221], v[56:59]
	v_mfma_f32_16x16x32_bf16 v[52:55], v[186:189], v[226:229], v[52:55]
	v_mfma_f32_16x16x32_bf16 v[48:51], v[194:197], v[226:229], v[48:51]
	v_mfma_f32_16x16x32_bf16 v[36:39], v[186:189], v[234:237], v[36:39]
	v_mfma_f32_16x16x32_bf16 v[32:35], v[194:197], v[234:237], v[32:35]
	v_mfma_f32_16x16x32_bf16 v[20:23], v[186:189], v[242:245], v[20:23]
	v_mfma_f32_16x16x32_bf16 v[16:19], v[194:197], v[242:245], v[16:19]
	s_setprio 0
	s_setprio 1
	v_mfma_f32_16x16x32_bf16 v[44:47], v[198:201], v[214:217], v[44:47]
	v_mfma_f32_16x16x32_bf16 v[40:43], v[206:209], v[214:217], v[40:43]
	v_mfma_f32_16x16x32_bf16 v[28:31], v[198:201], v[222:225], v[28:31]
	v_mfma_f32_16x16x32_bf16 v[24:27], v[206:209], v[222:225], v[24:27]
	v_mfma_f32_16x16x32_bf16 v[12:15], v[198:201], v[230:233], v[12:15]
	v_mfma_f32_16x16x32_bf16 v[8:11], v[206:209], v[230:233], v[8:11]
	v_mfma_f32_16x16x32_bf16 v[4:7], v[198:201], v[238:241], v[4:7]
	v_mfma_f32_16x16x32_bf16 v[0:3], v[206:209], v[238:241], v[0:3]
	v_mfma_f32_16x16x32_bf16 v[44:47], v[202:205], v[218:221], v[44:47]
	v_mfma_f32_16x16x32_bf16 v[40:43], v[210:213], v[218:221], v[40:43]
	v_mfma_f32_16x16x32_bf16 v[28:31], v[202:205], v[226:229], v[28:31]
	v_mfma_f32_16x16x32_bf16 v[24:27], v[210:213], v[226:229], v[24:27]
	v_mfma_f32_16x16x32_bf16 v[12:15], v[202:205], v[234:237], v[12:15]
	v_mfma_f32_16x16x32_bf16 v[8:11], v[210:213], v[234:237], v[8:11]
	v_mfma_f32_16x16x32_bf16 v[4:7], v[202:205], v[242:245], v[4:7]
	v_mfma_f32_16x16x32_bf16 v[0:3], v[210:213], v[242:245], v[0:3]
	s_setprio 0
	s_barrier
	v_add_u32_e32 v181, s34, v153
	ds_read_b128 v[182:185], v181
	ds_read_b128 v[186:189], v181 offset:1024
	ds_read_b128 v[190:193], v181 offset:2048
	ds_read_b128 v[194:197], v181 offset:3072
	v_add_u32_e32 v181, s35, v153
	ds_read_b128 v[198:201], v181
	ds_read_b128 v[202:205], v181 offset:1024
	ds_read_b128 v[206:209], v181 offset:2048
	ds_read_b128 v[210:213], v181 offset:3072
	s_add_u32 s40, s46, 0xb0000
	s_addc_u32 s41, s47, 0
	s_mov_b32 m0, s18
	ds_read_b128 v[214:217], v155 offset:32768
	ds_read_b128 v[218:221], v155 offset:33792
	ds_read_b128 v[222:225], v155 offset:34816
	ds_read_b128 v[226:229], v155 offset:35840
	ds_read_b128 v[230:233], v155 offset:36864
	ds_read_b128 v[234:237], v155 offset:37888
	ds_read_b128 v[238:241], v155 offset:38912
	ds_read_b128 v[242:245], v155 offset:39936
	global_load_lds_dwordx4 v142, s[40:41]
	s_mov_b32 m0, s19
	s_nop 0
	global_load_lds_dwordx4 v144, s[40:41]
	s_waitcnt vmcnt(8)
	s_waitcnt lgkmcnt(0)
	s_barrier
	s_setprio 1
	s_waitcnt lgkmcnt(0)
	v_mfma_f32_16x16x32_bf16 v[124:127], v[182:185], v[214:217], v[124:127]
	v_mfma_f32_16x16x32_bf16 v[120:123], v[190:193], v[214:217], v[120:123]
	v_mfma_f32_16x16x32_bf16 v[116:119], v[182:185], v[222:225], v[116:119]
	v_mfma_f32_16x16x32_bf16 v[112:115], v[190:193], v[222:225], v[112:115]
	v_mfma_f32_16x16x32_bf16 v[100:103], v[182:185], v[230:233], v[100:103]
	v_mfma_f32_16x16x32_bf16 v[96:99], v[190:193], v[230:233], v[96:99]
	v_mfma_f32_16x16x32_bf16 v[84:87], v[182:185], v[238:241], v[84:87]
	v_mfma_f32_16x16x32_bf16 v[80:83], v[190:193], v[238:241], v[80:83]
	v_mfma_f32_16x16x32_bf16 v[124:127], v[186:189], v[218:221], v[124:127]
	v_mfma_f32_16x16x32_bf16 v[120:123], v[194:197], v[218:221], v[120:123]
	v_mfma_f32_16x16x32_bf16 v[116:119], v[186:189], v[226:229], v[116:119]
	v_mfma_f32_16x16x32_bf16 v[112:115], v[194:197], v[226:229], v[112:115]
	v_mfma_f32_16x16x32_bf16 v[100:103], v[186:189], v[234:237], v[100:103]
	v_mfma_f32_16x16x32_bf16 v[96:99], v[194:197], v[234:237], v[96:99]
	v_mfma_f32_16x16x32_bf16 v[84:87], v[186:189], v[242:245], v[84:87]
	v_mfma_f32_16x16x32_bf16 v[80:83], v[194:197], v[242:245], v[80:83]
	s_setprio 0
	s_setprio 1
	v_mfma_f32_16x16x32_bf16 v[108:111], v[198:201], v[214:217], v[108:111]
	v_mfma_f32_16x16x32_bf16 v[104:107], v[206:209], v[214:217], v[104:107]
	v_mfma_f32_16x16x32_bf16 v[92:95], v[198:201], v[222:225], v[92:95]
	v_mfma_f32_16x16x32_bf16 v[88:91], v[206:209], v[222:225], v[88:91]
	v_mfma_f32_16x16x32_bf16 v[76:79], v[198:201], v[230:233], v[76:79]
	v_mfma_f32_16x16x32_bf16 v[72:75], v[206:209], v[230:233], v[72:75]
	v_mfma_f32_16x16x32_bf16 v[68:71], v[198:201], v[238:241], v[68:71]
	v_mfma_f32_16x16x32_bf16 v[64:67], v[206:209], v[238:241], v[64:67]
	v_mfma_f32_16x16x32_bf16 v[108:111], v[202:205], v[218:221], v[108:111]
	v_mfma_f32_16x16x32_bf16 v[104:107], v[210:213], v[218:221], v[104:107]
	v_mfma_f32_16x16x32_bf16 v[92:95], v[202:205], v[226:229], v[92:95]
	v_mfma_f32_16x16x32_bf16 v[88:91], v[210:213], v[226:229], v[88:91]
	v_mfma_f32_16x16x32_bf16 v[76:79], v[202:205], v[234:237], v[76:79]
	v_mfma_f32_16x16x32_bf16 v[72:75], v[210:213], v[234:237], v[72:75]
	v_mfma_f32_16x16x32_bf16 v[68:71], v[202:205], v[242:245], v[68:71]
	v_mfma_f32_16x16x32_bf16 v[64:67], v[210:213], v[242:245], v[64:67]
	s_setprio 0
	s_barrier
	s_add_i32 s21, s34, s3
	s_mov_b32 m0, s21
	ds_read_b128 v[214:217], v155 offset:49152
	ds_read_b128 v[218:221], v155 offset:50176
	ds_read_b128 v[222:225], v155 offset:51200
	ds_read_b128 v[226:229], v155 offset:52224
	ds_read_b128 v[230:233], v155 offset:53248
	ds_read_b128 v[234:237], v155 offset:54272
	ds_read_b128 v[238:241], v155 offset:55296
	ds_read_b128 v[242:245], v155 offset:56320
	global_load_lds_dwordx4 v130, s[60:61]
	s_add_i32 m0, s21, 0x2000
	s_add_u32 s40, s44, 0x40080
	s_addc_u32 s41, s45, 0
	s_add_i32 s21, s35, s3
	global_load_lds_dwordx4 v146, s[60:61]
	s_mov_b32 m0, s21
	s_nop 0
	global_load_lds_dwordx4 v130, s[40:41]
	s_add_i32 m0, s21, 0x2000
	s_nop 0
	global_load_lds_dwordx4 v146, s[40:41]
	s_mov_b32 m0, s20
	s_nop 0
	global_load_lds_dwordx4 v142, s[62:63]
	s_mov_b32 m0, s26
	s_nop 0
	global_load_lds_dwordx4 v144, s[62:63]
	s_waitcnt vmcnt(8)
	s_waitcnt lgkmcnt(0)
	s_barrier
	s_setprio 1
	s_waitcnt lgkmcnt(0)
	v_mfma_f32_16x16x32_bf16 v[60:63], v[182:185], v[214:217], v[60:63]
	v_mfma_f32_16x16x32_bf16 v[56:59], v[190:193], v[214:217], v[56:59]
	v_mfma_f32_16x16x32_bf16 v[52:55], v[182:185], v[222:225], v[52:55]
	v_mfma_f32_16x16x32_bf16 v[48:51], v[190:193], v[222:225], v[48:51]
	v_mfma_f32_16x16x32_bf16 v[36:39], v[182:185], v[230:233], v[36:39]
	v_mfma_f32_16x16x32_bf16 v[32:35], v[190:193], v[230:233], v[32:35]
	v_mfma_f32_16x16x32_bf16 v[20:23], v[182:185], v[238:241], v[20:23]
	v_mfma_f32_16x16x32_bf16 v[16:19], v[190:193], v[238:241], v[16:19]
	v_mfma_f32_16x16x32_bf16 v[60:63], v[186:189], v[218:221], v[60:63]
	v_mfma_f32_16x16x32_bf16 v[56:59], v[194:197], v[218:221], v[56:59]
	v_mfma_f32_16x16x32_bf16 v[52:55], v[186:189], v[226:229], v[52:55]
	v_mfma_f32_16x16x32_bf16 v[48:51], v[194:197], v[226:229], v[48:51]
	v_mfma_f32_16x16x32_bf16 v[36:39], v[186:189], v[234:237], v[36:39]
	v_mfma_f32_16x16x32_bf16 v[32:35], v[194:197], v[234:237], v[32:35]
	v_mfma_f32_16x16x32_bf16 v[20:23], v[186:189], v[242:245], v[20:23]
	v_mfma_f32_16x16x32_bf16 v[16:19], v[194:197], v[242:245], v[16:19]
	s_setprio 0
	s_setprio 1
	v_mfma_f32_16x16x32_bf16 v[44:47], v[198:201], v[214:217], v[44:47]
	v_mfma_f32_16x16x32_bf16 v[40:43], v[206:209], v[214:217], v[40:43]
	v_mfma_f32_16x16x32_bf16 v[28:31], v[198:201], v[222:225], v[28:31]
	v_mfma_f32_16x16x32_bf16 v[24:27], v[206:209], v[222:225], v[24:27]
	v_mfma_f32_16x16x32_bf16 v[12:15], v[198:201], v[230:233], v[12:15]
	v_mfma_f32_16x16x32_bf16 v[8:11], v[206:209], v[230:233], v[8:11]
	v_mfma_f32_16x16x32_bf16 v[4:7], v[198:201], v[238:241], v[4:7]
	v_mfma_f32_16x16x32_bf16 v[0:3], v[206:209], v[238:241], v[0:3]
	v_mfma_f32_16x16x32_bf16 v[44:47], v[202:205], v[218:221], v[44:47]
	v_mfma_f32_16x16x32_bf16 v[40:43], v[210:213], v[218:221], v[40:43]
	v_mfma_f32_16x16x32_bf16 v[28:31], v[202:205], v[226:229], v[28:31]
	v_mfma_f32_16x16x32_bf16 v[24:27], v[210:213], v[226:229], v[24:27]
	v_mfma_f32_16x16x32_bf16 v[12:15], v[202:205], v[234:237], v[12:15]
	v_mfma_f32_16x16x32_bf16 v[8:11], v[210:213], v[234:237], v[8:11]
	v_mfma_f32_16x16x32_bf16 v[4:7], v[202:205], v[242:245], v[4:7]
	v_mfma_f32_16x16x32_bf16 v[0:3], v[210:213], v[242:245], v[0:3]
	s_setprio 0
	s_barrier
	s_add_u32 s29, s29, 0x100
	s_addc_u32 s49, s49, 0
	s_cmp_ge_i32 s50, s48
	s_mov_b64 s[40:41], s[42:43]
	s_mov_b32 s44, s50
	s_cbranch_scc0 .LBB0_1272

.LBB0_1437:
	s_ashr_i32 s11, s10, 31
	s_lshl_b64 s[12:13], s[10:11], 19
	v_readlane_b32 s14, v252, 27
	v_readlane_b32 s15, v252, 28
	s_add_u32 s28, s14, s12
	s_addc_u32 s29, s15, s13
	s_and_b64 s[12:13], s[40:41], exec
	s_cselect_b32 s3, s29, s17
	s_cselect_b32 s11, s28, s16
	s_ashr_i32 s9, s8, 31
	s_lshl_b64 s[12:13], s[8:9], 19
	s_add_u32 s36, s26, s12
	s_addc_u32 s37, s46, s13
	s_and_b64 s[12:13], s[40:41], exec
	s_cselect_b32 s9, s37, s43
	s_cselect_b32 s12, s36, s42
	s_add_u32 s16, s16, 0x40080
	s_addc_u32 s17, s17, 0
	s_add_u32 s13, s42, 0x100
	s_addc_u32 s14, s43, 0
	s_mov_b32 s15, -2
	v_add_u32_e32 v152, s22, v155
	ds_read_b128 v[182:185], v152
	ds_read_b128 v[186:189], v152 offset:1024
	ds_read_b128 v[190:193], v152 offset:2048
	ds_read_b128 v[194:197], v152 offset:3072
	v_add_u32_e32 v152, s23, v155
	ds_read_b128 v[198:201], v152
	ds_read_b128 v[202:205], v152 offset:1024
	ds_read_b128 v[206:209], v152 offset:2048
	ds_read_b128 v[210:213], v152 offset:3072
	s_add_u32 s18, s16, 0xfffc0080
	s_addc_u32 s19, s17, -1
	s_cmp_eq_u32 s15, 12
	s_cselect_b32 s45, s3, s19
	s_cselect_b32 s44, s11, s18
	s_cselect_b32 s43, s9, s14
	s_cselect_b32 s42, s12, s13
	s_add_i32 m0, s48, 0xc000
	ds_read_b128 v[214:217], v157
	ds_read_b128 v[218:221], v157 offset:1024
	ds_read_b128 v[222:225], v157 offset:2048
	ds_read_b128 v[226:229], v157 offset:3072
	ds_read_b128 v[230:233], v157 offset:4096
	ds_read_b128 v[234:237], v157 offset:5120
	ds_read_b128 v[238:241], v157 offset:6144
	ds_read_b128 v[242:245], v157 offset:7168
	global_load_lds_dwordx4 v148, s[16:17]
	s_add_i32 m0, s48, 0xe000
	s_nop 0
	global_load_lds_dwordx4 v150, s[16:17]
	s_waitcnt vmcnt(8)
	s_waitcnt lgkmcnt(0)
	s_barrier
	s_setprio 1
	s_waitcnt lgkmcnt(0)
	v_mfma_f32_16x16x32_bf16 v[124:127], v[182:185], v[214:217], 0
	v_mfma_f32_16x16x32_bf16 v[120:123], v[190:193], v[214:217], 0
	v_mfma_f32_16x16x32_bf16 v[108:111], v[182:185], v[222:225], 0
	v_mfma_f32_16x16x32_bf16 v[104:107], v[190:193], v[222:225], 0
	v_mfma_f32_16x16x32_bf16 v[92:95], v[182:185], v[230:233], 0
	v_mfma_f32_16x16x32_bf16 v[88:91], v[190:193], v[230:233], 0
	v_mfma_f32_16x16x32_bf16 v[76:79], v[182:185], v[238:241], 0
	v_mfma_f32_16x16x32_bf16 v[72:75], v[190:193], v[238:241], 0
	v_mfma_f32_16x16x32_bf16 v[124:127], v[186:189], v[218:221], v[124:127]
	v_mfma_f32_16x16x32_bf16 v[120:123], v[194:197], v[218:221], v[120:123]
	v_mfma_f32_16x16x32_bf16 v[108:111], v[186:189], v[226:229], v[108:111]
	v_mfma_f32_16x16x32_bf16 v[104:107], v[194:197], v[226:229], v[104:107]
	v_mfma_f32_16x16x32_bf16 v[92:95], v[186:189], v[234:237], v[92:95]
	v_mfma_f32_16x16x32_bf16 v[88:91], v[194:197], v[234:237], v[88:91]
	v_mfma_f32_16x16x32_bf16 v[76:79], v[186:189], v[242:245], v[76:79]
	v_mfma_f32_16x16x32_bf16 v[72:75], v[194:197], v[242:245], v[72:75]
	s_setprio 0
	s_setprio 1
	v_mfma_f32_16x16x32_bf16 v[116:119], v[198:201], v[214:217], 0
	v_mfma_f32_16x16x32_bf16 v[112:115], v[206:209], v[214:217], 0
	v_mfma_f32_16x16x32_bf16 v[100:103], v[198:201], v[222:225], 0
	v_mfma_f32_16x16x32_bf16 v[96:99], v[206:209], v[222:225], 0
	v_mfma_f32_16x16x32_bf16 v[84:87], v[198:201], v[230:233], 0
	v_mfma_f32_16x16x32_bf16 v[80:83], v[206:209], v[230:233], 0
	v_mfma_f32_16x16x32_bf16 v[68:71], v[198:201], v[238:241], 0
	v_mfma_f32_16x16x32_bf16 v[64:67], v[206:209], v[238:241], 0
	v_mfma_f32_16x16x32_bf16 v[116:119], v[202:205], v[218:221], v[116:119]
	v_mfma_f32_16x16x32_bf16 v[112:115], v[210:213], v[218:221], v[112:115]
	v_mfma_f32_16x16x32_bf16 v[100:103], v[202:205], v[226:229], v[100:103]
	v_mfma_f32_16x16x32_bf16 v[96:99], v[210:213], v[226:229], v[96:99]
	v_mfma_f32_16x16x32_bf16 v[84:87], v[202:205], v[234:237], v[84:87]
	v_mfma_f32_16x16x32_bf16 v[80:83], v[210:213], v[234:237], v[80:83]
	v_mfma_f32_16x16x32_bf16 v[68:71], v[202:205], v[242:245], v[68:71]
	v_mfma_f32_16x16x32_bf16 v[64:67], v[210:213], v[242:245], v[64:67]
	s_setprio 0
	s_barrier
	s_add_u32 s60, s42, 0x80
	s_addc_u32 s61, s43, 0
	s_add_u32 s62, s44, 0x80
	s_addc_u32 s63, s45, 0
	s_add_i32 s18, s22, s47
	s_mov_b32 m0, s18
	ds_read_b128 v[214:217], v157 offset:16384
	ds_read_b128 v[218:221], v157 offset:17408
	ds_read_b128 v[222:225], v157 offset:18432
	ds_read_b128 v[226:229], v157 offset:19456
	ds_read_b128 v[230:233], v157 offset:20480
	ds_read_b128 v[234:237], v157 offset:21504
	ds_read_b128 v[238:241], v157 offset:22528
	ds_read_b128 v[242:245], v157 offset:23552
	global_load_lds_dwordx4 v130, s[42:43]
	s_add_i32 m0, s18, 0x2000
	s_add_u32 s18, s42, 0x40000
	s_addc_u32 s19, s43, 0
	s_add_i32 s21, s23, s47
	global_load_lds_dwordx4 v142, s[42:43]
	s_mov_b32 m0, s21
	s_nop 0
	global_load_lds_dwordx4 v130, s[18:19]
	s_add_i32 m0, s21, 0x2000
	s_nop 0
	global_load_lds_dwordx4 v142, s[18:19]
	s_mov_b32 m0, s48
	s_nop 0
	global_load_lds_dwordx4 v146, s[44:45]
	s_mov_b32 m0, s49
	s_nop 0
	global_load_lds_dwordx4 v144, s[44:45]
	s_waitcnt vmcnt(8)
	s_waitcnt lgkmcnt(0)
	s_barrier
	s_setprio 1
	s_waitcnt lgkmcnt(0)
	v_mfma_f32_16x16x32_bf16 v[60:63], v[182:185], v[214:217], 0
	v_mfma_f32_16x16x32_bf16 v[56:59], v[190:193], v[214:217], 0
	v_mfma_f32_16x16x32_bf16 v[44:47], v[182:185], v[222:225], 0
	v_mfma_f32_16x16x32_bf16 v[40:43], v[190:193], v[222:225], 0
	v_mfma_f32_16x16x32_bf16 v[28:31], v[182:185], v[230:233], 0
	v_mfma_f32_16x16x32_bf16 v[24:27], v[190:193], v[230:233], 0
	v_mfma_f32_16x16x32_bf16 v[12:15], v[182:185], v[238:241], 0
	v_mfma_f32_16x16x32_bf16 v[8:11], v[190:193], v[238:241], 0
	v_mfma_f32_16x16x32_bf16 v[60:63], v[186:189], v[218:221], v[60:63]
	v_mfma_f32_16x16x32_bf16 v[56:59], v[194:197], v[218:221], v[56:59]
	v_mfma_f32_16x16x32_bf16 v[44:47], v[186:189], v[226:229], v[44:47]
	v_mfma_f32_16x16x32_bf16 v[40:43], v[194:197], v[226:229], v[40:43]
	v_mfma_f32_16x16x32_bf16 v[28:31], v[186:189], v[234:237], v[28:31]
	v_mfma_f32_16x16x32_bf16 v[24:27], v[194:197], v[234:237], v[24:27]
	v_mfma_f32_16x16x32_bf16 v[12:15], v[186:189], v[242:245], v[12:15]
	v_mfma_f32_16x16x32_bf16 v[8:11], v[194:197], v[242:245], v[8:11]
	s_setprio 0
	s_setprio 1
	v_mfma_f32_16x16x32_bf16 v[52:55], v[198:201], v[214:217], 0
	v_mfma_f32_16x16x32_bf16 v[48:51], v[206:209], v[214:217], 0
	v_mfma_f32_16x16x32_bf16 v[36:39], v[198:201], v[222:225], 0
	v_mfma_f32_16x16x32_bf16 v[32:35], v[206:209], v[222:225], 0
	v_mfma_f32_16x16x32_bf16 v[20:23], v[198:201], v[230:233], 0
	v_mfma_f32_16x16x32_bf16 v[16:19], v[206:209], v[230:233], 0
	v_mfma_f32_16x16x32_bf16 v[4:7], v[198:201], v[238:241], 0
	v_mfma_f32_16x16x32_bf16 v[0:3], v[206:209], v[238:241], 0
	v_mfma_f32_16x16x32_bf16 v[52:55], v[202:205], v[218:221], v[52:55]
	v_mfma_f32_16x16x32_bf16 v[48:51], v[210:213], v[218:221], v[48:51]
	v_mfma_f32_16x16x32_bf16 v[36:39], v[202:205], v[226:229], v[36:39]
	v_mfma_f32_16x16x32_bf16 v[32:35], v[210:213], v[226:229], v[32:35]
	v_mfma_f32_16x16x32_bf16 v[20:23], v[202:205], v[234:237], v[20:23]
	v_mfma_f32_16x16x32_bf16 v[16:19], v[210:213], v[234:237], v[16:19]
	v_mfma_f32_16x16x32_bf16 v[4:7], v[202:205], v[242:245], v[4:7]
	v_mfma_f32_16x16x32_bf16 v[0:3], v[210:213], v[242:245], v[0:3]
	s_setprio 0
	s_barrier
	v_add_u32_e32 v181, s34, v155
	ds_read_b128 v[182:185], v181
	ds_read_b128 v[186:189], v181 offset:1024
	ds_read_b128 v[190:193], v181 offset:2048
	ds_read_b128 v[194:197], v181 offset:3072
	v_add_u32_e32 v181, s35, v155
	ds_read_b128 v[198:201], v181
	ds_read_b128 v[202:205], v181 offset:1024
	ds_read_b128 v[206:209], v181 offset:2048
	ds_read_b128 v[210:213], v181 offset:3072
	s_add_u32 s18, s44, 0x40000
	s_addc_u32 s19, s45, 0
	s_mov_b32 m0, s50
	ds_read_b128 v[214:217], v157 offset:32768
	ds_read_b128 v[218:221], v157 offset:33792
	ds_read_b128 v[222:225], v157 offset:34816
	ds_read_b128 v[226:229], v157 offset:35840
	ds_read_b128 v[230:233], v157 offset:36864
	ds_read_b128 v[234:237], v157 offset:37888
	ds_read_b128 v[238:241], v157 offset:38912
	ds_read_b128 v[242:245], v157 offset:39936
	global_load_lds_dwordx4 v146, s[18:19]
	s_mov_b32 m0, s51
	s_nop 0
	global_load_lds_dwordx4 v144, s[18:19]
	s_waitcnt vmcnt(8)
	s_waitcnt lgkmcnt(0)
	s_barrier
	s_setprio 1
	s_waitcnt lgkmcnt(0)
	v_mfma_f32_16x16x32_bf16 v[124:127], v[182:185], v[214:217], v[124:127]
	v_mfma_f32_16x16x32_bf16 v[120:123], v[190:193], v[214:217], v[120:123]
	v_mfma_f32_16x16x32_bf16 v[108:111], v[182:185], v[222:225], v[108:111]
	v_mfma_f32_16x16x32_bf16 v[104:107], v[190:193], v[222:225], v[104:107]
	v_mfma_f32_16x16x32_bf16 v[92:95], v[182:185], v[230:233], v[92:95]
	v_mfma_f32_16x16x32_bf16 v[88:91], v[190:193], v[230:233], v[88:91]
	v_mfma_f32_16x16x32_bf16 v[76:79], v[182:185], v[238:241], v[76:79]
	v_mfma_f32_16x16x32_bf16 v[72:75], v[190:193], v[238:241], v[72:75]
	v_mfma_f32_16x16x32_bf16 v[124:127], v[186:189], v[218:221], v[124:127]
	v_mfma_f32_16x16x32_bf16 v[120:123], v[194:197], v[218:221], v[120:123]
	v_mfma_f32_16x16x32_bf16 v[108:111], v[186:189], v[226:229], v[108:111]
	v_mfma_f32_16x16x32_bf16 v[104:107], v[194:197], v[226:229], v[104:107]
	v_mfma_f32_16x16x32_bf16 v[92:95], v[186:189], v[234:237], v[92:95]
	v_mfma_f32_16x16x32_bf16 v[88:91], v[194:197], v[234:237], v[88:91]
	v_mfma_f32_16x16x32_bf16 v[76:79], v[186:189], v[242:245], v[76:79]
	v_mfma_f32_16x16x32_bf16 v[72:75], v[194:197], v[242:245], v[72:75]
	s_setprio 0
	s_setprio 1
	v_mfma_f32_16x16x32_bf16 v[116:119], v[198:201], v[214:217], v[116:119]
	v_mfma_f32_16x16x32_bf16 v[112:115], v[206:209], v[214:217], v[112:115]
	v_mfma_f32_16x16x32_bf16 v[100:103], v[198:201], v[222:225], v[100:103]
	v_mfma_f32_16x16x32_bf16 v[96:99], v[206:209], v[222:225], v[96:99]
	v_mfma_f32_16x16x32_bf16 v[84:87], v[198:201], v[230:233], v[84:87]
	v_mfma_f32_16x16x32_bf16 v[80:83], v[206:209], v[230:233], v[80:83]
	v_mfma_f32_16x16x32_bf16 v[68:71], v[198:201], v[238:241], v[68:71]
	v_mfma_f32_16x16x32_bf16 v[64:67], v[206:209], v[238:241], v[64:67]
	v_mfma_f32_16x16x32_bf16 v[116:119], v[202:205], v[218:221], v[116:119]
	v_mfma_f32_16x16x32_bf16 v[112:115], v[210:213], v[218:221], v[112:115]
	v_mfma_f32_16x16x32_bf16 v[100:103], v[202:205], v[226:229], v[100:103]
	v_mfma_f32_16x16x32_bf16 v[96:99], v[210:213], v[226:229], v[96:99]
	v_mfma_f32_16x16x32_bf16 v[84:87], v[202:205], v[234:237], v[84:87]
	v_mfma_f32_16x16x32_bf16 v[80:83], v[210:213], v[234:237], v[80:83]
	v_mfma_f32_16x16x32_bf16 v[68:71], v[202:205], v[242:245], v[68:71]
	v_mfma_f32_16x16x32_bf16 v[64:67], v[210:213], v[242:245], v[64:67]
	s_setprio 0
	s_barrier
	s_add_i32 s18, s34, s47
	s_mov_b32 m0, s18
	ds_read_b128 v[214:217], v157 offset:49152
	ds_read_b128 v[218:221], v157 offset:50176
	ds_read_b128 v[222:225], v157 offset:51200
	ds_read_b128 v[226:229], v157 offset:52224
	ds_read_b128 v[230:233], v157 offset:53248
	ds_read_b128 v[234:237], v157 offset:54272
	ds_read_b128 v[238:241], v157 offset:55296
	ds_read_b128 v[242:245], v157 offset:56320
	global_load_lds_dwordx4 v130, s[60:61]
	s_add_i32 m0, s18, 0x2000
	s_add_u32 s18, s42, 0x40080
	s_addc_u32 s19, s43, 0
	s_add_i32 s21, s35, s47
	global_load_lds_dwordx4 v142, s[60:61]
	s_mov_b32 m0, s21
	s_nop 0
	global_load_lds_dwordx4 v130, s[18:19]
	s_add_i32 m0, s21, 0x2000
	s_nop 0
	global_load_lds_dwordx4 v142, s[18:19]
	s_mov_b32 m0, s52
	s_nop 0
	global_load_lds_dwordx4 v146, s[62:63]
	s_mov_b32 m0, s53
	s_nop 0
	global_load_lds_dwordx4 v144, s[62:63]
	s_waitcnt vmcnt(8)
	s_waitcnt lgkmcnt(0)
	s_barrier
	s_setprio 1
	s_waitcnt lgkmcnt(0)
	v_mfma_f32_16x16x32_bf16 v[60:63], v[182:185], v[214:217], v[60:63]
	v_mfma_f32_16x16x32_bf16 v[56:59], v[190:193], v[214:217], v[56:59]
	v_mfma_f32_16x16x32_bf16 v[44:47], v[182:185], v[222:225], v[44:47]
	v_mfma_f32_16x16x32_bf16 v[40:43], v[190:193], v[222:225], v[40:43]
	v_mfma_f32_16x16x32_bf16 v[28:31], v[182:185], v[230:233], v[28:31]
	v_mfma_f32_16x16x32_bf16 v[24:27], v[190:193], v[230:233], v[24:27]
	v_mfma_f32_16x16x32_bf16 v[12:15], v[182:185], v[238:241], v[12:15]
	v_mfma_f32_16x16x32_bf16 v[8:11], v[190:193], v[238:241], v[8:11]
	v_mfma_f32_16x16x32_bf16 v[60:63], v[186:189], v[218:221], v[60:63]
	v_mfma_f32_16x16x32_bf16 v[56:59], v[194:197], v[218:221], v[56:59]
	v_mfma_f32_16x16x32_bf16 v[44:47], v[186:189], v[226:229], v[44:47]
	v_mfma_f32_16x16x32_bf16 v[40:43], v[194:197], v[226:229], v[40:43]
	v_mfma_f32_16x16x32_bf16 v[28:31], v[186:189], v[234:237], v[28:31]
	v_mfma_f32_16x16x32_bf16 v[24:27], v[194:197], v[234:237], v[24:27]
	v_mfma_f32_16x16x32_bf16 v[12:15], v[186:189], v[242:245], v[12:15]
	v_mfma_f32_16x16x32_bf16 v[8:11], v[194:197], v[242:245], v[8:11]
	s_setprio 0
	s_setprio 1
	v_mfma_f32_16x16x32_bf16 v[52:55], v[198:201], v[214:217], v[52:55]
	v_mfma_f32_16x16x32_bf16 v[48:51], v[206:209], v[214:217], v[48:51]
	v_mfma_f32_16x16x32_bf16 v[36:39], v[198:201], v[222:225], v[36:39]
	v_mfma_f32_16x16x32_bf16 v[32:35], v[206:209], v[222:225], v[32:35]
	v_mfma_f32_16x16x32_bf16 v[20:23], v[198:201], v[230:233], v[20:23]
	v_mfma_f32_16x16x32_bf16 v[16:19], v[206:209], v[230:233], v[16:19]
	v_mfma_f32_16x16x32_bf16 v[4:7], v[198:201], v[238:241], v[4:7]
	v_mfma_f32_16x16x32_bf16 v[0:3], v[206:209], v[238:241], v[0:3]
	v_mfma_f32_16x16x32_bf16 v[52:55], v[202:205], v[218:221], v[52:55]
	v_mfma_f32_16x16x32_bf16 v[48:51], v[210:213], v[218:221], v[48:51]
	v_mfma_f32_16x16x32_bf16 v[36:39], v[202:205], v[226:229], v[36:39]
	v_mfma_f32_16x16x32_bf16 v[32:35], v[210:213], v[226:229], v[32:35]
	v_mfma_f32_16x16x32_bf16 v[20:23], v[202:205], v[234:237], v[20:23]
	v_mfma_f32_16x16x32_bf16 v[16:19], v[210:213], v[234:237], v[16:19]
	v_mfma_f32_16x16x32_bf16 v[4:7], v[202:205], v[242:245], v[4:7]
	v_mfma_f32_16x16x32_bf16 v[0:3], v[210:213], v[242:245], v[0:3]
	s_setprio 0
	s_barrier
	s_add_i32 s15, s15, 2
	s_add_u32 s16, s16, 0x100
	s_addc_u32 s17, s17, 0
	s_add_u32 s13, s13, 0x100
	s_addc_u32 s14, s14, 0
	s_cmp_gt_u32 s15, 13
	s_cbranch_scc1 .Lpeel_done_1438
.LBB0_1438:
	v_add_u32_e32 v152, s22, v155
	ds_read_b128 v[182:185], v152
	ds_read_b128 v[186:189], v152 offset:1024
	ds_read_b128 v[190:193], v152 offset:2048
	ds_read_b128 v[194:197], v152 offset:3072
	v_add_u32_e32 v152, s23, v155
	ds_read_b128 v[198:201], v152
	ds_read_b128 v[202:205], v152 offset:1024
	ds_read_b128 v[206:209], v152 offset:2048
	ds_read_b128 v[210:213], v152 offset:3072
	s_add_u32 s18, s16, 0xfffc0080
	s_addc_u32 s19, s17, -1
	s_cmp_eq_u32 s15, 12
	s_cselect_b32 s45, s3, s19
	s_cselect_b32 s44, s11, s18
	s_cselect_b32 s43, s9, s14
	s_cselect_b32 s42, s12, s13
	s_add_i32 m0, s48, 0xc000
	ds_read_b128 v[214:217], v157
	ds_read_b128 v[218:221], v157 offset:1024
	ds_read_b128 v[222:225], v157 offset:2048
	ds_read_b128 v[226:229], v157 offset:3072
	ds_read_b128 v[230:233], v157 offset:4096
	ds_read_b128 v[234:237], v157 offset:5120
	ds_read_b128 v[238:241], v157 offset:6144
	ds_read_b128 v[242:245], v157 offset:7168
	global_load_lds_dwordx4 v148, s[16:17]
	s_add_i32 m0, s48, 0xe000
	s_nop 0
	global_load_lds_dwordx4 v150, s[16:17]
	s_waitcnt vmcnt(8)
	s_waitcnt lgkmcnt(0)
	s_barrier
	s_setprio 1
	s_waitcnt lgkmcnt(0)
	v_mfma_f32_16x16x32_bf16 v[124:127], v[182:185], v[214:217], v[124:127]
	v_mfma_f32_16x16x32_bf16 v[120:123], v[190:193], v[214:217], v[120:123]
	v_mfma_f32_16x16x32_bf16 v[108:111], v[182:185], v[222:225], v[108:111]
	v_mfma_f32_16x16x32_bf16 v[104:107], v[190:193], v[222:225], v[104:107]
	v_mfma_f32_16x16x32_bf16 v[92:95], v[182:185], v[230:233], v[92:95]
	v_mfma_f32_16x16x32_bf16 v[88:91], v[190:193], v[230:233], v[88:91]
	v_mfma_f32_16x16x32_bf16 v[76:79], v[182:185], v[238:241], v[76:79]
	v_mfma_f32_16x16x32_bf16 v[72:75], v[190:193], v[238:241], v[72:75]
	v_mfma_f32_16x16x32_bf16 v[124:127], v[186:189], v[218:221], v[124:127]
	v_mfma_f32_16x16x32_bf16 v[120:123], v[194:197], v[218:221], v[120:123]
	v_mfma_f32_16x16x32_bf16 v[108:111], v[186:189], v[226:229], v[108:111]
	v_mfma_f32_16x16x32_bf16 v[104:107], v[194:197], v[226:229], v[104:107]
	v_mfma_f32_16x16x32_bf16 v[92:95], v[186:189], v[234:237], v[92:95]
	v_mfma_f32_16x16x32_bf16 v[88:91], v[194:197], v[234:237], v[88:91]
	v_mfma_f32_16x16x32_bf16 v[76:79], v[186:189], v[242:245], v[76:79]
	v_mfma_f32_16x16x32_bf16 v[72:75], v[194:197], v[242:245], v[72:75]
	s_setprio 0
	s_setprio 1
	v_mfma_f32_16x16x32_bf16 v[116:119], v[198:201], v[214:217], v[116:119]
	v_mfma_f32_16x16x32_bf16 v[112:115], v[206:209], v[214:217], v[112:115]
	v_mfma_f32_16x16x32_bf16 v[100:103], v[198:201], v[222:225], v[100:103]
	v_mfma_f32_16x16x32_bf16 v[96:99], v[206:209], v[222:225], v[96:99]
	v_mfma_f32_16x16x32_bf16 v[84:87], v[198:201], v[230:233], v[84:87]
	v_mfma_f32_16x16x32_bf16 v[80:83], v[206:209], v[230:233], v[80:83]
	v_mfma_f32_16x16x32_bf16 v[68:71], v[198:201], v[238:241], v[68:71]
	v_mfma_f32_16x16x32_bf16 v[64:67], v[206:209], v[238:241], v[64:67]
	v_mfma_f32_16x16x32_bf16 v[116:119], v[202:205], v[218:221], v[116:119]
	v_mfma_f32_16x16x32_bf16 v[112:115], v[210:213], v[218:221], v[112:115]
	v_mfma_f32_16x16x32_bf16 v[100:103], v[202:205], v[226:229], v[100:103]
	v_mfma_f32_16x16x32_bf16 v[96:99], v[210:213], v[226:229], v[96:99]
	v_mfma_f32_16x16x32_bf16 v[84:87], v[202:205], v[234:237], v[84:87]
	v_mfma_f32_16x16x32_bf16 v[80:83], v[210:213], v[234:237], v[80:83]
	v_mfma_f32_16x16x32_bf16 v[68:71], v[202:205], v[242:245], v[68:71]
	v_mfma_f32_16x16x32_bf16 v[64:67], v[210:213], v[242:245], v[64:67]
	s_setprio 0
	s_barrier
	s_add_u32 s60, s42, 0x80
	s_addc_u32 s61, s43, 0
	s_add_u32 s62, s44, 0x80
	s_addc_u32 s63, s45, 0
	s_add_i32 s18, s22, s47
	s_mov_b32 m0, s18
	ds_read_b128 v[214:217], v157 offset:16384
	ds_read_b128 v[218:221], v157 offset:17408
	ds_read_b128 v[222:225], v157 offset:18432
	ds_read_b128 v[226:229], v157 offset:19456
	ds_read_b128 v[230:233], v157 offset:20480
	ds_read_b128 v[234:237], v157 offset:21504
	ds_read_b128 v[238:241], v157 offset:22528
	ds_read_b128 v[242:245], v157 offset:23552
	global_load_lds_dwordx4 v130, s[42:43]
	s_add_i32 m0, s18, 0x2000
	s_add_u32 s18, s42, 0x40000
	s_addc_u32 s19, s43, 0
	s_add_i32 s21, s23, s47
	global_load_lds_dwordx4 v142, s[42:43]
	s_mov_b32 m0, s21
	s_nop 0
	global_load_lds_dwordx4 v130, s[18:19]
	s_add_i32 m0, s21, 0x2000
	s_nop 0
	global_load_lds_dwordx4 v142, s[18:19]
	s_mov_b32 m0, s48
	s_nop 0
	global_load_lds_dwordx4 v146, s[44:45]
	s_mov_b32 m0, s49
	s_nop 0
	global_load_lds_dwordx4 v144, s[44:45]
	s_waitcnt vmcnt(8)
	s_waitcnt lgkmcnt(0)
	s_barrier
	s_setprio 1
	s_waitcnt lgkmcnt(0)
	v_mfma_f32_16x16x32_bf16 v[60:63], v[182:185], v[214:217], v[60:63]
	v_mfma_f32_16x16x32_bf16 v[56:59], v[190:193], v[214:217], v[56:59]
	v_mfma_f32_16x16x32_bf16 v[44:47], v[182:185], v[222:225], v[44:47]
	v_mfma_f32_16x16x32_bf16 v[40:43], v[190:193], v[222:225], v[40:43]
	v_mfma_f32_16x16x32_bf16 v[28:31], v[182:185], v[230:233], v[28:31]
	v_mfma_f32_16x16x32_bf16 v[24:27], v[190:193], v[230:233], v[24:27]
	v_mfma_f32_16x16x32_bf16 v[12:15], v[182:185], v[238:241], v[12:15]
	v_mfma_f32_16x16x32_bf16 v[8:11], v[190:193], v[238:241], v[8:11]
	v_mfma_f32_16x16x32_bf16 v[60:63], v[186:189], v[218:221], v[60:63]
	v_mfma_f32_16x16x32_bf16 v[56:59], v[194:197], v[218:221], v[56:59]
	v_mfma_f32_16x16x32_bf16 v[44:47], v[186:189], v[226:229], v[44:47]
	v_mfma_f32_16x16x32_bf16 v[40:43], v[194:197], v[226:229], v[40:43]
	v_mfma_f32_16x16x32_bf16 v[28:31], v[186:189], v[234:237], v[28:31]
	v_mfma_f32_16x16x32_bf16 v[24:27], v[194:197], v[234:237], v[24:27]
	v_mfma_f32_16x16x32_bf16 v[12:15], v[186:189], v[242:245], v[12:15]
	v_mfma_f32_16x16x32_bf16 v[8:11], v[194:197], v[242:245], v[8:11]
	s_setprio 0
	s_setprio 1
	v_mfma_f32_16x16x32_bf16 v[52:55], v[198:201], v[214:217], v[52:55]
	v_mfma_f32_16x16x32_bf16 v[48:51], v[206:209], v[214:217], v[48:51]
	v_mfma_f32_16x16x32_bf16 v[36:39], v[198:201], v[222:225], v[36:39]
	v_mfma_f32_16x16x32_bf16 v[32:35], v[206:209], v[222:225], v[32:35]
	v_mfma_f32_16x16x32_bf16 v[20:23], v[198:201], v[230:233], v[20:23]
	v_mfma_f32_16x16x32_bf16 v[16:19], v[206:209], v[230:233], v[16:19]
	v_mfma_f32_16x16x32_bf16 v[4:7], v[198:201], v[238:241], v[4:7]
	v_mfma_f32_16x16x32_bf16 v[0:3], v[206:209], v[238:241], v[0:3]
	v_mfma_f32_16x16x32_bf16 v[52:55], v[202:205], v[218:221], v[52:55]
	v_mfma_f32_16x16x32_bf16 v[48:51], v[210:213], v[218:221], v[48:51]
	v_mfma_f32_16x16x32_bf16 v[36:39], v[202:205], v[226:229], v[36:39]
	v_mfma_f32_16x16x32_bf16 v[32:35], v[210:213], v[226:229], v[32:35]
	v_mfma_f32_16x16x32_bf16 v[20:23], v[202:205], v[234:237], v[20:23]
	v_mfma_f32_16x16x32_bf16 v[16:19], v[210:213], v[234:237], v[16:19]
	v_mfma_f32_16x16x32_bf16 v[4:7], v[202:205], v[242:245], v[4:7]
	v_mfma_f32_16x16x32_bf16 v[0:3], v[210:213], v[242:245], v[0:3]
	s_setprio 0
	s_barrier
	v_add_u32_e32 v181, s34, v155
	ds_read_b128 v[182:185], v181
	ds_read_b128 v[186:189], v181 offset:1024
	ds_read_b128 v[190:193], v181 offset:2048
	ds_read_b128 v[194:197], v181 offset:3072
	v_add_u32_e32 v181, s35, v155
	ds_read_b128 v[198:201], v181
	ds_read_b128 v[202:205], v181 offset:1024
	ds_read_b128 v[206:209], v181 offset:2048
	ds_read_b128 v[210:213], v181 offset:3072
	s_add_u32 s18, s44, 0x40000
	s_addc_u32 s19, s45, 0
	s_mov_b32 m0, s50
	ds_read_b128 v[214:217], v157 offset:32768
	ds_read_b128 v[218:221], v157 offset:33792
	ds_read_b128 v[222:225], v157 offset:34816
	ds_read_b128 v[226:229], v157 offset:35840
	ds_read_b128 v[230:233], v157 offset:36864
	ds_read_b128 v[234:237], v157 offset:37888
	ds_read_b128 v[238:241], v157 offset:38912
	ds_read_b128 v[242:245], v157 offset:39936
	global_load_lds_dwordx4 v146, s[18:19]
	s_mov_b32 m0, s51
	s_nop 0
	global_load_lds_dwordx4 v144, s[18:19]
	s_waitcnt vmcnt(8)
	s_waitcnt lgkmcnt(0)
	s_barrier
	s_setprio 1
	s_waitcnt lgkmcnt(0)
	v_mfma_f32_16x16x32_bf16 v[124:127], v[182:185], v[214:217], v[124:127]
	v_mfma_f32_16x16x32_bf16 v[120:123], v[190:193], v[214:217], v[120:123]
	v_mfma_f32_16x16x32_bf16 v[108:111], v[182:185], v[222:225], v[108:111]
	v_mfma_f32_16x16x32_bf16 v[104:107], v[190:193], v[222:225], v[104:107]
	v_mfma_f32_16x16x32_bf16 v[92:95], v[182:185], v[230:233], v[92:95]
	v_mfma_f32_16x16x32_bf16 v[88:91], v[190:193], v[230:233], v[88:91]
	v_mfma_f32_16x16x32_bf16 v[76:79], v[182:185], v[238:241], v[76:79]
	v_mfma_f32_16x16x32_bf16 v[72:75], v[190:193], v[238:241], v[72:75]
	v_mfma_f32_16x16x32_bf16 v[124:127], v[186:189], v[218:221], v[124:127]
	v_mfma_f32_16x16x32_bf16 v[120:123], v[194:197], v[218:221], v[120:123]
	v_mfma_f32_16x16x32_bf16 v[108:111], v[186:189], v[226:229], v[108:111]
	v_mfma_f32_16x16x32_bf16 v[104:107], v[194:197], v[226:229], v[104:107]
	v_mfma_f32_16x16x32_bf16 v[92:95], v[186:189], v[234:237], v[92:95]
	v_mfma_f32_16x16x32_bf16 v[88:91], v[194:197], v[234:237], v[88:91]
	v_mfma_f32_16x16x32_bf16 v[76:79], v[186:189], v[242:245], v[76:79]
	v_mfma_f32_16x16x32_bf16 v[72:75], v[194:197], v[242:245], v[72:75]
	s_setprio 0
	s_setprio 1
	v_mfma_f32_16x16x32_bf16 v[116:119], v[198:201], v[214:217], v[116:119]
	v_mfma_f32_16x16x32_bf16 v[112:115], v[206:209], v[214:217], v[112:115]
	v_mfma_f32_16x16x32_bf16 v[100:103], v[198:201], v[222:225], v[100:103]
	v_mfma_f32_16x16x32_bf16 v[96:99], v[206:209], v[222:225], v[96:99]
	v_mfma_f32_16x16x32_bf16 v[84:87], v[198:201], v[230:233], v[84:87]
	v_mfma_f32_16x16x32_bf16 v[80:83], v[206:209], v[230:233], v[80:83]
	v_mfma_f32_16x16x32_bf16 v[68:71], v[198:201], v[238:241], v[68:71]
	v_mfma_f32_16x16x32_bf16 v[64:67], v[206:209], v[238:241], v[64:67]
	v_mfma_f32_16x16x32_bf16 v[116:119], v[202:205], v[218:221], v[116:119]
	v_mfma_f32_16x16x32_bf16 v[112:115], v[210:213], v[218:221], v[112:115]
	v_mfma_f32_16x16x32_bf16 v[100:103], v[202:205], v[226:229], v[100:103]
	v_mfma_f32_16x16x32_bf16 v[96:99], v[210:213], v[226:229], v[96:99]
	v_mfma_f32_16x16x32_bf16 v[84:87], v[202:205], v[234:237], v[84:87]
	v_mfma_f32_16x16x32_bf16 v[80:83], v[210:213], v[234:237], v[80:83]
	v_mfma_f32_16x16x32_bf16 v[68:71], v[202:205], v[242:245], v[68:71]
	v_mfma_f32_16x16x32_bf16 v[64:67], v[210:213], v[242:245], v[64:67]
	s_setprio 0
	s_barrier
	s_add_i32 s18, s34, s47
	s_mov_b32 m0, s18
	ds_read_b128 v[214:217], v157 offset:49152
	ds_read_b128 v[218:221], v157 offset:50176
	ds_read_b128 v[222:225], v157 offset:51200
	ds_read_b128 v[226:229], v157 offset:52224
	ds_read_b128 v[230:233], v157 offset:53248
	ds_read_b128 v[234:237], v157 offset:54272
	ds_read_b128 v[238:241], v157 offset:55296
	ds_read_b128 v[242:245], v157 offset:56320
	global_load_lds_dwordx4 v130, s[60:61]
	s_add_i32 m0, s18, 0x2000
	s_add_u32 s18, s42, 0x40080
	s_addc_u32 s19, s43, 0
	s_add_i32 s21, s35, s47
	global_load_lds_dwordx4 v142, s[60:61]
	s_mov_b32 m0, s21
	s_nop 0
	global_load_lds_dwordx4 v130, s[18:19]
	s_add_i32 m0, s21, 0x2000
	s_nop 0
	global_load_lds_dwordx4 v142, s[18:19]
	s_mov_b32 m0, s52
	s_nop 0
	global_load_lds_dwordx4 v146, s[62:63]
	s_mov_b32 m0, s53
	s_nop 0
	global_load_lds_dwordx4 v144, s[62:63]
	s_waitcnt vmcnt(8)
	s_waitcnt lgkmcnt(0)
	s_barrier
	s_setprio 1
	s_waitcnt lgkmcnt(0)
	v_mfma_f32_16x16x32_bf16 v[60:63], v[182:185], v[214:217], v[60:63]
	v_mfma_f32_16x16x32_bf16 v[56:59], v[190:193], v[214:217], v[56:59]
	v_mfma_f32_16x16x32_bf16 v[44:47], v[182:185], v[222:225], v[44:47]
	v_mfma_f32_16x16x32_bf16 v[40:43], v[190:193], v[222:225], v[40:43]
	v_mfma_f32_16x16x32_bf16 v[28:31], v[182:185], v[230:233], v[28:31]
	v_mfma_f32_16x16x32_bf16 v[24:27], v[190:193], v[230:233], v[24:27]
	v_mfma_f32_16x16x32_bf16 v[12:15], v[182:185], v[238:241], v[12:15]
	v_mfma_f32_16x16x32_bf16 v[8:11], v[190:193], v[238:241], v[8:11]
	v_mfma_f32_16x16x32_bf16 v[60:63], v[186:189], v[218:221], v[60:63]
	v_mfma_f32_16x16x32_bf16 v[56:59], v[194:197], v[218:221], v[56:59]
	v_mfma_f32_16x16x32_bf16 v[44:47], v[186:189], v[226:229], v[44:47]
	v_mfma_f32_16x16x32_bf16 v[40:43], v[194:197], v[226:229], v[40:43]
	v_mfma_f32_16x16x32_bf16 v[28:31], v[186:189], v[234:237], v[28:31]
	v_mfma_f32_16x16x32_bf16 v[24:27], v[194:197], v[234:237], v[24:27]
	v_mfma_f32_16x16x32_bf16 v[12:15], v[186:189], v[242:245], v[12:15]
	v_mfma_f32_16x16x32_bf16 v[8:11], v[194:197], v[242:245], v[8:11]
	s_setprio 0
	s_setprio 1
	v_mfma_f32_16x16x32_bf16 v[52:55], v[198:201], v[214:217], v[52:55]
	v_mfma_f32_16x16x32_bf16 v[48:51], v[206:209], v[214:217], v[48:51]
	v_mfma_f32_16x16x32_bf16 v[36:39], v[198:201], v[222:225], v[36:39]
	v_mfma_f32_16x16x32_bf16 v[32:35], v[206:209], v[222:225], v[32:35]
	v_mfma_f32_16x16x32_bf16 v[20:23], v[198:201], v[230:233], v[20:23]
	v_mfma_f32_16x16x32_bf16 v[16:19], v[206:209], v[230:233], v[16:19]
	v_mfma_f32_16x16x32_bf16 v[4:7], v[198:201], v[238:241], v[4:7]
	v_mfma_f32_16x16x32_bf16 v[0:3], v[206:209], v[238:241], v[0:3]
	v_mfma_f32_16x16x32_bf16 v[52:55], v[202:205], v[218:221], v[52:55]
	v_mfma_f32_16x16x32_bf16 v[48:51], v[210:213], v[218:221], v[48:51]
	v_mfma_f32_16x16x32_bf16 v[36:39], v[202:205], v[226:229], v[36:39]
	v_mfma_f32_16x16x32_bf16 v[32:35], v[210:213], v[226:229], v[32:35]
	v_mfma_f32_16x16x32_bf16 v[20:23], v[202:205], v[234:237], v[20:23]
	v_mfma_f32_16x16x32_bf16 v[16:19], v[210:213], v[234:237], v[16:19]
	v_mfma_f32_16x16x32_bf16 v[4:7], v[202:205], v[242:245], v[4:7]
	v_mfma_f32_16x16x32_bf16 v[0:3], v[210:213], v[242:245], v[0:3]
	s_setprio 0
	s_barrier
	s_add_i32 s15, s15, 2
	s_add_u32 s16, s16, 0x100
	s_addc_u32 s17, s17, 0
	s_add_u32 s13, s13, 0x100
	s_addc_u32 s14, s14, 0
	s_cmp_gt_u32 s15, 13
	s_cbranch_scc0 .LBB0_1438

.LBB0_1510:
	s_add_i32 s11, s49, -2
	s_add_u32 s50, s40, 0x100
	s_addc_u32 s51, s41, 0
	s_mov_b32 s42, 0
	v_add_u32_e32 v156, s22, v153
	ds_read_b128 v[182:185], v156
	ds_read_b128 v[186:189], v156 offset:1024
	ds_read_b128 v[190:193], v156 offset:2048
	ds_read_b128 v[194:197], v156 offset:3072
	v_add_u32_e32 v156, s23, v153
	ds_read_b128 v[198:201], v156
	ds_read_b128 v[202:205], v156 offset:1024
	ds_read_b128 v[206:209], v156 offset:2048
	ds_read_b128 v[210:213], v156 offset:3072
	s_add_i32 s52, s42, 2
	s_add_u32 s40, s36, 0x100
	s_addc_u32 s41, s37, 0
	s_cmp_eq_u32 s11, s42
	s_cselect_b32 s42, s28, s50
	s_cselect_b32 s45, s17, s41
	s_cselect_b32 s44, s16, s40
	s_cselect_b32 s43, s29, s51
	s_add_i32 m0, s13, 0xc000
	ds_read_b128 v[214:217], v155
	ds_read_b128 v[218:221], v155 offset:1024
	ds_read_b128 v[222:225], v155 offset:2048
	ds_read_b128 v[226:229], v155 offset:3072
	ds_read_b128 v[230:233], v155 offset:4096
	ds_read_b128 v[234:237], v155 offset:5120
	ds_read_b128 v[238:241], v155 offset:6144
	ds_read_b128 v[242:245], v155 offset:7168
	global_load_lds_dwordx4 v148, s[36:37]
	s_add_i32 m0, s13, 0xe000
	s_nop 0
	global_load_lds_dwordx4 v150, s[36:37]
	s_waitcnt vmcnt(8)
	s_waitcnt lgkmcnt(0)
	s_barrier
	s_setprio 1
	s_waitcnt lgkmcnt(0)
	v_mfma_f32_16x16x32_bf16 v[124:127], v[182:185], v[214:217], 0
	v_mfma_f32_16x16x32_bf16 v[120:123], v[190:193], v[214:217], 0
	v_mfma_f32_16x16x32_bf16 v[116:119], v[182:185], v[222:225], 0
	v_mfma_f32_16x16x32_bf16 v[112:115], v[190:193], v[222:225], 0
	v_mfma_f32_16x16x32_bf16 v[100:103], v[182:185], v[230:233], 0
	v_mfma_f32_16x16x32_bf16 v[96:99], v[190:193], v[230:233], 0
	v_mfma_f32_16x16x32_bf16 v[84:87], v[182:185], v[238:241], 0
	v_mfma_f32_16x16x32_bf16 v[80:83], v[190:193], v[238:241], 0
	v_mfma_f32_16x16x32_bf16 v[124:127], v[186:189], v[218:221], v[124:127]
	v_mfma_f32_16x16x32_bf16 v[120:123], v[194:197], v[218:221], v[120:123]
	v_mfma_f32_16x16x32_bf16 v[116:119], v[186:189], v[226:229], v[116:119]
	v_mfma_f32_16x16x32_bf16 v[112:115], v[194:197], v[226:229], v[112:115]
	v_mfma_f32_16x16x32_bf16 v[100:103], v[186:189], v[234:237], v[100:103]
	v_mfma_f32_16x16x32_bf16 v[96:99], v[194:197], v[234:237], v[96:99]
	v_mfma_f32_16x16x32_bf16 v[84:87], v[186:189], v[242:245], v[84:87]
	v_mfma_f32_16x16x32_bf16 v[80:83], v[194:197], v[242:245], v[80:83]
	s_setprio 0
	s_setprio 1
	v_mfma_f32_16x16x32_bf16 v[108:111], v[198:201], v[214:217], 0
	v_mfma_f32_16x16x32_bf16 v[104:107], v[206:209], v[214:217], 0
	v_mfma_f32_16x16x32_bf16 v[92:95], v[198:201], v[222:225], 0
	v_mfma_f32_16x16x32_bf16 v[88:91], v[206:209], v[222:225], 0
	v_mfma_f32_16x16x32_bf16 v[76:79], v[198:201], v[230:233], 0
	v_mfma_f32_16x16x32_bf16 v[72:75], v[206:209], v[230:233], 0
	v_mfma_f32_16x16x32_bf16 v[68:71], v[198:201], v[238:241], 0
	v_mfma_f32_16x16x32_bf16 v[64:67], v[206:209], v[238:241], 0
	v_mfma_f32_16x16x32_bf16 v[108:111], v[202:205], v[218:221], v[108:111]
	v_mfma_f32_16x16x32_bf16 v[104:107], v[210:213], v[218:221], v[104:107]
	v_mfma_f32_16x16x32_bf16 v[92:95], v[202:205], v[226:229], v[92:95]
	v_mfma_f32_16x16x32_bf16 v[88:91], v[210:213], v[226:229], v[88:91]
	v_mfma_f32_16x16x32_bf16 v[76:79], v[202:205], v[234:237], v[76:79]
	v_mfma_f32_16x16x32_bf16 v[72:75], v[210:213], v[234:237], v[72:75]
	v_mfma_f32_16x16x32_bf16 v[68:71], v[202:205], v[242:245], v[68:71]
	v_mfma_f32_16x16x32_bf16 v[64:67], v[210:213], v[242:245], v[64:67]
	s_setprio 0
	s_barrier
	s_add_u32 s60, s42, 0x80
	s_addc_u32 s61, s43, 0
	s_add_u32 s62, s44, 0x80
	s_addc_u32 s63, s45, 0
	s_add_i32 s21, s22, s12
	s_mov_b32 m0, s21
	ds_read_b128 v[214:217], v155 offset:16384
	ds_read_b128 v[218:221], v155 offset:17408
	ds_read_b128 v[222:225], v155 offset:18432
	ds_read_b128 v[226:229], v155 offset:19456
	ds_read_b128 v[230:233], v155 offset:20480
	ds_read_b128 v[234:237], v155 offset:21504
	ds_read_b128 v[238:241], v155 offset:22528
	ds_read_b128 v[242:245], v155 offset:23552
	global_load_lds_dwordx4 v130, s[42:43]
	s_add_i32 m0, s21, 0x2000
	s_add_u32 s24, s42, 0xb0000
	s_addc_u32 s25, s43, 0
	s_add_i32 s21, s23, s12
	global_load_lds_dwordx4 v146, s[42:43]
	s_mov_b32 m0, s21
	s_nop 0
	global_load_lds_dwordx4 v130, s[24:25]
	s_add_i32 m0, s21, 0x2000
	s_nop 0
	global_load_lds_dwordx4 v146, s[24:25]
	s_mov_b32 m0, s13
	s_nop 0
	global_load_lds_dwordx4 v142, s[44:45]
	s_mov_b32 m0, s19
	s_nop 0
	global_load_lds_dwordx4 v144, s[44:45]
	s_waitcnt vmcnt(8)
	s_waitcnt lgkmcnt(0)
	s_barrier
	s_setprio 1
	s_waitcnt lgkmcnt(0)
	v_mfma_f32_16x16x32_bf16 v[60:63], v[182:185], v[214:217], 0
	v_mfma_f32_16x16x32_bf16 v[56:59], v[190:193], v[214:217], 0
	v_mfma_f32_16x16x32_bf16 v[52:55], v[182:185], v[222:225], 0
	v_mfma_f32_16x16x32_bf16 v[48:51], v[190:193], v[222:225], 0
	v_mfma_f32_16x16x32_bf16 v[36:39], v[182:185], v[230:233], 0
	v_mfma_f32_16x16x32_bf16 v[32:35], v[190:193], v[230:233], 0
	v_mfma_f32_16x16x32_bf16 v[20:23], v[182:185], v[238:241], 0
	v_mfma_f32_16x16x32_bf16 v[16:19], v[190:193], v[238:241], 0
	v_mfma_f32_16x16x32_bf16 v[60:63], v[186:189], v[218:221], v[60:63]
	v_mfma_f32_16x16x32_bf16 v[56:59], v[194:197], v[218:221], v[56:59]
	v_mfma_f32_16x16x32_bf16 v[52:55], v[186:189], v[226:229], v[52:55]
	v_mfma_f32_16x16x32_bf16 v[48:51], v[194:197], v[226:229], v[48:51]
	v_mfma_f32_16x16x32_bf16 v[36:39], v[186:189], v[234:237], v[36:39]
	v_mfma_f32_16x16x32_bf16 v[32:35], v[194:197], v[234:237], v[32:35]
	v_mfma_f32_16x16x32_bf16 v[20:23], v[186:189], v[242:245], v[20:23]
	v_mfma_f32_16x16x32_bf16 v[16:19], v[194:197], v[242:245], v[16:19]
	s_setprio 0
	s_setprio 1
	v_mfma_f32_16x16x32_bf16 v[44:47], v[198:201], v[214:217], 0
	v_mfma_f32_16x16x32_bf16 v[40:43], v[206:209], v[214:217], 0
	v_mfma_f32_16x16x32_bf16 v[28:31], v[198:201], v[222:225], 0
	v_mfma_f32_16x16x32_bf16 v[24:27], v[206:209], v[222:225], 0
	v_mfma_f32_16x16x32_bf16 v[12:15], v[198:201], v[230:233], 0
	v_mfma_f32_16x16x32_bf16 v[8:11], v[206:209], v[230:233], 0
	v_mfma_f32_16x16x32_bf16 v[4:7], v[198:201], v[238:241], 0
	v_mfma_f32_16x16x32_bf16 v[0:3], v[206:209], v[238:241], 0
	v_mfma_f32_16x16x32_bf16 v[44:47], v[202:205], v[218:221], v[44:47]
	v_mfma_f32_16x16x32_bf16 v[40:43], v[210:213], v[218:221], v[40:43]
	v_mfma_f32_16x16x32_bf16 v[28:31], v[202:205], v[226:229], v[28:31]
	v_mfma_f32_16x16x32_bf16 v[24:27], v[210:213], v[226:229], v[24:27]
	v_mfma_f32_16x16x32_bf16 v[12:15], v[202:205], v[234:237], v[12:15]
	v_mfma_f32_16x16x32_bf16 v[8:11], v[210:213], v[234:237], v[8:11]
	v_mfma_f32_16x16x32_bf16 v[4:7], v[202:205], v[242:245], v[4:7]
	v_mfma_f32_16x16x32_bf16 v[0:3], v[210:213], v[242:245], v[0:3]
	s_setprio 0
	s_barrier
	v_add_u32_e32 v181, s34, v153
	ds_read_b128 v[182:185], v181
	ds_read_b128 v[186:189], v181 offset:1024
	ds_read_b128 v[190:193], v181 offset:2048
	ds_read_b128 v[194:197], v181 offset:3072
	v_add_u32_e32 v181, s35, v153
	ds_read_b128 v[198:201], v181
	ds_read_b128 v[202:205], v181 offset:1024
	ds_read_b128 v[206:209], v181 offset:2048
	ds_read_b128 v[210:213], v181 offset:3072
	s_add_u32 s24, s44, 0xb0000
	s_addc_u32 s25, s45, 0
	s_mov_b32 m0, s20
	ds_read_b128 v[214:217], v155 offset:32768
	ds_read_b128 v[218:221], v155 offset:33792
	ds_read_b128 v[222:225], v155 offset:34816
	ds_read_b128 v[226:229], v155 offset:35840
	ds_read_b128 v[230:233], v155 offset:36864
	ds_read_b128 v[234:237], v155 offset:37888
	ds_read_b128 v[238:241], v155 offset:38912
	ds_read_b128 v[242:245], v155 offset:39936
	global_load_lds_dwordx4 v142, s[24:25]
	s_mov_b32 m0, s26
	s_nop 0
	global_load_lds_dwordx4 v144, s[24:25]
	s_waitcnt vmcnt(8)
	s_waitcnt lgkmcnt(0)
	s_barrier
	s_setprio 1
	s_waitcnt lgkmcnt(0)
	v_mfma_f32_16x16x32_bf16 v[124:127], v[182:185], v[214:217], v[124:127]
	v_mfma_f32_16x16x32_bf16 v[120:123], v[190:193], v[214:217], v[120:123]
	v_mfma_f32_16x16x32_bf16 v[116:119], v[182:185], v[222:225], v[116:119]
	v_mfma_f32_16x16x32_bf16 v[112:115], v[190:193], v[222:225], v[112:115]
	v_mfma_f32_16x16x32_bf16 v[100:103], v[182:185], v[230:233], v[100:103]
	v_mfma_f32_16x16x32_bf16 v[96:99], v[190:193], v[230:233], v[96:99]
	v_mfma_f32_16x16x32_bf16 v[84:87], v[182:185], v[238:241], v[84:87]
	v_mfma_f32_16x16x32_bf16 v[80:83], v[190:193], v[238:241], v[80:83]
	v_mfma_f32_16x16x32_bf16 v[124:127], v[186:189], v[218:221], v[124:127]
	v_mfma_f32_16x16x32_bf16 v[120:123], v[194:197], v[218:221], v[120:123]
	v_mfma_f32_16x16x32_bf16 v[116:119], v[186:189], v[226:229], v[116:119]
	v_mfma_f32_16x16x32_bf16 v[112:115], v[194:197], v[226:229], v[112:115]
	v_mfma_f32_16x16x32_bf16 v[100:103], v[186:189], v[234:237], v[100:103]
	v_mfma_f32_16x16x32_bf16 v[96:99], v[194:197], v[234:237], v[96:99]
	v_mfma_f32_16x16x32_bf16 v[84:87], v[186:189], v[242:245], v[84:87]
	v_mfma_f32_16x16x32_bf16 v[80:83], v[194:197], v[242:245], v[80:83]
	s_setprio 0
	s_setprio 1
	v_mfma_f32_16x16x32_bf16 v[108:111], v[198:201], v[214:217], v[108:111]
	v_mfma_f32_16x16x32_bf16 v[104:107], v[206:209], v[214:217], v[104:107]
	v_mfma_f32_16x16x32_bf16 v[92:95], v[198:201], v[222:225], v[92:95]
	v_mfma_f32_16x16x32_bf16 v[88:91], v[206:209], v[222:225], v[88:91]
	v_mfma_f32_16x16x32_bf16 v[76:79], v[198:201], v[230:233], v[76:79]
	v_mfma_f32_16x16x32_bf16 v[72:75], v[206:209], v[230:233], v[72:75]
	v_mfma_f32_16x16x32_bf16 v[68:71], v[198:201], v[238:241], v[68:71]
	v_mfma_f32_16x16x32_bf16 v[64:67], v[206:209], v[238:241], v[64:67]
	v_mfma_f32_16x16x32_bf16 v[108:111], v[202:205], v[218:221], v[108:111]
	v_mfma_f32_16x16x32_bf16 v[104:107], v[210:213], v[218:221], v[104:107]
	v_mfma_f32_16x16x32_bf16 v[92:95], v[202:205], v[226:229], v[92:95]
	v_mfma_f32_16x16x32_bf16 v[88:91], v[210:213], v[226:229], v[88:91]
	v_mfma_f32_16x16x32_bf16 v[76:79], v[202:205], v[234:237], v[76:79]
	v_mfma_f32_16x16x32_bf16 v[72:75], v[210:213], v[234:237], v[72:75]
	v_mfma_f32_16x16x32_bf16 v[68:71], v[202:205], v[242:245], v[68:71]
	v_mfma_f32_16x16x32_bf16 v[64:67], v[210:213], v[242:245], v[64:67]
	s_setprio 0
	s_barrier
	s_add_i32 s21, s34, s12
	s_mov_b32 m0, s21
	ds_read_b128 v[214:217], v155 offset:49152
	ds_read_b128 v[218:221], v155 offset:50176
	ds_read_b128 v[222:225], v155 offset:51200
	ds_read_b128 v[226:229], v155 offset:52224
	ds_read_b128 v[230:233], v155 offset:53248
	ds_read_b128 v[234:237], v155 offset:54272
	ds_read_b128 v[238:241], v155 offset:55296
	ds_read_b128 v[242:245], v155 offset:56320
	global_load_lds_dwordx4 v130, s[60:61]
	s_add_i32 m0, s21, 0x2000
	s_add_u32 s24, s42, 0xb0080
	s_addc_u32 s25, s43, 0
	s_add_i32 s21, s35, s12
	global_load_lds_dwordx4 v146, s[60:61]
	s_mov_b32 m0, s21
	s_nop 0
	global_load_lds_dwordx4 v130, s[24:25]
	s_add_i32 m0, s21, 0x2000
	s_nop 0
	global_load_lds_dwordx4 v146, s[24:25]
	s_mov_b32 m0, s33
	s_nop 0
	global_load_lds_dwordx4 v142, s[62:63]
	s_mov_b32 m0, s38
	s_nop 0
	global_load_lds_dwordx4 v144, s[62:63]
	s_waitcnt vmcnt(8)
	s_waitcnt lgkmcnt(0)
	s_barrier
	s_setprio 1
	s_waitcnt lgkmcnt(0)
	v_mfma_f32_16x16x32_bf16 v[60:63], v[182:185], v[214:217], v[60:63]
	v_mfma_f32_16x16x32_bf16 v[56:59], v[190:193], v[214:217], v[56:59]
	v_mfma_f32_16x16x32_bf16 v[52:55], v[182:185], v[222:225], v[52:55]
	v_mfma_f32_16x16x32_bf16 v[48:51], v[190:193], v[222:225], v[48:51]
	v_mfma_f32_16x16x32_bf16 v[36:39], v[182:185], v[230:233], v[36:39]
	v_mfma_f32_16x16x32_bf16 v[32:35], v[190:193], v[230:233], v[32:35]
	v_mfma_f32_16x16x32_bf16 v[20:23], v[182:185], v[238:241], v[20:23]
	v_mfma_f32_16x16x32_bf16 v[16:19], v[190:193], v[238:241], v[16:19]
	v_mfma_f32_16x16x32_bf16 v[60:63], v[186:189], v[218:221], v[60:63]
	v_mfma_f32_16x16x32_bf16 v[56:59], v[194:197], v[218:221], v[56:59]
	v_mfma_f32_16x16x32_bf16 v[52:55], v[186:189], v[226:229], v[52:55]
	v_mfma_f32_16x16x32_bf16 v[48:51], v[194:197], v[226:229], v[48:51]
	v_mfma_f32_16x16x32_bf16 v[36:39], v[186:189], v[234:237], v[36:39]
	v_mfma_f32_16x16x32_bf16 v[32:35], v[194:197], v[234:237], v[32:35]
	v_mfma_f32_16x16x32_bf16 v[20:23], v[186:189], v[242:245], v[20:23]
	v_mfma_f32_16x16x32_bf16 v[16:19], v[194:197], v[242:245], v[16:19]
	s_setprio 0
	s_setprio 1
	v_mfma_f32_16x16x32_bf16 v[44:47], v[198:201], v[214:217], v[44:47]
	v_mfma_f32_16x16x32_bf16 v[40:43], v[206:209], v[214:217], v[40:43]
	v_mfma_f32_16x16x32_bf16 v[28:31], v[198:201], v[222:225], v[28:31]
	v_mfma_f32_16x16x32_bf16 v[24:27], v[206:209], v[222:225], v[24:27]
	v_mfma_f32_16x16x32_bf16 v[12:15], v[198:201], v[230:233], v[12:15]
	v_mfma_f32_16x16x32_bf16 v[8:11], v[206:209], v[230:233], v[8:11]
	v_mfma_f32_16x16x32_bf16 v[4:7], v[198:201], v[238:241], v[4:7]
	v_mfma_f32_16x16x32_bf16 v[0:3], v[206:209], v[238:241], v[0:3]
	v_mfma_f32_16x16x32_bf16 v[44:47], v[202:205], v[218:221], v[44:47]
	v_mfma_f32_16x16x32_bf16 v[40:43], v[210:213], v[218:221], v[40:43]
	v_mfma_f32_16x16x32_bf16 v[28:31], v[202:205], v[226:229], v[28:31]
	v_mfma_f32_16x16x32_bf16 v[24:27], v[210:213], v[226:229], v[24:27]
	v_mfma_f32_16x16x32_bf16 v[12:15], v[202:205], v[234:237], v[12:15]
	v_mfma_f32_16x16x32_bf16 v[8:11], v[210:213], v[234:237], v[8:11]
	v_mfma_f32_16x16x32_bf16 v[4:7], v[202:205], v[242:245], v[4:7]
	v_mfma_f32_16x16x32_bf16 v[0:3], v[210:213], v[242:245], v[0:3]
	s_setprio 0
	s_barrier
	s_add_u32 s50, s50, 0x100
	s_addc_u32 s51, s51, 0
	s_cmp_ge_i32 s52, s49
	s_mov_b64 s[36:37], s[40:41]
	s_mov_b32 s42, s52
	s_cbranch_scc1 .Lpeel_done_1511
.LBB0_1511:
	v_add_u32_e32 v156, s22, v153
	ds_read_b128 v[182:185], v156
	ds_read_b128 v[186:189], v156 offset:1024
	ds_read_b128 v[190:193], v156 offset:2048
	ds_read_b128 v[194:197], v156 offset:3072
	v_add_u32_e32 v156, s23, v153
	ds_read_b128 v[198:201], v156
	ds_read_b128 v[202:205], v156 offset:1024
	ds_read_b128 v[206:209], v156 offset:2048
	ds_read_b128 v[210:213], v156 offset:3072
	s_add_i32 s52, s42, 2
	s_add_u32 s40, s36, 0x100
	s_addc_u32 s41, s37, 0
	s_cmp_eq_u32 s11, s42
	s_cselect_b32 s42, s28, s50
	s_cselect_b32 s45, s17, s41
	s_cselect_b32 s44, s16, s40
	s_cselect_b32 s43, s29, s51
	s_add_i32 m0, s13, 0xc000
	ds_read_b128 v[214:217], v155
	ds_read_b128 v[218:221], v155 offset:1024
	ds_read_b128 v[222:225], v155 offset:2048
	ds_read_b128 v[226:229], v155 offset:3072
	ds_read_b128 v[230:233], v155 offset:4096
	ds_read_b128 v[234:237], v155 offset:5120
	ds_read_b128 v[238:241], v155 offset:6144
	ds_read_b128 v[242:245], v155 offset:7168
	global_load_lds_dwordx4 v148, s[36:37]
	s_add_i32 m0, s13, 0xe000
	s_nop 0
	global_load_lds_dwordx4 v150, s[36:37]
	s_waitcnt vmcnt(8)
	s_waitcnt lgkmcnt(0)
	s_barrier
	s_setprio 1
	s_waitcnt lgkmcnt(0)
	v_mfma_f32_16x16x32_bf16 v[124:127], v[182:185], v[214:217], v[124:127]
	v_mfma_f32_16x16x32_bf16 v[120:123], v[190:193], v[214:217], v[120:123]
	v_mfma_f32_16x16x32_bf16 v[116:119], v[182:185], v[222:225], v[116:119]
	v_mfma_f32_16x16x32_bf16 v[112:115], v[190:193], v[222:225], v[112:115]
	v_mfma_f32_16x16x32_bf16 v[100:103], v[182:185], v[230:233], v[100:103]
	v_mfma_f32_16x16x32_bf16 v[96:99], v[190:193], v[230:233], v[96:99]
	v_mfma_f32_16x16x32_bf16 v[84:87], v[182:185], v[238:241], v[84:87]
	v_mfma_f32_16x16x32_bf16 v[80:83], v[190:193], v[238:241], v[80:83]
	v_mfma_f32_16x16x32_bf16 v[124:127], v[186:189], v[218:221], v[124:127]
	v_mfma_f32_16x16x32_bf16 v[120:123], v[194:197], v[218:221], v[120:123]
	v_mfma_f32_16x16x32_bf16 v[116:119], v[186:189], v[226:229], v[116:119]
	v_mfma_f32_16x16x32_bf16 v[112:115], v[194:197], v[226:229], v[112:115]
	v_mfma_f32_16x16x32_bf16 v[100:103], v[186:189], v[234:237], v[100:103]
	v_mfma_f32_16x16x32_bf16 v[96:99], v[194:197], v[234:237], v[96:99]
	v_mfma_f32_16x16x32_bf16 v[84:87], v[186:189], v[242:245], v[84:87]
	v_mfma_f32_16x16x32_bf16 v[80:83], v[194:197], v[242:245], v[80:83]
	s_setprio 0
	s_setprio 1
	v_mfma_f32_16x16x32_bf16 v[108:111], v[198:201], v[214:217], v[108:111]
	v_mfma_f32_16x16x32_bf16 v[104:107], v[206:209], v[214:217], v[104:107]
	v_mfma_f32_16x16x32_bf16 v[92:95], v[198:201], v[222:225], v[92:95]
	v_mfma_f32_16x16x32_bf16 v[88:91], v[206:209], v[222:225], v[88:91]
	v_mfma_f32_16x16x32_bf16 v[76:79], v[198:201], v[230:233], v[76:79]
	v_mfma_f32_16x16x32_bf16 v[72:75], v[206:209], v[230:233], v[72:75]
	v_mfma_f32_16x16x32_bf16 v[68:71], v[198:201], v[238:241], v[68:71]
	v_mfma_f32_16x16x32_bf16 v[64:67], v[206:209], v[238:241], v[64:67]
	v_mfma_f32_16x16x32_bf16 v[108:111], v[202:205], v[218:221], v[108:111]
	v_mfma_f32_16x16x32_bf16 v[104:107], v[210:213], v[218:221], v[104:107]
	v_mfma_f32_16x16x32_bf16 v[92:95], v[202:205], v[226:229], v[92:95]
	v_mfma_f32_16x16x32_bf16 v[88:91], v[210:213], v[226:229], v[88:91]
	v_mfma_f32_16x16x32_bf16 v[76:79], v[202:205], v[234:237], v[76:79]
	v_mfma_f32_16x16x32_bf16 v[72:75], v[210:213], v[234:237], v[72:75]
	v_mfma_f32_16x16x32_bf16 v[68:71], v[202:205], v[242:245], v[68:71]
	v_mfma_f32_16x16x32_bf16 v[64:67], v[210:213], v[242:245], v[64:67]
	s_setprio 0
	s_barrier
	s_add_u32 s60, s42, 0x80
	s_addc_u32 s61, s43, 0
	s_add_u32 s62, s44, 0x80
	s_addc_u32 s63, s45, 0
	s_add_i32 s21, s22, s12
	s_mov_b32 m0, s21
	ds_read_b128 v[214:217], v155 offset:16384
	ds_read_b128 v[218:221], v155 offset:17408
	ds_read_b128 v[222:225], v155 offset:18432
	ds_read_b128 v[226:229], v155 offset:19456
	ds_read_b128 v[230:233], v155 offset:20480
	ds_read_b128 v[234:237], v155 offset:21504
	ds_read_b128 v[238:241], v155 offset:22528
	ds_read_b128 v[242:245], v155 offset:23552
	global_load_lds_dwordx4 v130, s[42:43]
	s_add_i32 m0, s21, 0x2000
	s_add_u32 s24, s42, 0xb0000
	s_addc_u32 s25, s43, 0
	s_add_i32 s21, s23, s12
	global_load_lds_dwordx4 v146, s[42:43]
	s_mov_b32 m0, s21
	s_nop 0
	global_load_lds_dwordx4 v130, s[24:25]
	s_add_i32 m0, s21, 0x2000
	s_nop 0
	global_load_lds_dwordx4 v146, s[24:25]
	s_mov_b32 m0, s13
	s_nop 0
	global_load_lds_dwordx4 v142, s[44:45]
	s_mov_b32 m0, s19
	s_nop 0
	global_load_lds_dwordx4 v144, s[44:45]
	s_waitcnt vmcnt(8)
	s_waitcnt lgkmcnt(0)
	s_barrier
	s_setprio 1
	s_waitcnt lgkmcnt(0)
	v_mfma_f32_16x16x32_bf16 v[60:63], v[182:185], v[214:217], v[60:63]
	v_mfma_f32_16x16x32_bf16 v[56:59], v[190:193], v[214:217], v[56:59]
	v_mfma_f32_16x16x32_bf16 v[52:55], v[182:185], v[222:225], v[52:55]
	v_mfma_f32_16x16x32_bf16 v[48:51], v[190:193], v[222:225], v[48:51]
	v_mfma_f32_16x16x32_bf16 v[36:39], v[182:185], v[230:233], v[36:39]
	v_mfma_f32_16x16x32_bf16 v[32:35], v[190:193], v[230:233], v[32:35]
	v_mfma_f32_16x16x32_bf16 v[20:23], v[182:185], v[238:241], v[20:23]
	v_mfma_f32_16x16x32_bf16 v[16:19], v[190:193], v[238:241], v[16:19]
	v_mfma_f32_16x16x32_bf16 v[60:63], v[186:189], v[218:221], v[60:63]
	v_mfma_f32_16x16x32_bf16 v[56:59], v[194:197], v[218:221], v[56:59]
	v_mfma_f32_16x16x32_bf16 v[52:55], v[186:189], v[226:229], v[52:55]
	v_mfma_f32_16x16x32_bf16 v[48:51], v[194:197], v[226:229], v[48:51]
	v_mfma_f32_16x16x32_bf16 v[36:39], v[186:189], v[234:237], v[36:39]
	v_mfma_f32_16x16x32_bf16 v[32:35], v[194:197], v[234:237], v[32:35]
	v_mfma_f32_16x16x32_bf16 v[20:23], v[186:189], v[242:245], v[20:23]
	v_mfma_f32_16x16x32_bf16 v[16:19], v[194:197], v[242:245], v[16:19]
	s_setprio 0
	s_setprio 1
	v_mfma_f32_16x16x32_bf16 v[44:47], v[198:201], v[214:217], v[44:47]
	v_mfma_f32_16x16x32_bf16 v[40:43], v[206:209], v[214:217], v[40:43]
	v_mfma_f32_16x16x32_bf16 v[28:31], v[198:201], v[222:225], v[28:31]
	v_mfma_f32_16x16x32_bf16 v[24:27], v[206:209], v[222:225], v[24:27]
	v_mfma_f32_16x16x32_bf16 v[12:15], v[198:201], v[230:233], v[12:15]
	v_mfma_f32_16x16x32_bf16 v[8:11], v[206:209], v[230:233], v[8:11]
	v_mfma_f32_16x16x32_bf16 v[4:7], v[198:201], v[238:241], v[4:7]
	v_mfma_f32_16x16x32_bf16 v[0:3], v[206:209], v[238:241], v[0:3]
	v_mfma_f32_16x16x32_bf16 v[44:47], v[202:205], v[218:221], v[44:47]
	v_mfma_f32_16x16x32_bf16 v[40:43], v[210:213], v[218:221], v[40:43]
	v_mfma_f32_16x16x32_bf16 v[28:31], v[202:205], v[226:229], v[28:31]
	v_mfma_f32_16x16x32_bf16 v[24:27], v[210:213], v[226:229], v[24:27]
	v_mfma_f32_16x16x32_bf16 v[12:15], v[202:205], v[234:237], v[12:15]
	v_mfma_f32_16x16x32_bf16 v[8:11], v[210:213], v[234:237], v[8:11]
	v_mfma_f32_16x16x32_bf16 v[4:7], v[202:205], v[242:245], v[4:7]
	v_mfma_f32_16x16x32_bf16 v[0:3], v[210:213], v[242:245], v[0:3]
	s_setprio 0
	s_barrier
	v_add_u32_e32 v181, s34, v153
	ds_read_b128 v[182:185], v181
	ds_read_b128 v[186:189], v181 offset:1024
	ds_read_b128 v[190:193], v181 offset:2048
	ds_read_b128 v[194:197], v181 offset:3072
	v_add_u32_e32 v181, s35, v153
	ds_read_b128 v[198:201], v181
	ds_read_b128 v[202:205], v181 offset:1024
	ds_read_b128 v[206:209], v181 offset:2048
	ds_read_b128 v[210:213], v181 offset:3072
	s_add_u32 s24, s44, 0xb0000
	s_addc_u32 s25, s45, 0
	s_mov_b32 m0, s20
	ds_read_b128 v[214:217], v155 offset:32768
	ds_read_b128 v[218:221], v155 offset:33792
	ds_read_b128 v[222:225], v155 offset:34816
	ds_read_b128 v[226:229], v155 offset:35840
	ds_read_b128 v[230:233], v155 offset:36864
	ds_read_b128 v[234:237], v155 offset:37888
	ds_read_b128 v[238:241], v155 offset:38912
	ds_read_b128 v[242:245], v155 offset:39936
	global_load_lds_dwordx4 v142, s[24:25]
	s_mov_b32 m0, s26
	s_nop 0
	global_load_lds_dwordx4 v144, s[24:25]
	s_waitcnt vmcnt(8)
	s_waitcnt lgkmcnt(0)
	s_barrier
	s_setprio 1
	s_waitcnt lgkmcnt(0)
	v_mfma_f32_16x16x32_bf16 v[124:127], v[182:185], v[214:217], v[124:127]
	v_mfma_f32_16x16x32_bf16 v[120:123], v[190:193], v[214:217], v[120:123]
	v_mfma_f32_16x16x32_bf16 v[116:119], v[182:185], v[222:225], v[116:119]
	v_mfma_f32_16x16x32_bf16 v[112:115], v[190:193], v[222:225], v[112:115]
	v_mfma_f32_16x16x32_bf16 v[100:103], v[182:185], v[230:233], v[100:103]
	v_mfma_f32_16x16x32_bf16 v[96:99], v[190:193], v[230:233], v[96:99]
	v_mfma_f32_16x16x32_bf16 v[84:87], v[182:185], v[238:241], v[84:87]
	v_mfma_f32_16x16x32_bf16 v[80:83], v[190:193], v[238:241], v[80:83]
	v_mfma_f32_16x16x32_bf16 v[124:127], v[186:189], v[218:221], v[124:127]
	v_mfma_f32_16x16x32_bf16 v[120:123], v[194:197], v[218:221], v[120:123]
	v_mfma_f32_16x16x32_bf16 v[116:119], v[186:189], v[226:229], v[116:119]
	v_mfma_f32_16x16x32_bf16 v[112:115], v[194:197], v[226:229], v[112:115]
	v_mfma_f32_16x16x32_bf16 v[100:103], v[186:189], v[234:237], v[100:103]
	v_mfma_f32_16x16x32_bf16 v[96:99], v[194:197], v[234:237], v[96:99]
	v_mfma_f32_16x16x32_bf16 v[84:87], v[186:189], v[242:245], v[84:87]
	v_mfma_f32_16x16x32_bf16 v[80:83], v[194:197], v[242:245], v[80:83]
	s_setprio 0
	s_setprio 1
	v_mfma_f32_16x16x32_bf16 v[108:111], v[198:201], v[214:217], v[108:111]
	v_mfma_f32_16x16x32_bf16 v[104:107], v[206:209], v[214:217], v[104:107]
	v_mfma_f32_16x16x32_bf16 v[92:95], v[198:201], v[222:225], v[92:95]
	v_mfma_f32_16x16x32_bf16 v[88:91], v[206:209], v[222:225], v[88:91]
	v_mfma_f32_16x16x32_bf16 v[76:79], v[198:201], v[230:233], v[76:79]
	v_mfma_f32_16x16x32_bf16 v[72:75], v[206:209], v[230:233], v[72:75]
	v_mfma_f32_16x16x32_bf16 v[68:71], v[198:201], v[238:241], v[68:71]
	v_mfma_f32_16x16x32_bf16 v[64:67], v[206:209], v[238:241], v[64:67]
	v_mfma_f32_16x16x32_bf16 v[108:111], v[202:205], v[218:221], v[108:111]
	v_mfma_f32_16x16x32_bf16 v[104:107], v[210:213], v[218:221], v[104:107]
	v_mfma_f32_16x16x32_bf16 v[92:95], v[202:205], v[226:229], v[92:95]
	v_mfma_f32_16x16x32_bf16 v[88:91], v[210:213], v[226:229], v[88:91]
	v_mfma_f32_16x16x32_bf16 v[76:79], v[202:205], v[234:237], v[76:79]
	v_mfma_f32_16x16x32_bf16 v[72:75], v[210:213], v[234:237], v[72:75]
	v_mfma_f32_16x16x32_bf16 v[68:71], v[202:205], v[242:245], v[68:71]
	v_mfma_f32_16x16x32_bf16 v[64:67], v[210:213], v[242:245], v[64:67]
	s_setprio 0
	s_barrier
	s_add_i32 s21, s34, s12
	s_mov_b32 m0, s21
	ds_read_b128 v[214:217], v155 offset:49152
	ds_read_b128 v[218:221], v155 offset:50176
	ds_read_b128 v[222:225], v155 offset:51200
	ds_read_b128 v[226:229], v155 offset:52224
	ds_read_b128 v[230:233], v155 offset:53248
	ds_read_b128 v[234:237], v155 offset:54272
	ds_read_b128 v[238:241], v155 offset:55296
	ds_read_b128 v[242:245], v155 offset:56320
	global_load_lds_dwordx4 v130, s[60:61]
	s_add_i32 m0, s21, 0x2000
	s_add_u32 s24, s42, 0xb0080
	s_addc_u32 s25, s43, 0
	s_add_i32 s21, s35, s12
	global_load_lds_dwordx4 v146, s[60:61]
	s_mov_b32 m0, s21
	s_nop 0
	global_load_lds_dwordx4 v130, s[24:25]
	s_add_i32 m0, s21, 0x2000
	s_nop 0
	global_load_lds_dwordx4 v146, s[24:25]
	s_mov_b32 m0, s33
	s_nop 0
	global_load_lds_dwordx4 v142, s[62:63]
	s_mov_b32 m0, s38
	s_nop 0
	global_load_lds_dwordx4 v144, s[62:63]
	s_waitcnt vmcnt(8)
	s_waitcnt lgkmcnt(0)
	s_barrier
	s_setprio 1
	s_waitcnt lgkmcnt(0)
	v_mfma_f32_16x16x32_bf16 v[60:63], v[182:185], v[214:217], v[60:63]
	v_mfma_f32_16x16x32_bf16 v[56:59], v[190:193], v[214:217], v[56:59]
	v_mfma_f32_16x16x32_bf16 v[52:55], v[182:185], v[222:225], v[52:55]
	v_mfma_f32_16x16x32_bf16 v[48:51], v[190:193], v[222:225], v[48:51]
	v_mfma_f32_16x16x32_bf16 v[36:39], v[182:185], v[230:233], v[36:39]
	v_mfma_f32_16x16x32_bf16 v[32:35], v[190:193], v[230:233], v[32:35]
	v_mfma_f32_16x16x32_bf16 v[20:23], v[182:185], v[238:241], v[20:23]
	v_mfma_f32_16x16x32_bf16 v[16:19], v[190:193], v[238:241], v[16:19]
	v_mfma_f32_16x16x32_bf16 v[60:63], v[186:189], v[218:221], v[60:63]
	v_mfma_f32_16x16x32_bf16 v[56:59], v[194:197], v[218:221], v[56:59]
	v_mfma_f32_16x16x32_bf16 v[52:55], v[186:189], v[226:229], v[52:55]
	v_mfma_f32_16x16x32_bf16 v[48:51], v[194:197], v[226:229], v[48:51]
	v_mfma_f32_16x16x32_bf16 v[36:39], v[186:189], v[234:237], v[36:39]
	v_mfma_f32_16x16x32_bf16 v[32:35], v[194:197], v[234:237], v[32:35]
	v_mfma_f32_16x16x32_bf16 v[20:23], v[186:189], v[242:245], v[20:23]
	v_mfma_f32_16x16x32_bf16 v[16:19], v[194:197], v[242:245], v[16:19]
	s_setprio 0
	s_setprio 1
	v_mfma_f32_16x16x32_bf16 v[44:47], v[198:201], v[214:217], v[44:47]
	v_mfma_f32_16x16x32_bf16 v[40:43], v[206:209], v[214:217], v[40:43]
	v_mfma_f32_16x16x32_bf16 v[28:31], v[198:201], v[222:225], v[28:31]
	v_mfma_f32_16x16x32_bf16 v[24:27], v[206:209], v[222:225], v[24:27]
	v_mfma_f32_16x16x32_bf16 v[12:15], v[198:201], v[230:233], v[12:15]
	v_mfma_f32_16x16x32_bf16 v[8:11], v[206:209], v[230:233], v[8:11]
	v_mfma_f32_16x16x32_bf16 v[4:7], v[198:201], v[238:241], v[4:7]
	v_mfma_f32_16x16x32_bf16 v[0:3], v[206:209], v[238:241], v[0:3]
	v_mfma_f32_16x16x32_bf16 v[44:47], v[202:205], v[218:221], v[44:47]
	v_mfma_f32_16x16x32_bf16 v[40:43], v[210:213], v[218:221], v[40:43]
	v_mfma_f32_16x16x32_bf16 v[28:31], v[202:205], v[226:229], v[28:31]
	v_mfma_f32_16x16x32_bf16 v[24:27], v[210:213], v[226:229], v[24:27]
	v_mfma_f32_16x16x32_bf16 v[12:15], v[202:205], v[234:237], v[12:15]
	v_mfma_f32_16x16x32_bf16 v[8:11], v[210:213], v[234:237], v[8:11]
	v_mfma_f32_16x16x32_bf16 v[4:7], v[202:205], v[242:245], v[4:7]
	v_mfma_f32_16x16x32_bf16 v[0:3], v[210:213], v[242:245], v[0:3]
	s_setprio 0
	s_barrier
	s_add_u32 s50, s50, 0x100
	s_addc_u32 s51, s51, 0
	s_cmp_ge_i32 s52, s49
	s_mov_b64 s[36:37], s[40:41]
	s_mov_b32 s42, s52
	s_cbranch_scc0 .LBB0_1511
